# K-loop: first 2 MFMAs of every 32-MFMA block issued before the block-opening barrier
# speedup vs baseline: 1.0123x; 1.0123x over previous
; #define PG8_STAGE(bufoff, gbase, voff) do { _Pragma("unroll") for (int _i = 0; _i < 2; ++_i) \
;         __builtin_amdgcn_global_load_lds((const unsigned*)((const char*)(gbase) + (voff)[_i]), (PG8_LAS unsigned*)(lds + (bufoff) + ldsw + _i * 8192), 16, 0, 0); } while (0)
; #define PG8_LDA(dst, b, h) do { _Pragma("unroll") for (int m = 0; m < 4; ++m) _Pragma("unroll") for (int k = 0; k < 2; ++k) dst[m][k] = *(const PG8_LAS bf16x8*)(lds + PG8_SA(b, h) + aoff + m * 2048 + k * 1024); } while (0)
; #define PG8_LDB(dst, b, h) do { _Pragma("unroll") for (int n = 0; n < 2; ++n) _Pragma("unroll") for (int k = 0; k < 2; ++k) dst[n][k] = *(const PG8_LAS bf16x8*)(lds + PG8_SB(b, h) + boff + n * 2048 + k * 1024); } while (0)
; #define PG8_MMA(ai, bj, At, Bt) do { __builtin_amdgcn_s_setprio(1); _Pragma("unroll") for (int m = 0; m < 4; ++m) _Pragma("unroll") for (int n = 0; n < 2; ++n) _Pragma("unroll") for (int k = 0; k < 2; ++k) \
;         acc[ai][bj][m][n] = __builtin_amdgcn_mfma_f32_16x16x32_bf16(Bt[n][k], At[m][k], acc[ai][bj][m][n], 0, 0, 0); __builtin_amdgcn_s_setprio(0); } while (0)
; #define PG8_WAIT_V(n) asm volatile("s_waitcnt vmcnt(" #n ")" ::: "memory")
; #define PG8_WAIT_L(n) asm volatile("s_waitcnt lgkmcnt(" #n ")" ::: "memory")
; #define PG8_BAR __builtin_amdgcn_s_barrier()
; #define PG8_SCHED __builtin_amdgcn_sched_barrier(0)
; template <class Epi, class Sched, bool ALIGN_EPI = false, bool SP2 = false>
; __device__ __forceinline__ void gemm_phase(PG8_LAS unsigned char* lds, const Gemm g, const Sched& S, const Epi& E) {
;     ...
;             PG8_LDB(B0, 0, 0); PG8_LDB(B1, 0, 1); PG8_SCHED; PG8_LDA(At, 0, 0); PG8_STAGE(PG8_SA(1, 1), a1 + hstep, voffA);
;             PG8_WAIT_V(8); PG8_WAIT_L(0); PG8_BAR; PG8_MMA(0, 0, At, B0); PG8_MMA(0, 1, At, B1); PG8_BAR; PG8_SCHED;
;             PG8_LDA(At, 0, 1); PG8_STAGE(PG8_SB(0, 0), b2, voffB); PG8_STAGE(PG8_SB(0, 1), b2 + hstep, voffB); PG8_STAGE(PG8_SA(0, 0), a2, voffA);
;             PG8_WAIT_V(8); PG8_WAIT_L(0); PG8_BAR; PG8_MMA(1, 0, At, B0); PG8_MMA(1, 1, At, B1); PG8_BAR; PG8_SCHED;
.LBB0_289:
	ds_read_b128 v[146:149], v156
	ds_read_b128 v[160:163], v156 offset:1024
	ds_read_b128 v[164:167], v156 offset:2048
	ds_read_b128 v[168:171], v156 offset:3072
	ds_read_b128 v[180:183], v157
	ds_read_b128 v[184:187], v157 offset:1024
	ds_read_b128 v[188:191], v157 offset:2048
	ds_read_b128 v[192:195], v157 offset:3072
	s_add_u32 s24, s22, 0xfff80080
	s_addc_u32 s25, s23, -1
	s_cmp_eq_u32 s50, 28
	s_cselect_b32 s27, s15, s25
	s_cselect_b32 s26, s46, s24
	s_cselect_b32 s25, s13, s49
	s_cselect_b32 s24, s47, s48
	v_lshl_add_u64 v[150:151], s[22:23], 0, v[138:139]
	s_add_i32 m0, s21, 0xc000
	ds_read_b128 v[196:199], v158
	ds_read_b128 v[200:203], v158 offset:1024
	ds_read_b128 v[204:207], v158 offset:2048
	ds_read_b128 v[208:211], v158 offset:3072
	ds_read_b128 v[212:215], v158 offset:4096
	ds_read_b128 v[216:219], v158 offset:5120
	ds_read_b128 v[220:223], v158 offset:6144
	ds_read_b128 v[224:227], v158 offset:7168
	global_load_lds_dwordx4 v[150:151], off
	v_lshl_add_u64 v[150:151], s[22:23], 0, v[140:141]
	s_add_i32 m0, s21, 0xe000
	s_nop 0
	global_load_lds_dwordx4 v[150:151], off
	s_waitcnt vmcnt(8)
	s_waitcnt lgkmcnt(0)
	v_mfma_f32_16x16x32_bf16 v[124:127], v[146:149], v[196:199], v[124:127]
	v_mfma_f32_16x16x32_bf16 v[120:123], v[164:167], v[196:199], v[120:123]
	s_barrier
	s_setprio 1
	s_waitcnt lgkmcnt(0)
	v_mfma_f32_16x16x32_bf16 v[116:119], v[146:149], v[204:207], v[116:119]
	v_mfma_f32_16x16x32_bf16 v[108:111], v[164:167], v[204:207], v[108:111]
	v_mfma_f32_16x16x32_bf16 v[100:103], v[146:149], v[212:215], v[100:103]
	v_mfma_f32_16x16x32_bf16 v[92:95], v[164:167], v[212:215], v[92:95]
	v_mfma_f32_16x16x32_bf16 v[84:87], v[146:149], v[220:223], v[84:87]
	v_mfma_f32_16x16x32_bf16 v[76:79], v[164:167], v[220:223], v[76:79]
	v_mfma_f32_16x16x32_bf16 v[124:127], v[160:163], v[200:203], v[124:127]
	v_mfma_f32_16x16x32_bf16 v[120:123], v[168:171], v[200:203], v[120:123]
	v_mfma_f32_16x16x32_bf16 v[116:119], v[160:163], v[208:211], v[116:119]
	v_mfma_f32_16x16x32_bf16 v[108:111], v[168:171], v[208:211], v[108:111]
	v_mfma_f32_16x16x32_bf16 v[100:103], v[160:163], v[216:219], v[100:103]
	v_mfma_f32_16x16x32_bf16 v[92:95], v[168:171], v[216:219], v[92:95]
	v_mfma_f32_16x16x32_bf16 v[84:87], v[160:163], v[224:227], v[84:87]
	v_mfma_f32_16x16x32_bf16 v[76:79], v[168:171], v[224:227], v[76:79]
	s_setprio 0
	s_setprio 1
	v_mfma_f32_16x16x32_bf16 v[112:115], v[180:183], v[196:199], v[112:115]
	v_mfma_f32_16x16x32_bf16 v[104:107], v[188:191], v[196:199], v[104:107]
	v_mfma_f32_16x16x32_bf16 v[96:99], v[180:183], v[204:207], v[96:99]
	v_mfma_f32_16x16x32_bf16 v[88:91], v[188:191], v[204:207], v[88:91]
	v_mfma_f32_16x16x32_bf16 v[80:83], v[180:183], v[212:215], v[80:83]
	v_mfma_f32_16x16x32_bf16 v[72:75], v[188:191], v[212:215], v[72:75]
	v_mfma_f32_16x16x32_bf16 v[68:71], v[180:183], v[220:223], v[68:71]
	v_mfma_f32_16x16x32_bf16 v[64:67], v[188:191], v[220:223], v[64:67]
	v_mfma_f32_16x16x32_bf16 v[112:115], v[184:187], v[200:203], v[112:115]
	v_mfma_f32_16x16x32_bf16 v[104:107], v[192:195], v[200:203], v[104:107]
	v_mfma_f32_16x16x32_bf16 v[96:99], v[184:187], v[208:211], v[96:99]
	v_mfma_f32_16x16x32_bf16 v[88:91], v[192:195], v[208:211], v[88:91]
	v_mfma_f32_16x16x32_bf16 v[80:83], v[184:187], v[216:219], v[80:83]
	v_mfma_f32_16x16x32_bf16 v[72:75], v[192:195], v[216:219], v[72:75]
	v_mfma_f32_16x16x32_bf16 v[68:71], v[184:187], v[224:227], v[68:71]
	v_mfma_f32_16x16x32_bf16 v[64:67], v[192:195], v[224:227], v[64:67]
	s_setprio 0
	s_barrier
	s_add_i32 s51, s40, s30
	v_lshl_add_u64 v[150:151], s[24:25], 0, v[134:135]
	s_mov_b32 m0, s51
	ds_read_b128 v[196:199], v158 offset:16384
	ds_read_b128 v[200:203], v158 offset:17408
	ds_read_b128 v[204:207], v158 offset:18432
	ds_read_b128 v[208:211], v158 offset:19456
	ds_read_b128 v[212:215], v158 offset:20480
	ds_read_b128 v[216:219], v158 offset:21504
	ds_read_b128 v[220:223], v158 offset:22528
	ds_read_b128 v[224:227], v158 offset:23552
	global_load_lds_dwordx4 v[150:151], off
	s_add_i32 m0, s51, 0x2000
	s_add_u32 s52, s24, 0x80000
	v_lshl_add_u64 v[228:229], s[24:25], 0, v[130:131]
	s_addc_u32 s53, s25, 0
	s_add_i32 s51, s41, s30
	global_load_lds_dwordx4 v[228:229], off
	v_lshl_add_u64 v[230:231], s[52:53], 0, v[134:135]
	s_mov_b32 m0, s51
	v_lshl_add_u64 v[232:233], s[26:27], 0, v[132:133]
	global_load_lds_dwordx4 v[230:231], off
	v_lshl_add_u64 v[230:231], s[52:53], 0, v[130:131]
	s_add_i32 m0, s51, 0x2000
	s_nop 0
	global_load_lds_dwordx4 v[230:231], off
	v_lshl_add_u64 v[230:231], s[26:27], 0, v[136:137]
	s_mov_b32 m0, s21
	s_nop 0
	global_load_lds_dwordx4 v[230:231], off
	s_mov_b32 m0, s33
	s_nop 0
	global_load_lds_dwordx4 v[232:233], off
	s_waitcnt vmcnt(8)
	s_waitcnt lgkmcnt(0)
	v_mfma_f32_16x16x32_bf16 v[60:63], v[146:149], v[196:199], v[60:63]
	v_mfma_f32_16x16x32_bf16 v[56:59], v[164:167], v[196:199], v[56:59]
	s_barrier
; #define PG8_STAGE(bufoff, gbase, voff) do { _Pragma("unroll") for (int _i = 0; _i < 2; ++_i) \
;         __builtin_amdgcn_global_load_lds((const unsigned*)((const char*)(gbase) + (voff)[_i]), (PG8_LAS unsigned*)(lds + (bufoff) + ldsw + _i * 8192), 16, 0, 0); } while (0)
; #define PG8_LDA(dst, b, h) do { _Pragma("unroll") for (int m = 0; m < 4; ++m) _Pragma("unroll") for (int k = 0; k < 2; ++k) dst[m][k] = *(const PG8_LAS bf16x8*)(lds + PG8_SA(b, h) + aoff + m * 2048 + k * 1024); } while (0)
; #define PG8_LDB(dst, b, h) do { _Pragma("unroll") for (int n = 0; n < 2; ++n) _Pragma("unroll") for (int k = 0; k < 2; ++k) dst[n][k] = *(const PG8_LAS bf16x8*)(lds + PG8_SB(b, h) + boff + n * 2048 + k * 1024); } while (0)
; #define PG8_MMA(ai, bj, At, Bt) do { __builtin_amdgcn_s_setprio(1); _Pragma("unroll") for (int m = 0; m < 4; ++m) _Pragma("unroll") for (int n = 0; n < 2; ++n) _Pragma("unroll") for (int k = 0; k < 2; ++k) \
;         acc[ai][bj][m][n] = __builtin_amdgcn_mfma_f32_16x16x32_bf16(Bt[n][k], At[m][k], acc[ai][bj][m][n], 0, 0, 0); __builtin_amdgcn_s_setprio(0); } while (0)
; #define PG8_WAIT_V(n) asm volatile("s_waitcnt vmcnt(" #n ")" ::: "memory")
; #define PG8_WAIT_L(n) asm volatile("s_waitcnt lgkmcnt(" #n ")" ::: "memory")
; #define PG8_BAR __builtin_amdgcn_s_barrier()
; #define PG8_SCHED __builtin_amdgcn_sched_barrier(0)
; template <class Epi, class Sched, bool ALIGN_EPI = false, bool SP2 = false>
; __device__ __forceinline__ void gemm_phase(PG8_LAS unsigned char* lds, const Gemm g, const Sched& S, const Epi& E) {
;     ...
;             PG8_WAIT_V(8); PG8_WAIT_L(0); PG8_BAR; PG8_MMA(1, 0, At, B0); PG8_MMA(1, 1, At, B1); PG8_BAR; PG8_SCHED;
;             PG8_LDB(B0, 1, 0); PG8_LDB(B1, 1, 1); PG8_SCHED; PG8_LDA(At, 1, 0); PG8_STAGE(PG8_SA(0, 1), a2 + hstep, voffA);
;             PG8_WAIT_V(8); PG8_WAIT_L(0); PG8_BAR; PG8_MMA(0, 0, At, B0); PG8_MMA(0, 1, At, B1); PG8_BAR; PG8_SCHED;
	s_setprio 1
	s_waitcnt lgkmcnt(0)
	v_mfma_f32_16x16x32_bf16 v[52:55], v[146:149], v[204:207], v[52:55]
	v_mfma_f32_16x16x32_bf16 v[44:47], v[164:167], v[204:207], v[44:47]
	v_mfma_f32_16x16x32_bf16 v[36:39], v[146:149], v[212:215], v[36:39]
	v_mfma_f32_16x16x32_bf16 v[28:31], v[164:167], v[212:215], v[28:31]
	v_mfma_f32_16x16x32_bf16 v[20:23], v[146:149], v[220:223], v[20:23]
	v_mfma_f32_16x16x32_bf16 v[12:15], v[164:167], v[220:223], v[12:15]
	v_mfma_f32_16x16x32_bf16 v[60:63], v[160:163], v[200:203], v[60:63]
	v_mfma_f32_16x16x32_bf16 v[56:59], v[168:171], v[200:203], v[56:59]
	v_mfma_f32_16x16x32_bf16 v[52:55], v[160:163], v[208:211], v[52:55]
	v_mfma_f32_16x16x32_bf16 v[44:47], v[168:171], v[208:211], v[44:47]
	v_mfma_f32_16x16x32_bf16 v[36:39], v[160:163], v[216:219], v[36:39]
	v_mfma_f32_16x16x32_bf16 v[28:31], v[168:171], v[216:219], v[28:31]
	v_mfma_f32_16x16x32_bf16 v[20:23], v[160:163], v[224:227], v[20:23]
	v_mfma_f32_16x16x32_bf16 v[12:15], v[168:171], v[224:227], v[12:15]
	s_setprio 0
	s_setprio 1
	v_mfma_f32_16x16x32_bf16 v[48:51], v[180:183], v[196:199], v[48:51]
	v_mfma_f32_16x16x32_bf16 v[40:43], v[188:191], v[196:199], v[40:43]
	v_mfma_f32_16x16x32_bf16 v[32:35], v[180:183], v[204:207], v[32:35]
	v_mfma_f32_16x16x32_bf16 v[24:27], v[188:191], v[204:207], v[24:27]
	v_mfma_f32_16x16x32_bf16 v[16:19], v[180:183], v[212:215], v[16:19]
	v_mfma_f32_16x16x32_bf16 v[8:11], v[188:191], v[212:215], v[8:11]
	v_mfma_f32_16x16x32_bf16 v[4:7], v[180:183], v[220:223], v[4:7]
	v_mfma_f32_16x16x32_bf16 v[0:3], v[188:191], v[220:223], v[0:3]
	v_mfma_f32_16x16x32_bf16 v[48:51], v[184:187], v[200:203], v[48:51]
	v_mfma_f32_16x16x32_bf16 v[40:43], v[192:195], v[200:203], v[40:43]
	v_mfma_f32_16x16x32_bf16 v[32:35], v[184:187], v[208:211], v[32:35]
	v_mfma_f32_16x16x32_bf16 v[24:27], v[192:195], v[208:211], v[24:27]
	v_mfma_f32_16x16x32_bf16 v[16:19], v[184:187], v[216:219], v[16:19]
	v_mfma_f32_16x16x32_bf16 v[8:11], v[192:195], v[216:219], v[8:11]
	v_mfma_f32_16x16x32_bf16 v[4:7], v[184:187], v[224:227], v[4:7]
	v_mfma_f32_16x16x32_bf16 v[0:3], v[192:195], v[224:227], v[0:3]
	s_setprio 0
	s_barrier
	s_add_i32 s51, 0, 0x18000
	v_add_u32_e32 v159, s51, v153
	s_add_i32 s52, 0, 0x1c000
	ds_read_b128 v[146:149], v159
	ds_read_b128 v[160:163], v159 offset:1024
	ds_read_b128 v[164:167], v159 offset:2048
	ds_read_b128 v[168:171], v159 offset:3072
	v_add_u32_e32 v159, s52, v153
	ds_read_b128 v[180:183], v159
	ds_read_b128 v[184:187], v159 offset:1024
	ds_read_b128 v[188:191], v159 offset:2048
	ds_read_b128 v[192:195], v159 offset:3072
	s_add_u32 s26, s26, 0x80000
	s_addc_u32 s27, s27, 0
	s_mov_b32 m0, s34
	v_lshl_add_u64 v[234:235], s[26:27], 0, v[136:137]
	ds_read_b128 v[196:199], v158 offset:32768
	ds_read_b128 v[200:203], v158 offset:33792
	ds_read_b128 v[204:207], v158 offset:34816
	ds_read_b128 v[208:211], v158 offset:35840
	ds_read_b128 v[212:215], v158 offset:36864
	ds_read_b128 v[216:219], v158 offset:37888
	ds_read_b128 v[220:223], v158 offset:38912
	ds_read_b128 v[224:227], v158 offset:39936
	global_load_lds_dwordx4 v[234:235], off
	v_lshl_add_u64 v[234:235], s[26:27], 0, v[132:133]
	s_mov_b32 m0, s35
	s_nop 0
	global_load_lds_dwordx4 v[234:235], off
	s_waitcnt vmcnt(8)
	s_waitcnt lgkmcnt(0)
	v_mfma_f32_16x16x32_bf16 v[124:127], v[146:149], v[196:199], v[124:127]
	v_mfma_f32_16x16x32_bf16 v[120:123], v[164:167], v[196:199], v[120:123]
	s_barrier
	s_setprio 1
	s_waitcnt lgkmcnt(0)
	v_mfma_f32_16x16x32_bf16 v[116:119], v[146:149], v[204:207], v[116:119]
	v_mfma_f32_16x16x32_bf16 v[108:111], v[164:167], v[204:207], v[108:111]
	v_mfma_f32_16x16x32_bf16 v[100:103], v[146:149], v[212:215], v[100:103]
	v_mfma_f32_16x16x32_bf16 v[92:95], v[164:167], v[212:215], v[92:95]
	v_mfma_f32_16x16x32_bf16 v[84:87], v[146:149], v[220:223], v[84:87]
	v_mfma_f32_16x16x32_bf16 v[76:79], v[164:167], v[220:223], v[76:79]
	v_mfma_f32_16x16x32_bf16 v[124:127], v[160:163], v[200:203], v[124:127]
	v_mfma_f32_16x16x32_bf16 v[120:123], v[168:171], v[200:203], v[120:123]
	v_mfma_f32_16x16x32_bf16 v[116:119], v[160:163], v[208:211], v[116:119]
	v_mfma_f32_16x16x32_bf16 v[108:111], v[168:171], v[208:211], v[108:111]
	v_mfma_f32_16x16x32_bf16 v[100:103], v[160:163], v[216:219], v[100:103]
	v_mfma_f32_16x16x32_bf16 v[92:95], v[168:171], v[216:219], v[92:95]
	v_mfma_f32_16x16x32_bf16 v[84:87], v[160:163], v[224:227], v[84:87]
	v_mfma_f32_16x16x32_bf16 v[76:79], v[168:171], v[224:227], v[76:79]
	s_setprio 0
	s_setprio 1
	v_mfma_f32_16x16x32_bf16 v[112:115], v[180:183], v[196:199], v[112:115]
	v_mfma_f32_16x16x32_bf16 v[104:107], v[188:191], v[196:199], v[104:107]
	v_mfma_f32_16x16x32_bf16 v[96:99], v[180:183], v[204:207], v[96:99]
	v_mfma_f32_16x16x32_bf16 v[88:91], v[188:191], v[204:207], v[88:91]
	v_mfma_f32_16x16x32_bf16 v[80:83], v[180:183], v[212:215], v[80:83]
	v_mfma_f32_16x16x32_bf16 v[72:75], v[188:191], v[212:215], v[72:75]
	v_mfma_f32_16x16x32_bf16 v[68:71], v[180:183], v[220:223], v[68:71]
	v_mfma_f32_16x16x32_bf16 v[64:67], v[188:191], v[220:223], v[64:67]
	v_mfma_f32_16x16x32_bf16 v[112:115], v[184:187], v[200:203], v[112:115]
	v_mfma_f32_16x16x32_bf16 v[104:107], v[192:195], v[200:203], v[104:107]
	v_mfma_f32_16x16x32_bf16 v[96:99], v[184:187], v[208:211], v[96:99]
	v_mfma_f32_16x16x32_bf16 v[88:91], v[192:195], v[208:211], v[88:91]
	v_mfma_f32_16x16x32_bf16 v[80:83], v[184:187], v[216:219], v[80:83]
	v_mfma_f32_16x16x32_bf16 v[72:75], v[192:195], v[216:219], v[72:75]
	v_mfma_f32_16x16x32_bf16 v[68:71], v[184:187], v[224:227], v[68:71]
	v_mfma_f32_16x16x32_bf16 v[64:67], v[192:195], v[224:227], v[64:67]
	s_setprio 0
	s_barrier
; #define PG8_STAGE(bufoff, gbase, voff) do { _Pragma("unroll") for (int _i = 0; _i < 2; ++_i) \
;         __builtin_amdgcn_global_load_lds((const unsigned*)((const char*)(gbase) + (voff)[_i]), (PG8_LAS unsigned*)(lds + (bufoff) + ldsw + _i * 8192), 16, 0, 0); } while (0)
; #define PG8_LDA(dst, b, h) do { _Pragma("unroll") for (int m = 0; m < 4; ++m) _Pragma("unroll") for (int k = 0; k < 2; ++k) dst[m][k] = *(const PG8_LAS bf16x8*)(lds + PG8_SA(b, h) + aoff + m * 2048 + k * 1024); } while (0)
; #define PG8_MMA(ai, bj, At, Bt) do { __builtin_amdgcn_s_setprio(1); _Pragma("unroll") for (int m = 0; m < 4; ++m) _Pragma("unroll") for (int n = 0; n < 2; ++n) _Pragma("unroll") for (int k = 0; k < 2; ++k) \
;         acc[ai][bj][m][n] = __builtin_amdgcn_mfma_f32_16x16x32_bf16(Bt[n][k], At[m][k], acc[ai][bj][m][n], 0, 0, 0); __builtin_amdgcn_s_setprio(0); } while (0)
; #define PG8_WAIT_V(n) asm volatile("s_waitcnt vmcnt(" #n ")" ::: "memory")
; #define PG8_WAIT_L(n) asm volatile("s_waitcnt lgkmcnt(" #n ")" ::: "memory")
; #define PG8_BAR __builtin_amdgcn_s_barrier()
; #define PG8_SCHED __builtin_amdgcn_sched_barrier(0)
; template <class Epi, class Sched, bool ALIGN_EPI = false, bool SP2 = false>
; __device__ __forceinline__ void gemm_phase(PG8_LAS unsigned char* lds, const Gemm g, const Sched& S, const Epi& E) {
;     ...
;             PG8_LDA(At, 1, 1); PG8_STAGE(PG8_SB(1, 0), b3, voffB); PG8_STAGE(PG8_SB(1, 1), b3 + hstep, voffB); PG8_STAGE(PG8_SA(1, 0), a3, voffA);
;             PG8_WAIT_V(8); PG8_WAIT_L(0); PG8_BAR; PG8_MMA(1, 0, At, B0); PG8_MMA(1, 1, At, B1); PG8_BAR; PG8_SCHED;
	s_add_i32 s26, s51, s30
	v_lshl_add_u64 v[150:151], v[150:151], 0, s[2:3]
	s_mov_b32 m0, s26
	ds_read_b128 v[196:199], v158 offset:49152
	ds_read_b128 v[200:203], v158 offset:50176
	ds_read_b128 v[204:207], v158 offset:51200
	ds_read_b128 v[208:211], v158 offset:52224
	ds_read_b128 v[212:215], v158 offset:53248
	ds_read_b128 v[216:219], v158 offset:54272
	ds_read_b128 v[220:223], v158 offset:55296
	ds_read_b128 v[224:227], v158 offset:56320
	global_load_lds_dwordx4 v[150:151], off
	s_add_i32 m0, s26, 0x2000
	s_add_u32 s24, s24, 0x80080
	v_lshl_add_u64 v[150:151], v[228:229], 0, s[2:3]
	s_addc_u32 s25, s25, 0
	s_add_i32 s26, s52, s30
	global_load_lds_dwordx4 v[150:151], off
	v_lshl_add_u64 v[150:151], s[24:25], 0, v[134:135]
	s_mov_b32 m0, s26
	s_nop 0
	global_load_lds_dwordx4 v[150:151], off
	v_lshl_add_u64 v[150:151], s[24:25], 0, v[130:131]
	s_add_i32 m0, s26, 0x2000
	s_nop 0
	global_load_lds_dwordx4 v[150:151], off
	v_lshl_add_u64 v[150:151], v[230:231], 0, s[2:3]
	s_mov_b32 m0, s36
	s_nop 0
	global_load_lds_dwordx4 v[150:151], off
	v_lshl_add_u64 v[150:151], v[232:233], 0, s[2:3]
	s_mov_b32 m0, s37
	s_nop 0
	global_load_lds_dwordx4 v[150:151], off
	s_waitcnt vmcnt(8)
	s_waitcnt lgkmcnt(0)
	v_mfma_f32_16x16x32_bf16 v[60:63], v[146:149], v[196:199], v[60:63]
	v_mfma_f32_16x16x32_bf16 v[56:59], v[164:167], v[196:199], v[56:59]
	s_barrier
	s_setprio 1
	s_waitcnt lgkmcnt(0)
	v_mfma_f32_16x16x32_bf16 v[52:55], v[146:149], v[204:207], v[52:55]
	v_mfma_f32_16x16x32_bf16 v[44:47], v[164:167], v[204:207], v[44:47]
	v_mfma_f32_16x16x32_bf16 v[36:39], v[146:149], v[212:215], v[36:39]
	v_mfma_f32_16x16x32_bf16 v[28:31], v[164:167], v[212:215], v[28:31]
	v_mfma_f32_16x16x32_bf16 v[20:23], v[146:149], v[220:223], v[20:23]
	v_mfma_f32_16x16x32_bf16 v[12:15], v[164:167], v[220:223], v[12:15]
	v_mfma_f32_16x16x32_bf16 v[60:63], v[160:163], v[200:203], v[60:63]
	v_mfma_f32_16x16x32_bf16 v[56:59], v[168:171], v[200:203], v[56:59]
	v_mfma_f32_16x16x32_bf16 v[52:55], v[160:163], v[208:211], v[52:55]
	v_mfma_f32_16x16x32_bf16 v[44:47], v[168:171], v[208:211], v[44:47]
	v_mfma_f32_16x16x32_bf16 v[36:39], v[160:163], v[216:219], v[36:39]
	v_mfma_f32_16x16x32_bf16 v[28:31], v[168:171], v[216:219], v[28:31]
	v_mfma_f32_16x16x32_bf16 v[20:23], v[160:163], v[224:227], v[20:23]
	v_mfma_f32_16x16x32_bf16 v[12:15], v[168:171], v[224:227], v[12:15]
	s_setprio 0
	s_setprio 1
	v_mfma_f32_16x16x32_bf16 v[48:51], v[180:183], v[196:199], v[48:51]
	v_mfma_f32_16x16x32_bf16 v[40:43], v[188:191], v[196:199], v[40:43]
	v_mfma_f32_16x16x32_bf16 v[32:35], v[180:183], v[204:207], v[32:35]
	v_mfma_f32_16x16x32_bf16 v[24:27], v[188:191], v[204:207], v[24:27]
	v_mfma_f32_16x16x32_bf16 v[16:19], v[180:183], v[212:215], v[16:19]
	v_mfma_f32_16x16x32_bf16 v[8:11], v[188:191], v[212:215], v[8:11]
	v_mfma_f32_16x16x32_bf16 v[4:7], v[180:183], v[220:223], v[4:7]
	v_mfma_f32_16x16x32_bf16 v[0:3], v[188:191], v[220:223], v[0:3]
	v_mfma_f32_16x16x32_bf16 v[48:51], v[184:187], v[200:203], v[48:51]
	v_mfma_f32_16x16x32_bf16 v[40:43], v[192:195], v[200:203], v[40:43]
	v_mfma_f32_16x16x32_bf16 v[32:35], v[184:187], v[208:211], v[32:35]
	v_mfma_f32_16x16x32_bf16 v[24:27], v[192:195], v[208:211], v[24:27]
	v_mfma_f32_16x16x32_bf16 v[16:19], v[184:187], v[216:219], v[16:19]
	v_mfma_f32_16x16x32_bf16 v[8:11], v[192:195], v[216:219], v[8:11]
	v_mfma_f32_16x16x32_bf16 v[4:7], v[184:187], v[224:227], v[4:7]
	v_mfma_f32_16x16x32_bf16 v[0:3], v[192:195], v[224:227], v[0:3]
	s_setprio 0
	s_barrier
	s_add_i32 s50, s50, 2
	s_add_u32 s22, s22, 0x100
	s_addc_u32 s23, s23, 0
	s_add_u32 s48, s48, 0x100
	s_addc_u32 s49, s49, 0
	s_cmp_gt_u32 s50, 29
	s_cbranch_scc0 .LBB0_289
	s_and_b64 vcc, exec, s[4:5]
	s_cbranch_vccz .LBB0_292
	s_barrier

; #define PG8_STAGE(bufoff, gbase, voff) do { _Pragma("unroll") for (int _i = 0; _i < 2; ++_i) \
;         __builtin_amdgcn_global_load_lds((const unsigned*)((const char*)(gbase) + (voff)[_i]), (PG8_LAS unsigned*)(lds + (bufoff) + ldsw + _i * 8192), 16, 0, 0); } while (0)
; #define PG8_LDA(dst, b, h) do { _Pragma("unroll") for (int m = 0; m < 4; ++m) _Pragma("unroll") for (int k = 0; k < 2; ++k) dst[m][k] = *(const PG8_LAS bf16x8*)(lds + PG8_SA(b, h) + aoff + m * 2048 + k * 1024); } while (0)
; #define PG8_LDB(dst, b, h) do { _Pragma("unroll") for (int n = 0; n < 2; ++n) _Pragma("unroll") for (int k = 0; k < 2; ++k) dst[n][k] = *(const PG8_LAS bf16x8*)(lds + PG8_SB(b, h) + boff + n * 2048 + k * 1024); } while (0)
; #define PG8_MMA(ai, bj, At, Bt) do { __builtin_amdgcn_s_setprio(1); _Pragma("unroll") for (int m = 0; m < 4; ++m) _Pragma("unroll") for (int n = 0; n < 2; ++n) _Pragma("unroll") for (int k = 0; k < 2; ++k) \
;         acc[ai][bj][m][n] = __builtin_amdgcn_mfma_f32_16x16x32_bf16(Bt[n][k], At[m][k], acc[ai][bj][m][n], 0, 0, 0); __builtin_amdgcn_s_setprio(0); } while (0)
; #define PG8_WAIT_V(n) asm volatile("s_waitcnt vmcnt(" #n ")" ::: "memory")
; #define PG8_WAIT_L(n) asm volatile("s_waitcnt lgkmcnt(" #n ")" ::: "memory")
; #define PG8_BAR __builtin_amdgcn_s_barrier()
; #define PG8_SCHED __builtin_amdgcn_sched_barrier(0)
; template <class Epi, class Sched, bool ALIGN_EPI = false, bool SP2 = false>
; __device__ __forceinline__ void gemm_phase(PG8_LAS unsigned char* lds, const Gemm g, const Sched& S, const Epi& E) {
;     ...
;             PG8_LDB(B0, 0, 0); PG8_LDB(B1, 0, 1); PG8_SCHED; PG8_LDA(At, 0, 0); PG8_STAGE(PG8_SA(1, 1), a1 + hstep, voffA);
;             PG8_WAIT_V(8); PG8_WAIT_L(0); PG8_BAR; PG8_MMA(0, 0, At, B0); PG8_MMA(0, 1, At, B1); PG8_BAR; PG8_SCHED;
;             PG8_LDA(At, 0, 1); PG8_STAGE(PG8_SB(0, 0), b2, voffB); PG8_STAGE(PG8_SB(0, 1), b2 + hstep, voffB); PG8_STAGE(PG8_SA(0, 0), a2, voffA);
;             PG8_WAIT_V(8); PG8_WAIT_L(0); PG8_BAR; PG8_MMA(1, 0, At, B0); PG8_MMA(1, 1, At, B1); PG8_BAR; PG8_SCHED;
.LBB0_585:
	ds_read_b128 v[142:145], v149
	ds_read_b128 v[152:155], v149 offset:1024
	ds_read_b128 v[156:159], v149 offset:2048
	ds_read_b128 v[160:163], v149 offset:3072
	ds_read_b128 v[164:167], v150
	ds_read_b128 v[168:171], v150 offset:1024
	ds_read_b128 v[180:183], v150 offset:2048
	ds_read_b128 v[184:187], v150 offset:3072
	s_add_u32 s26, s24, 0xfff80080
	s_addc_u32 s27, s25, -1
	s_cmp_eq_u32 s51, 28
	s_cselect_b32 s29, s17, s27
	s_cselect_b32 s28, s23, s26
	s_cselect_b32 s27, s13, s50
	s_cselect_b32 s26, s48, s49
	v_lshl_add_u64 v[220:221], s[24:25], 0, v[134:135]
	s_add_i32 m0, s34, 0xc000
	ds_read_b128 v[188:191], v151
	ds_read_b128 v[192:195], v151 offset:1024
	ds_read_b128 v[196:199], v151 offset:2048
	ds_read_b128 v[200:203], v151 offset:3072
	ds_read_b128 v[204:207], v151 offset:4096
	ds_read_b128 v[208:211], v151 offset:5120
	ds_read_b128 v[212:215], v151 offset:6144
	ds_read_b128 v[216:219], v151 offset:7168
	global_load_lds_dwordx4 v[220:221], off
	v_lshl_add_u64 v[220:221], s[24:25], 0, v[136:137]
	s_add_i32 m0, s34, 0xe000
	s_nop 0
	global_load_lds_dwordx4 v[220:221], off
	s_waitcnt vmcnt(8)
	s_waitcnt lgkmcnt(0)
	v_mfma_f32_16x16x32_bf16 v[124:127], v[142:145], v[188:191], v[124:127]
	v_mfma_f32_16x16x32_bf16 v[120:123], v[156:159], v[188:191], v[120:123]
	s_barrier
	s_setprio 1
	s_waitcnt lgkmcnt(0)
	v_mfma_f32_16x16x32_bf16 v[108:111], v[142:145], v[196:199], v[108:111]
	v_mfma_f32_16x16x32_bf16 v[104:107], v[156:159], v[196:199], v[104:107]
	v_mfma_f32_16x16x32_bf16 v[92:95], v[142:145], v[204:207], v[92:95]
	v_mfma_f32_16x16x32_bf16 v[88:91], v[156:159], v[204:207], v[88:91]
	v_mfma_f32_16x16x32_bf16 v[76:79], v[142:145], v[212:215], v[76:79]
	v_mfma_f32_16x16x32_bf16 v[72:75], v[156:159], v[212:215], v[72:75]
	v_mfma_f32_16x16x32_bf16 v[124:127], v[152:155], v[192:195], v[124:127]
	v_mfma_f32_16x16x32_bf16 v[120:123], v[160:163], v[192:195], v[120:123]
	v_mfma_f32_16x16x32_bf16 v[108:111], v[152:155], v[200:203], v[108:111]
	v_mfma_f32_16x16x32_bf16 v[104:107], v[160:163], v[200:203], v[104:107]
	v_mfma_f32_16x16x32_bf16 v[92:95], v[152:155], v[208:211], v[92:95]
	v_mfma_f32_16x16x32_bf16 v[88:91], v[160:163], v[208:211], v[88:91]
	v_mfma_f32_16x16x32_bf16 v[76:79], v[152:155], v[216:219], v[76:79]
	v_mfma_f32_16x16x32_bf16 v[72:75], v[160:163], v[216:219], v[72:75]
	s_setprio 0
	s_setprio 1
	v_mfma_f32_16x16x32_bf16 v[116:119], v[164:167], v[188:191], v[116:119]
	v_mfma_f32_16x16x32_bf16 v[112:115], v[180:183], v[188:191], v[112:115]
	v_mfma_f32_16x16x32_bf16 v[100:103], v[164:167], v[196:199], v[100:103]
	v_mfma_f32_16x16x32_bf16 v[96:99], v[180:183], v[196:199], v[96:99]
	v_mfma_f32_16x16x32_bf16 v[84:87], v[164:167], v[204:207], v[84:87]
	v_mfma_f32_16x16x32_bf16 v[80:83], v[180:183], v[204:207], v[80:83]
	v_mfma_f32_16x16x32_bf16 v[68:71], v[164:167], v[212:215], v[68:71]
	v_mfma_f32_16x16x32_bf16 v[64:67], v[180:183], v[212:215], v[64:67]
	v_mfma_f32_16x16x32_bf16 v[116:119], v[168:171], v[192:195], v[116:119]
	v_mfma_f32_16x16x32_bf16 v[112:115], v[184:187], v[192:195], v[112:115]
	v_mfma_f32_16x16x32_bf16 v[100:103], v[168:171], v[200:203], v[100:103]
	v_mfma_f32_16x16x32_bf16 v[96:99], v[184:187], v[200:203], v[96:99]
	v_mfma_f32_16x16x32_bf16 v[84:87], v[168:171], v[208:211], v[84:87]
	v_mfma_f32_16x16x32_bf16 v[80:83], v[184:187], v[208:211], v[80:83]
	v_mfma_f32_16x16x32_bf16 v[68:71], v[168:171], v[216:219], v[68:71]
	v_mfma_f32_16x16x32_bf16 v[64:67], v[184:187], v[216:219], v[64:67]
	s_setprio 0
	s_barrier
	s_add_i32 s52, s45, s33
	v_lshl_add_u64 v[220:221], s[26:27], 0, v[130:131]
	s_mov_b32 m0, s52
	ds_read_b128 v[188:191], v151 offset:16384
	ds_read_b128 v[192:195], v151 offset:17408
	ds_read_b128 v[196:199], v151 offset:18432
	ds_read_b128 v[200:203], v151 offset:19456
	ds_read_b128 v[204:207], v151 offset:20480
	ds_read_b128 v[208:211], v151 offset:21504
	ds_read_b128 v[212:215], v151 offset:22528
	ds_read_b128 v[216:219], v151 offset:23552
	global_load_lds_dwordx4 v[220:221], off
	s_add_i32 m0, s52, 0x2000
	s_add_u32 s52, s26, 0x80000
	v_lshl_add_u64 v[222:223], s[26:27], 0, v[132:133]
	s_addc_u32 s53, s27, 0
	s_add_i32 s54, s46, s33
	global_load_lds_dwordx4 v[222:223], off
	v_lshl_add_u64 v[224:225], s[52:53], 0, v[130:131]
	s_mov_b32 m0, s54
	v_lshl_add_u64 v[226:227], s[28:29], 0, v[132:133]
	global_load_lds_dwordx4 v[224:225], off
	v_lshl_add_u64 v[224:225], s[52:53], 0, v[132:133]
	s_add_i32 m0, s54, 0x2000
	s_nop 0
	global_load_lds_dwordx4 v[224:225], off
	v_lshl_add_u64 v[224:225], s[28:29], 0, v[130:131]
	s_mov_b32 m0, s34
	s_nop 0
	global_load_lds_dwordx4 v[224:225], off
	s_mov_b32 m0, s35
	s_nop 0
	global_load_lds_dwordx4 v[226:227], off
	s_waitcnt vmcnt(8)
	s_waitcnt lgkmcnt(0)
	v_mfma_f32_16x16x32_bf16 v[60:63], v[142:145], v[188:191], v[60:63]
	v_mfma_f32_16x16x32_bf16 v[56:59], v[156:159], v[188:191], v[56:59]
	s_barrier
; #define PG8_STAGE(bufoff, gbase, voff) do { _Pragma("unroll") for (int _i = 0; _i < 2; ++_i) \
;         __builtin_amdgcn_global_load_lds((const unsigned*)((const char*)(gbase) + (voff)[_i]), (PG8_LAS unsigned*)(lds + (bufoff) + ldsw + _i * 8192), 16, 0, 0); } while (0)
; #define PG8_LDA(dst, b, h) do { _Pragma("unroll") for (int m = 0; m < 4; ++m) _Pragma("unroll") for (int k = 0; k < 2; ++k) dst[m][k] = *(const PG8_LAS bf16x8*)(lds + PG8_SA(b, h) + aoff + m * 2048 + k * 1024); } while (0)
; #define PG8_LDB(dst, b, h) do { _Pragma("unroll") for (int n = 0; n < 2; ++n) _Pragma("unroll") for (int k = 0; k < 2; ++k) dst[n][k] = *(const PG8_LAS bf16x8*)(lds + PG8_SB(b, h) + boff + n * 2048 + k * 1024); } while (0)
; #define PG8_MMA(ai, bj, At, Bt) do { __builtin_amdgcn_s_setprio(1); _Pragma("unroll") for (int m = 0; m < 4; ++m) _Pragma("unroll") for (int n = 0; n < 2; ++n) _Pragma("unroll") for (int k = 0; k < 2; ++k) \
;         acc[ai][bj][m][n] = __builtin_amdgcn_mfma_f32_16x16x32_bf16(Bt[n][k], At[m][k], acc[ai][bj][m][n], 0, 0, 0); __builtin_amdgcn_s_setprio(0); } while (0)
; #define PG8_WAIT_V(n) asm volatile("s_waitcnt vmcnt(" #n ")" ::: "memory")
; #define PG8_WAIT_L(n) asm volatile("s_waitcnt lgkmcnt(" #n ")" ::: "memory")
; #define PG8_BAR __builtin_amdgcn_s_barrier()
; #define PG8_SCHED __builtin_amdgcn_sched_barrier(0)
; template <class Epi, class Sched, bool ALIGN_EPI = false, bool SP2 = false>
; __device__ __forceinline__ void gemm_phase(PG8_LAS unsigned char* lds, const Gemm g, const Sched& S, const Epi& E) {
;     ...
;             PG8_WAIT_V(8); PG8_WAIT_L(0); PG8_BAR; PG8_MMA(1, 0, At, B0); PG8_MMA(1, 1, At, B1); PG8_BAR; PG8_SCHED;
;             PG8_LDB(B0, 1, 0); PG8_LDB(B1, 1, 1); PG8_SCHED; PG8_LDA(At, 1, 0); PG8_STAGE(PG8_SA(0, 1), a2 + hstep, voffA);
;             PG8_WAIT_V(8); PG8_WAIT_L(0); PG8_BAR; PG8_MMA(0, 0, At, B0); PG8_MMA(0, 1, At, B1); PG8_BAR; PG8_SCHED;
	s_setprio 1
	s_waitcnt lgkmcnt(0)
	v_mfma_f32_16x16x32_bf16 v[44:47], v[142:145], v[196:199], v[44:47]
	v_mfma_f32_16x16x32_bf16 v[40:43], v[156:159], v[196:199], v[40:43]
	v_mfma_f32_16x16x32_bf16 v[28:31], v[142:145], v[204:207], v[28:31]
	v_mfma_f32_16x16x32_bf16 v[24:27], v[156:159], v[204:207], v[24:27]
	v_mfma_f32_16x16x32_bf16 v[12:15], v[142:145], v[212:215], v[12:15]
	v_mfma_f32_16x16x32_bf16 v[8:11], v[156:159], v[212:215], v[8:11]
	v_mfma_f32_16x16x32_bf16 v[60:63], v[152:155], v[192:195], v[60:63]
	v_mfma_f32_16x16x32_bf16 v[56:59], v[160:163], v[192:195], v[56:59]
	v_mfma_f32_16x16x32_bf16 v[44:47], v[152:155], v[200:203], v[44:47]
	v_mfma_f32_16x16x32_bf16 v[40:43], v[160:163], v[200:203], v[40:43]
	v_mfma_f32_16x16x32_bf16 v[28:31], v[152:155], v[208:211], v[28:31]
	v_mfma_f32_16x16x32_bf16 v[24:27], v[160:163], v[208:211], v[24:27]
	v_mfma_f32_16x16x32_bf16 v[12:15], v[152:155], v[216:219], v[12:15]
	v_mfma_f32_16x16x32_bf16 v[8:11], v[160:163], v[216:219], v[8:11]
	s_setprio 0
	s_setprio 1
	v_mfma_f32_16x16x32_bf16 v[52:55], v[164:167], v[188:191], v[52:55]
	v_mfma_f32_16x16x32_bf16 v[48:51], v[180:183], v[188:191], v[48:51]
	v_mfma_f32_16x16x32_bf16 v[36:39], v[164:167], v[196:199], v[36:39]
	v_mfma_f32_16x16x32_bf16 v[32:35], v[180:183], v[196:199], v[32:35]
	v_mfma_f32_16x16x32_bf16 v[20:23], v[164:167], v[204:207], v[20:23]
	v_mfma_f32_16x16x32_bf16 v[16:19], v[180:183], v[204:207], v[16:19]
	v_mfma_f32_16x16x32_bf16 v[4:7], v[164:167], v[212:215], v[4:7]
	v_mfma_f32_16x16x32_bf16 v[0:3], v[180:183], v[212:215], v[0:3]
	v_mfma_f32_16x16x32_bf16 v[52:55], v[168:171], v[192:195], v[52:55]
	v_mfma_f32_16x16x32_bf16 v[48:51], v[184:187], v[192:195], v[48:51]
	v_mfma_f32_16x16x32_bf16 v[36:39], v[168:171], v[200:203], v[36:39]
	v_mfma_f32_16x16x32_bf16 v[32:35], v[184:187], v[200:203], v[32:35]
	v_mfma_f32_16x16x32_bf16 v[20:23], v[168:171], v[208:211], v[20:23]
	v_mfma_f32_16x16x32_bf16 v[16:19], v[184:187], v[208:211], v[16:19]
	v_mfma_f32_16x16x32_bf16 v[4:7], v[168:171], v[216:219], v[4:7]
	v_mfma_f32_16x16x32_bf16 v[0:3], v[184:187], v[216:219], v[0:3]
	s_setprio 0
	s_barrier
	s_add_i32 s52, 0, 0x18000
	s_add_i32 s53, 0, 0x1c000
	v_add_u32_e32 v160, s52, v147
	v_add_u32_e32 v179, s53, v147
	ds_read_b128 v[142:145], v160
	ds_read_b128 v[152:155], v160 offset:1024
	ds_read_b128 v[156:159], v160 offset:2048
	ds_read_b128 v[160:163], v160 offset:3072
	ds_read_b128 v[164:167], v179
	ds_read_b128 v[168:171], v179 offset:1024
	ds_read_b128 v[180:183], v179 offset:2048
	ds_read_b128 v[184:187], v179 offset:3072
	s_add_u32 s28, s28, 0x80000
	s_addc_u32 s29, s29, 0
	s_mov_b32 m0, s36
	v_lshl_add_u64 v[228:229], s[28:29], 0, v[130:131]
	ds_read_b128 v[188:191], v151 offset:32768
	ds_read_b128 v[192:195], v151 offset:33792
	ds_read_b128 v[196:199], v151 offset:34816
	ds_read_b128 v[200:203], v151 offset:35840
	ds_read_b128 v[204:207], v151 offset:36864
	ds_read_b128 v[208:211], v151 offset:37888
	ds_read_b128 v[212:215], v151 offset:38912
	ds_read_b128 v[216:219], v151 offset:39936
	global_load_lds_dwordx4 v[228:229], off
	v_lshl_add_u64 v[228:229], s[28:29], 0, v[132:133]
	s_mov_b32 m0, s37
	s_nop 0
	global_load_lds_dwordx4 v[228:229], off
	s_waitcnt vmcnt(8)
	s_waitcnt lgkmcnt(0)
	v_mfma_f32_16x16x32_bf16 v[124:127], v[142:145], v[188:191], v[124:127]
	v_mfma_f32_16x16x32_bf16 v[120:123], v[156:159], v[188:191], v[120:123]
	s_barrier
	s_setprio 1
	s_waitcnt lgkmcnt(0)
	v_mfma_f32_16x16x32_bf16 v[108:111], v[142:145], v[196:199], v[108:111]
	v_mfma_f32_16x16x32_bf16 v[104:107], v[156:159], v[196:199], v[104:107]
	v_mfma_f32_16x16x32_bf16 v[92:95], v[142:145], v[204:207], v[92:95]
	v_mfma_f32_16x16x32_bf16 v[88:91], v[156:159], v[204:207], v[88:91]
	v_mfma_f32_16x16x32_bf16 v[76:79], v[142:145], v[212:215], v[76:79]
	v_mfma_f32_16x16x32_bf16 v[72:75], v[156:159], v[212:215], v[72:75]
	v_mfma_f32_16x16x32_bf16 v[124:127], v[152:155], v[192:195], v[124:127]
	v_mfma_f32_16x16x32_bf16 v[120:123], v[160:163], v[192:195], v[120:123]
	v_mfma_f32_16x16x32_bf16 v[108:111], v[152:155], v[200:203], v[108:111]
	v_mfma_f32_16x16x32_bf16 v[104:107], v[160:163], v[200:203], v[104:107]
	v_mfma_f32_16x16x32_bf16 v[92:95], v[152:155], v[208:211], v[92:95]
	v_mfma_f32_16x16x32_bf16 v[88:91], v[160:163], v[208:211], v[88:91]
	v_mfma_f32_16x16x32_bf16 v[76:79], v[152:155], v[216:219], v[76:79]
	v_mfma_f32_16x16x32_bf16 v[72:75], v[160:163], v[216:219], v[72:75]
	s_setprio 0
	s_setprio 1
	v_mfma_f32_16x16x32_bf16 v[116:119], v[164:167], v[188:191], v[116:119]
	v_mfma_f32_16x16x32_bf16 v[112:115], v[180:183], v[188:191], v[112:115]
	v_mfma_f32_16x16x32_bf16 v[100:103], v[164:167], v[196:199], v[100:103]
	v_mfma_f32_16x16x32_bf16 v[96:99], v[180:183], v[196:199], v[96:99]
	v_mfma_f32_16x16x32_bf16 v[84:87], v[164:167], v[204:207], v[84:87]
	v_mfma_f32_16x16x32_bf16 v[80:83], v[180:183], v[204:207], v[80:83]
	v_mfma_f32_16x16x32_bf16 v[68:71], v[164:167], v[212:215], v[68:71]
	v_mfma_f32_16x16x32_bf16 v[64:67], v[180:183], v[212:215], v[64:67]
	v_mfma_f32_16x16x32_bf16 v[116:119], v[168:171], v[192:195], v[116:119]
	v_mfma_f32_16x16x32_bf16 v[112:115], v[184:187], v[192:195], v[112:115]
	v_mfma_f32_16x16x32_bf16 v[100:103], v[168:171], v[200:203], v[100:103]
	v_mfma_f32_16x16x32_bf16 v[96:99], v[184:187], v[200:203], v[96:99]
	v_mfma_f32_16x16x32_bf16 v[84:87], v[168:171], v[208:211], v[84:87]
	v_mfma_f32_16x16x32_bf16 v[80:83], v[184:187], v[208:211], v[80:83]
	v_mfma_f32_16x16x32_bf16 v[68:71], v[168:171], v[216:219], v[68:71]
	v_mfma_f32_16x16x32_bf16 v[64:67], v[184:187], v[216:219], v[64:67]
	s_setprio 0
	s_barrier
; #define PG8_STAGE(bufoff, gbase, voff) do { _Pragma("unroll") for (int _i = 0; _i < 2; ++_i) \
;         __builtin_amdgcn_global_load_lds((const unsigned*)((const char*)(gbase) + (voff)[_i]), (PG8_LAS unsigned*)(lds + (bufoff) + ldsw + _i * 8192), 16, 0, 0); } while (0)
; #define PG8_LDA(dst, b, h) do { _Pragma("unroll") for (int m = 0; m < 4; ++m) _Pragma("unroll") for (int k = 0; k < 2; ++k) dst[m][k] = *(const PG8_LAS bf16x8*)(lds + PG8_SA(b, h) + aoff + m * 2048 + k * 1024); } while (0)
; #define PG8_MMA(ai, bj, At, Bt) do { __builtin_amdgcn_s_setprio(1); _Pragma("unroll") for (int m = 0; m < 4; ++m) _Pragma("unroll") for (int n = 0; n < 2; ++n) _Pragma("unroll") for (int k = 0; k < 2; ++k) \
;         acc[ai][bj][m][n] = __builtin_amdgcn_mfma_f32_16x16x32_bf16(Bt[n][k], At[m][k], acc[ai][bj][m][n], 0, 0, 0); __builtin_amdgcn_s_setprio(0); } while (0)
; #define PG8_WAIT_V(n) asm volatile("s_waitcnt vmcnt(" #n ")" ::: "memory")
; #define PG8_WAIT_L(n) asm volatile("s_waitcnt lgkmcnt(" #n ")" ::: "memory")
; #define PG8_BAR __builtin_amdgcn_s_barrier()
; #define PG8_SCHED __builtin_amdgcn_sched_barrier(0)
; template <class Epi, class Sched, bool ALIGN_EPI = false, bool SP2 = false>
; __device__ __forceinline__ void gemm_phase(PG8_LAS unsigned char* lds, const Gemm g, const Sched& S, const Epi& E) {
;     ...
;             PG8_LDA(At, 1, 1); PG8_STAGE(PG8_SB(1, 0), b3, voffB); PG8_STAGE(PG8_SB(1, 1), b3 + hstep, voffB); PG8_STAGE(PG8_SA(1, 0), a3, voffA);
;             PG8_WAIT_V(8); PG8_WAIT_L(0); PG8_BAR; PG8_MMA(1, 0, At, B0); PG8_MMA(1, 1, At, B1); PG8_BAR; PG8_SCHED;
	s_add_i32 s28, s52, s33
	v_lshl_add_u64 v[220:221], v[220:221], 0, s[4:5]
	s_mov_b32 m0, s28
	ds_read_b128 v[188:191], v151 offset:49152
	ds_read_b128 v[192:195], v151 offset:50176
	ds_read_b128 v[196:199], v151 offset:51200
	ds_read_b128 v[200:203], v151 offset:52224
	ds_read_b128 v[204:207], v151 offset:53248
	ds_read_b128 v[208:211], v151 offset:54272
	ds_read_b128 v[212:215], v151 offset:55296
	ds_read_b128 v[216:219], v151 offset:56320
	global_load_lds_dwordx4 v[220:221], off
	s_add_i32 m0, s28, 0x2000
	s_add_u32 s26, s26, 0x80080
	v_lshl_add_u64 v[220:221], v[222:223], 0, s[4:5]
	s_addc_u32 s27, s27, 0
	s_add_i32 s28, s53, s33
	global_load_lds_dwordx4 v[220:221], off
	v_lshl_add_u64 v[220:221], s[26:27], 0, v[130:131]
	s_mov_b32 m0, s28
	s_nop 0
	global_load_lds_dwordx4 v[220:221], off
	v_lshl_add_u64 v[220:221], s[26:27], 0, v[132:133]
	s_add_i32 m0, s28, 0x2000
	s_nop 0
	global_load_lds_dwordx4 v[220:221], off
	v_lshl_add_u64 v[220:221], v[224:225], 0, s[4:5]
	s_mov_b32 m0, s41
	s_nop 0
	global_load_lds_dwordx4 v[220:221], off
	v_lshl_add_u64 v[220:221], v[226:227], 0, s[4:5]
	s_mov_b32 m0, s44
	s_nop 0
	global_load_lds_dwordx4 v[220:221], off
	s_waitcnt vmcnt(8)
	s_waitcnt lgkmcnt(0)
	v_mfma_f32_16x16x32_bf16 v[60:63], v[142:145], v[188:191], v[60:63]
	v_mfma_f32_16x16x32_bf16 v[56:59], v[156:159], v[188:191], v[56:59]
	s_barrier
	s_setprio 1
	s_waitcnt lgkmcnt(0)
	v_mfma_f32_16x16x32_bf16 v[44:47], v[142:145], v[196:199], v[44:47]
	v_mfma_f32_16x16x32_bf16 v[40:43], v[156:159], v[196:199], v[40:43]
	v_mfma_f32_16x16x32_bf16 v[28:31], v[142:145], v[204:207], v[28:31]
	v_mfma_f32_16x16x32_bf16 v[24:27], v[156:159], v[204:207], v[24:27]
	v_mfma_f32_16x16x32_bf16 v[12:15], v[142:145], v[212:215], v[12:15]
	v_mfma_f32_16x16x32_bf16 v[8:11], v[156:159], v[212:215], v[8:11]
	v_mfma_f32_16x16x32_bf16 v[60:63], v[152:155], v[192:195], v[60:63]
	v_mfma_f32_16x16x32_bf16 v[56:59], v[160:163], v[192:195], v[56:59]
	v_mfma_f32_16x16x32_bf16 v[44:47], v[152:155], v[200:203], v[44:47]
	v_mfma_f32_16x16x32_bf16 v[40:43], v[160:163], v[200:203], v[40:43]
	v_mfma_f32_16x16x32_bf16 v[28:31], v[152:155], v[208:211], v[28:31]
	v_mfma_f32_16x16x32_bf16 v[24:27], v[160:163], v[208:211], v[24:27]
	v_mfma_f32_16x16x32_bf16 v[12:15], v[152:155], v[216:219], v[12:15]
	v_mfma_f32_16x16x32_bf16 v[8:11], v[160:163], v[216:219], v[8:11]
	s_setprio 0
	s_setprio 1
	v_mfma_f32_16x16x32_bf16 v[52:55], v[164:167], v[188:191], v[52:55]
	v_mfma_f32_16x16x32_bf16 v[48:51], v[180:183], v[188:191], v[48:51]
	v_mfma_f32_16x16x32_bf16 v[36:39], v[164:167], v[196:199], v[36:39]
	v_mfma_f32_16x16x32_bf16 v[32:35], v[180:183], v[196:199], v[32:35]
	v_mfma_f32_16x16x32_bf16 v[20:23], v[164:167], v[204:207], v[20:23]
	v_mfma_f32_16x16x32_bf16 v[16:19], v[180:183], v[204:207], v[16:19]
	v_mfma_f32_16x16x32_bf16 v[4:7], v[164:167], v[212:215], v[4:7]
	v_mfma_f32_16x16x32_bf16 v[0:3], v[180:183], v[212:215], v[0:3]
	v_mfma_f32_16x16x32_bf16 v[52:55], v[168:171], v[192:195], v[52:55]
	v_mfma_f32_16x16x32_bf16 v[48:51], v[184:187], v[192:195], v[48:51]
	v_mfma_f32_16x16x32_bf16 v[36:39], v[168:171], v[200:203], v[36:39]
	v_mfma_f32_16x16x32_bf16 v[32:35], v[184:187], v[200:203], v[32:35]
	v_mfma_f32_16x16x32_bf16 v[20:23], v[168:171], v[208:211], v[20:23]
	v_mfma_f32_16x16x32_bf16 v[16:19], v[184:187], v[208:211], v[16:19]
	v_mfma_f32_16x16x32_bf16 v[4:7], v[168:171], v[216:219], v[4:7]
	v_mfma_f32_16x16x32_bf16 v[0:3], v[184:187], v[216:219], v[0:3]
	s_setprio 0
	s_barrier
	s_add_i32 s51, s51, 2
	s_add_u32 s24, s24, 0x100
	s_addc_u32 s25, s25, 0
	s_add_u32 s49, s49, 0x100
	s_addc_u32 s50, s50, 0
	s_cmp_gt_u32 s51, 29
	s_cbranch_scc0 .LBB0_585
	s_and_b64 vcc, exec, s[6:7]
	s_cbranch_vccz .LBB0_588
	s_barrier

; #define PG8_STAGE(bufoff, gbase, voff) do { _Pragma("unroll") for (int _i = 0; _i < 2; ++_i) \
;         __builtin_amdgcn_global_load_lds((const unsigned*)((const char*)(gbase) + (voff)[_i]), (PG8_LAS unsigned*)(lds + (bufoff) + ldsw + _i * 8192), 16, 0, 0); } while (0)
; #define PG8_LDA(dst, b, h) do { _Pragma("unroll") for (int m = 0; m < 4; ++m) _Pragma("unroll") for (int k = 0; k < 2; ++k) dst[m][k] = *(const PG8_LAS bf16x8*)(lds + PG8_SA(b, h) + aoff + m * 2048 + k * 1024); } while (0)
; #define PG8_LDB(dst, b, h) do { _Pragma("unroll") for (int n = 0; n < 2; ++n) _Pragma("unroll") for (int k = 0; k < 2; ++k) dst[n][k] = *(const PG8_LAS bf16x8*)(lds + PG8_SB(b, h) + boff + n * 2048 + k * 1024); } while (0)
; #define PG8_MMA(ai, bj, At, Bt) do { __builtin_amdgcn_s_setprio(1); _Pragma("unroll") for (int m = 0; m < 4; ++m) _Pragma("unroll") for (int n = 0; n < 2; ++n) _Pragma("unroll") for (int k = 0; k < 2; ++k) \
;         acc[ai][bj][m][n] = __builtin_amdgcn_mfma_f32_16x16x32_bf16(Bt[n][k], At[m][k], acc[ai][bj][m][n], 0, 0, 0); __builtin_amdgcn_s_setprio(0); } while (0)
; #define PG8_WAIT_V(n) asm volatile("s_waitcnt vmcnt(" #n ")" ::: "memory")
; #define PG8_WAIT_L(n) asm volatile("s_waitcnt lgkmcnt(" #n ")" ::: "memory")
; #define PG8_BAR __builtin_amdgcn_s_barrier()
; #define PG8_SCHED __builtin_amdgcn_sched_barrier(0)
; template <class Epi, class Sched, bool ALIGN_EPI = false, bool SP2 = false>
; __device__ __forceinline__ void gemm_phase(PG8_LAS unsigned char* lds, const Gemm g, const Sched& S, const Epi& E) {
;     ...
;             PG8_LDB(B0, 0, 0); PG8_LDB(B1, 0, 1); PG8_SCHED; PG8_LDA(At, 0, 0); PG8_STAGE(PG8_SA(1, 1), a1 + hstep, voffA);
;             PG8_WAIT_V(8); PG8_WAIT_L(0); PG8_BAR; PG8_MMA(0, 0, At, B0); PG8_MMA(0, 1, At, B1); PG8_BAR; PG8_SCHED;
;             PG8_LDA(At, 0, 1); PG8_STAGE(PG8_SB(0, 0), b2, voffB); PG8_STAGE(PG8_SB(0, 1), b2 + hstep, voffB); PG8_STAGE(PG8_SA(0, 0), a2, voffA);
;             PG8_WAIT_V(8); PG8_WAIT_L(0); PG8_BAR; PG8_MMA(1, 0, At, B0); PG8_MMA(1, 1, At, B1); PG8_BAR; PG8_SCHED;
.LBB0_837:
	ds_read_b128 v[146:149], v158
	ds_read_b128 v[150:153], v158 offset:1024
	ds_read_b128 v[162:165], v158 offset:2048
	ds_read_b128 v[166:169], v158 offset:3072
	ds_read_b128 v[180:183], v159
	ds_read_b128 v[184:187], v159 offset:1024
	ds_read_b128 v[188:191], v159 offset:2048
	ds_read_b128 v[192:195], v159 offset:3072
	s_add_u32 s22, s20, 0xfff80080
	s_addc_u32 s23, s21, -1
	s_cmp_eq_u32 s50, 28
	s_cselect_b32 s25, s11, s23
	s_cselect_b32 s24, s46, s22
	s_cselect_b32 s23, s7, s49
	s_cselect_b32 s22, s47, s48
	v_lshl_add_u64 v[170:171], s[20:21], 0, v[138:139]
	s_add_i32 m0, s30, 0xc000
	ds_read_b128 v[196:199], v160
	ds_read_b128 v[200:203], v160 offset:1024
	ds_read_b128 v[204:207], v160 offset:2048
	ds_read_b128 v[208:211], v160 offset:3072
	ds_read_b128 v[212:215], v160 offset:4096
	ds_read_b128 v[216:219], v160 offset:5120
	ds_read_b128 v[220:223], v160 offset:6144
	ds_read_b128 v[224:227], v160 offset:7168
	global_load_lds_dwordx4 v[170:171], off
	v_lshl_add_u64 v[170:171], s[20:21], 0, v[140:141]
	s_add_i32 m0, s30, 0xe000
	s_nop 0
	global_load_lds_dwordx4 v[170:171], off
	s_waitcnt vmcnt(8)
	s_waitcnt lgkmcnt(0)
	v_mfma_f32_16x16x32_bf16 v[124:127], v[146:149], v[196:199], v[124:127]
	v_mfma_f32_16x16x32_bf16 v[116:119], v[162:165], v[196:199], v[116:119]
	s_barrier
	s_setprio 1
	s_waitcnt lgkmcnt(0)
	v_mfma_f32_16x16x32_bf16 v[108:111], v[146:149], v[204:207], v[108:111]
	v_mfma_f32_16x16x32_bf16 v[100:103], v[162:165], v[204:207], v[100:103]
	v_mfma_f32_16x16x32_bf16 v[92:95], v[146:149], v[212:215], v[92:95]
	v_mfma_f32_16x16x32_bf16 v[84:87], v[162:165], v[212:215], v[84:87]
	v_mfma_f32_16x16x32_bf16 v[76:79], v[146:149], v[220:223], v[76:79]
	v_mfma_f32_16x16x32_bf16 v[68:71], v[162:165], v[220:223], v[68:71]
	v_mfma_f32_16x16x32_bf16 v[124:127], v[150:153], v[200:203], v[124:127]
	v_mfma_f32_16x16x32_bf16 v[116:119], v[166:169], v[200:203], v[116:119]
	v_mfma_f32_16x16x32_bf16 v[108:111], v[150:153], v[208:211], v[108:111]
	v_mfma_f32_16x16x32_bf16 v[100:103], v[166:169], v[208:211], v[100:103]
	v_mfma_f32_16x16x32_bf16 v[92:95], v[150:153], v[216:219], v[92:95]
	v_mfma_f32_16x16x32_bf16 v[84:87], v[166:169], v[216:219], v[84:87]
	v_mfma_f32_16x16x32_bf16 v[76:79], v[150:153], v[224:227], v[76:79]
	v_mfma_f32_16x16x32_bf16 v[68:71], v[166:169], v[224:227], v[68:71]
	s_setprio 0
	s_setprio 1
	v_mfma_f32_16x16x32_bf16 v[120:123], v[180:183], v[196:199], v[120:123]
	v_mfma_f32_16x16x32_bf16 v[112:115], v[188:191], v[196:199], v[112:115]
	v_mfma_f32_16x16x32_bf16 v[104:107], v[180:183], v[204:207], v[104:107]
	v_mfma_f32_16x16x32_bf16 v[96:99], v[188:191], v[204:207], v[96:99]
	v_mfma_f32_16x16x32_bf16 v[88:91], v[180:183], v[212:215], v[88:91]
	v_mfma_f32_16x16x32_bf16 v[80:83], v[188:191], v[212:215], v[80:83]
	v_mfma_f32_16x16x32_bf16 v[72:75], v[180:183], v[220:223], v[72:75]
	v_mfma_f32_16x16x32_bf16 v[64:67], v[188:191], v[220:223], v[64:67]
	v_mfma_f32_16x16x32_bf16 v[120:123], v[184:187], v[200:203], v[120:123]
	v_mfma_f32_16x16x32_bf16 v[112:115], v[192:195], v[200:203], v[112:115]
	v_mfma_f32_16x16x32_bf16 v[104:107], v[184:187], v[208:211], v[104:107]
	v_mfma_f32_16x16x32_bf16 v[96:99], v[192:195], v[208:211], v[96:99]
	v_mfma_f32_16x16x32_bf16 v[88:91], v[184:187], v[216:219], v[88:91]
	v_mfma_f32_16x16x32_bf16 v[80:83], v[192:195], v[216:219], v[80:83]
	v_mfma_f32_16x16x32_bf16 v[72:75], v[184:187], v[224:227], v[72:75]
	v_mfma_f32_16x16x32_bf16 v[64:67], v[192:195], v[224:227], v[64:67]
	s_setprio 0
	s_barrier
	s_add_i32 s51, s37, s26
	v_lshl_add_u64 v[170:171], s[22:23], 0, v[134:135]
	s_mov_b32 m0, s51
	ds_read_b128 v[196:199], v160 offset:16384
	ds_read_b128 v[200:203], v160 offset:17408
	ds_read_b128 v[204:207], v160 offset:18432
	ds_read_b128 v[208:211], v160 offset:19456
	ds_read_b128 v[212:215], v160 offset:20480
	ds_read_b128 v[216:219], v160 offset:21504
	ds_read_b128 v[220:223], v160 offset:22528
	ds_read_b128 v[224:227], v160 offset:23552
	global_load_lds_dwordx4 v[170:171], off
	s_add_i32 m0, s51, 0x2000
	s_add_u32 s52, s22, 0x80000
	v_lshl_add_u64 v[228:229], s[22:23], 0, v[130:131]
	s_addc_u32 s53, s23, 0
	s_add_i32 s51, s40, s26
	global_load_lds_dwordx4 v[228:229], off
	v_lshl_add_u64 v[230:231], s[52:53], 0, v[134:135]
	s_mov_b32 m0, s51
	v_lshl_add_u64 v[232:233], s[24:25], 0, v[132:133]
	global_load_lds_dwordx4 v[230:231], off
	v_lshl_add_u64 v[230:231], s[52:53], 0, v[130:131]
	s_add_i32 m0, s51, 0x2000
	s_nop 0
	global_load_lds_dwordx4 v[230:231], off
	v_lshl_add_u64 v[230:231], s[24:25], 0, v[136:137]
	s_mov_b32 m0, s30
	s_nop 0
	global_load_lds_dwordx4 v[230:231], off
	s_mov_b32 m0, s31
	s_nop 0
	global_load_lds_dwordx4 v[232:233], off
	s_waitcnt vmcnt(8)
	s_waitcnt lgkmcnt(0)
	v_mfma_f32_16x16x32_bf16 v[60:63], v[146:149], v[196:199], v[60:63]
	v_mfma_f32_16x16x32_bf16 v[52:55], v[162:165], v[196:199], v[52:55]
	s_barrier
; #define PG8_STAGE(bufoff, gbase, voff) do { _Pragma("unroll") for (int _i = 0; _i < 2; ++_i) \
;         __builtin_amdgcn_global_load_lds((const unsigned*)((const char*)(gbase) + (voff)[_i]), (PG8_LAS unsigned*)(lds + (bufoff) + ldsw + _i * 8192), 16, 0, 0); } while (0)
; #define PG8_LDA(dst, b, h) do { _Pragma("unroll") for (int m = 0; m < 4; ++m) _Pragma("unroll") for (int k = 0; k < 2; ++k) dst[m][k] = *(const PG8_LAS bf16x8*)(lds + PG8_SA(b, h) + aoff + m * 2048 + k * 1024); } while (0)
; #define PG8_LDB(dst, b, h) do { _Pragma("unroll") for (int n = 0; n < 2; ++n) _Pragma("unroll") for (int k = 0; k < 2; ++k) dst[n][k] = *(const PG8_LAS bf16x8*)(lds + PG8_SB(b, h) + boff + n * 2048 + k * 1024); } while (0)
; #define PG8_MMA(ai, bj, At, Bt) do { __builtin_amdgcn_s_setprio(1); _Pragma("unroll") for (int m = 0; m < 4; ++m) _Pragma("unroll") for (int n = 0; n < 2; ++n) _Pragma("unroll") for (int k = 0; k < 2; ++k) \
;         acc[ai][bj][m][n] = __builtin_amdgcn_mfma_f32_16x16x32_bf16(Bt[n][k], At[m][k], acc[ai][bj][m][n], 0, 0, 0); __builtin_amdgcn_s_setprio(0); } while (0)
; #define PG8_WAIT_V(n) asm volatile("s_waitcnt vmcnt(" #n ")" ::: "memory")
; #define PG8_WAIT_L(n) asm volatile("s_waitcnt lgkmcnt(" #n ")" ::: "memory")
; #define PG8_BAR __builtin_amdgcn_s_barrier()
; #define PG8_SCHED __builtin_amdgcn_sched_barrier(0)
; template <class Epi, class Sched, bool ALIGN_EPI = false, bool SP2 = false>
; __device__ __forceinline__ void gemm_phase(PG8_LAS unsigned char* lds, const Gemm g, const Sched& S, const Epi& E) {
;     ...
;             PG8_WAIT_V(8); PG8_WAIT_L(0); PG8_BAR; PG8_MMA(1, 0, At, B0); PG8_MMA(1, 1, At, B1); PG8_BAR; PG8_SCHED;
;             PG8_LDB(B0, 1, 0); PG8_LDB(B1, 1, 1); PG8_SCHED; PG8_LDA(At, 1, 0); PG8_STAGE(PG8_SA(0, 1), a2 + hstep, voffA);
;             PG8_WAIT_V(8); PG8_WAIT_L(0); PG8_BAR; PG8_MMA(0, 0, At, B0); PG8_MMA(0, 1, At, B1); PG8_BAR; PG8_SCHED;
	s_setprio 1
	s_waitcnt lgkmcnt(0)
	v_mfma_f32_16x16x32_bf16 v[44:47], v[146:149], v[204:207], v[44:47]
	v_mfma_f32_16x16x32_bf16 v[36:39], v[162:165], v[204:207], v[36:39]
	v_mfma_f32_16x16x32_bf16 v[28:31], v[146:149], v[212:215], v[28:31]
	v_mfma_f32_16x16x32_bf16 v[20:23], v[162:165], v[212:215], v[20:23]
	v_mfma_f32_16x16x32_bf16 v[12:15], v[146:149], v[220:223], v[12:15]
	v_mfma_f32_16x16x32_bf16 v[4:7], v[162:165], v[220:223], v[4:7]
	v_mfma_f32_16x16x32_bf16 v[60:63], v[150:153], v[200:203], v[60:63]
	v_mfma_f32_16x16x32_bf16 v[52:55], v[166:169], v[200:203], v[52:55]
	v_mfma_f32_16x16x32_bf16 v[44:47], v[150:153], v[208:211], v[44:47]
	v_mfma_f32_16x16x32_bf16 v[36:39], v[166:169], v[208:211], v[36:39]
	v_mfma_f32_16x16x32_bf16 v[28:31], v[150:153], v[216:219], v[28:31]
	v_mfma_f32_16x16x32_bf16 v[20:23], v[166:169], v[216:219], v[20:23]
	v_mfma_f32_16x16x32_bf16 v[12:15], v[150:153], v[224:227], v[12:15]
	v_mfma_f32_16x16x32_bf16 v[4:7], v[166:169], v[224:227], v[4:7]
	s_setprio 0
	s_setprio 1
	v_mfma_f32_16x16x32_bf16 v[56:59], v[180:183], v[196:199], v[56:59]
	v_mfma_f32_16x16x32_bf16 v[48:51], v[188:191], v[196:199], v[48:51]
	v_mfma_f32_16x16x32_bf16 v[40:43], v[180:183], v[204:207], v[40:43]
	v_mfma_f32_16x16x32_bf16 v[32:35], v[188:191], v[204:207], v[32:35]
	v_mfma_f32_16x16x32_bf16 v[24:27], v[180:183], v[212:215], v[24:27]
	v_mfma_f32_16x16x32_bf16 v[16:19], v[188:191], v[212:215], v[16:19]
	v_mfma_f32_16x16x32_bf16 v[8:11], v[180:183], v[220:223], v[8:11]
	v_mfma_f32_16x16x32_bf16 v[0:3], v[188:191], v[220:223], v[0:3]
	v_mfma_f32_16x16x32_bf16 v[56:59], v[184:187], v[200:203], v[56:59]
	v_mfma_f32_16x16x32_bf16 v[48:51], v[192:195], v[200:203], v[48:51]
	v_mfma_f32_16x16x32_bf16 v[40:43], v[184:187], v[208:211], v[40:43]
	v_mfma_f32_16x16x32_bf16 v[32:35], v[192:195], v[208:211], v[32:35]
	v_mfma_f32_16x16x32_bf16 v[24:27], v[184:187], v[216:219], v[24:27]
	v_mfma_f32_16x16x32_bf16 v[16:19], v[192:195], v[216:219], v[16:19]
	v_mfma_f32_16x16x32_bf16 v[8:11], v[184:187], v[224:227], v[8:11]
	v_mfma_f32_16x16x32_bf16 v[0:3], v[192:195], v[224:227], v[0:3]
	s_setprio 0
	s_barrier
	s_add_i32 s51, 0, 0x18000
	v_add_u32_e32 v161, s51, v155
	s_add_i32 s52, 0, 0x1c000
	ds_read_b128 v[146:149], v161
	ds_read_b128 v[150:153], v161 offset:1024
	ds_read_b128 v[162:165], v161 offset:2048
	ds_read_b128 v[166:169], v161 offset:3072
	v_add_u32_e32 v161, s52, v155
	ds_read_b128 v[180:183], v161
	ds_read_b128 v[184:187], v161 offset:1024
	ds_read_b128 v[188:191], v161 offset:2048
	ds_read_b128 v[192:195], v161 offset:3072
	s_add_u32 s24, s24, 0x80000
	s_addc_u32 s25, s25, 0
	s_mov_b32 m0, s33
	v_lshl_add_u64 v[234:235], s[24:25], 0, v[136:137]
	ds_read_b128 v[196:199], v160 offset:32768
	ds_read_b128 v[200:203], v160 offset:33792
	ds_read_b128 v[204:207], v160 offset:34816
	ds_read_b128 v[208:211], v160 offset:35840
	ds_read_b128 v[212:215], v160 offset:36864
	ds_read_b128 v[216:219], v160 offset:37888
	ds_read_b128 v[220:223], v160 offset:38912
	ds_read_b128 v[224:227], v160 offset:39936
	global_load_lds_dwordx4 v[234:235], off
	v_lshl_add_u64 v[234:235], s[24:25], 0, v[132:133]
	s_mov_b32 m0, s34
	s_nop 0
	global_load_lds_dwordx4 v[234:235], off
	s_waitcnt vmcnt(8)
	s_waitcnt lgkmcnt(0)
	v_mfma_f32_16x16x32_bf16 v[124:127], v[146:149], v[196:199], v[124:127]
	v_mfma_f32_16x16x32_bf16 v[116:119], v[162:165], v[196:199], v[116:119]
	s_barrier
	s_setprio 1
	s_waitcnt lgkmcnt(0)
	v_mfma_f32_16x16x32_bf16 v[108:111], v[146:149], v[204:207], v[108:111]
	v_mfma_f32_16x16x32_bf16 v[100:103], v[162:165], v[204:207], v[100:103]
	v_mfma_f32_16x16x32_bf16 v[92:95], v[146:149], v[212:215], v[92:95]
	v_mfma_f32_16x16x32_bf16 v[84:87], v[162:165], v[212:215], v[84:87]
	v_mfma_f32_16x16x32_bf16 v[76:79], v[146:149], v[220:223], v[76:79]
	v_mfma_f32_16x16x32_bf16 v[68:71], v[162:165], v[220:223], v[68:71]
	v_mfma_f32_16x16x32_bf16 v[124:127], v[150:153], v[200:203], v[124:127]
	v_mfma_f32_16x16x32_bf16 v[116:119], v[166:169], v[200:203], v[116:119]
	v_mfma_f32_16x16x32_bf16 v[108:111], v[150:153], v[208:211], v[108:111]
	v_mfma_f32_16x16x32_bf16 v[100:103], v[166:169], v[208:211], v[100:103]
	v_mfma_f32_16x16x32_bf16 v[92:95], v[150:153], v[216:219], v[92:95]
	v_mfma_f32_16x16x32_bf16 v[84:87], v[166:169], v[216:219], v[84:87]
	v_mfma_f32_16x16x32_bf16 v[76:79], v[150:153], v[224:227], v[76:79]
	v_mfma_f32_16x16x32_bf16 v[68:71], v[166:169], v[224:227], v[68:71]
	s_setprio 0
	s_setprio 1
	v_mfma_f32_16x16x32_bf16 v[120:123], v[180:183], v[196:199], v[120:123]
	v_mfma_f32_16x16x32_bf16 v[112:115], v[188:191], v[196:199], v[112:115]
	v_mfma_f32_16x16x32_bf16 v[104:107], v[180:183], v[204:207], v[104:107]
	v_mfma_f32_16x16x32_bf16 v[96:99], v[188:191], v[204:207], v[96:99]
	v_mfma_f32_16x16x32_bf16 v[88:91], v[180:183], v[212:215], v[88:91]
	v_mfma_f32_16x16x32_bf16 v[80:83], v[188:191], v[212:215], v[80:83]
	v_mfma_f32_16x16x32_bf16 v[72:75], v[180:183], v[220:223], v[72:75]
	v_mfma_f32_16x16x32_bf16 v[64:67], v[188:191], v[220:223], v[64:67]
	v_mfma_f32_16x16x32_bf16 v[120:123], v[184:187], v[200:203], v[120:123]
	v_mfma_f32_16x16x32_bf16 v[112:115], v[192:195], v[200:203], v[112:115]
	v_mfma_f32_16x16x32_bf16 v[104:107], v[184:187], v[208:211], v[104:107]
	v_mfma_f32_16x16x32_bf16 v[96:99], v[192:195], v[208:211], v[96:99]
	v_mfma_f32_16x16x32_bf16 v[88:91], v[184:187], v[216:219], v[88:91]
	v_mfma_f32_16x16x32_bf16 v[80:83], v[192:195], v[216:219], v[80:83]
	v_mfma_f32_16x16x32_bf16 v[72:75], v[184:187], v[224:227], v[72:75]
	v_mfma_f32_16x16x32_bf16 v[64:67], v[192:195], v[224:227], v[64:67]
	s_setprio 0
	s_barrier
; #define PG8_STAGE(bufoff, gbase, voff) do { _Pragma("unroll") for (int _i = 0; _i < 2; ++_i) \
;         __builtin_amdgcn_global_load_lds((const unsigned*)((const char*)(gbase) + (voff)[_i]), (PG8_LAS unsigned*)(lds + (bufoff) + ldsw + _i * 8192), 16, 0, 0); } while (0)
; #define PG8_LDA(dst, b, h) do { _Pragma("unroll") for (int m = 0; m < 4; ++m) _Pragma("unroll") for (int k = 0; k < 2; ++k) dst[m][k] = *(const PG8_LAS bf16x8*)(lds + PG8_SA(b, h) + aoff + m * 2048 + k * 1024); } while (0)
; #define PG8_MMA(ai, bj, At, Bt) do { __builtin_amdgcn_s_setprio(1); _Pragma("unroll") for (int m = 0; m < 4; ++m) _Pragma("unroll") for (int n = 0; n < 2; ++n) _Pragma("unroll") for (int k = 0; k < 2; ++k) \
;         acc[ai][bj][m][n] = __builtin_amdgcn_mfma_f32_16x16x32_bf16(Bt[n][k], At[m][k], acc[ai][bj][m][n], 0, 0, 0); __builtin_amdgcn_s_setprio(0); } while (0)
; #define PG8_WAIT_V(n) asm volatile("s_waitcnt vmcnt(" #n ")" ::: "memory")
; #define PG8_WAIT_L(n) asm volatile("s_waitcnt lgkmcnt(" #n ")" ::: "memory")
; #define PG8_BAR __builtin_amdgcn_s_barrier()
; #define PG8_SCHED __builtin_amdgcn_sched_barrier(0)
; template <class Epi, class Sched, bool ALIGN_EPI = false, bool SP2 = false>
; __device__ __forceinline__ void gemm_phase(PG8_LAS unsigned char* lds, const Gemm g, const Sched& S, const Epi& E) {
;     ...
;             PG8_LDA(At, 1, 1); PG8_STAGE(PG8_SB(1, 0), b3, voffB); PG8_STAGE(PG8_SB(1, 1), b3 + hstep, voffB); PG8_STAGE(PG8_SA(1, 0), a3, voffA);
;             PG8_WAIT_V(8); PG8_WAIT_L(0); PG8_BAR; PG8_MMA(1, 0, At, B0); PG8_MMA(1, 1, At, B1); PG8_BAR; PG8_SCHED;
	s_add_i32 s24, s51, s26
	v_lshl_add_u64 v[170:171], v[170:171], 0, s[2:3]
	s_mov_b32 m0, s24
	ds_read_b128 v[196:199], v160 offset:49152
	ds_read_b128 v[200:203], v160 offset:50176
	ds_read_b128 v[204:207], v160 offset:51200
	ds_read_b128 v[208:211], v160 offset:52224
	ds_read_b128 v[212:215], v160 offset:53248
	ds_read_b128 v[216:219], v160 offset:54272
	ds_read_b128 v[220:223], v160 offset:55296
	ds_read_b128 v[224:227], v160 offset:56320
	global_load_lds_dwordx4 v[170:171], off
	s_add_i32 m0, s24, 0x2000
	s_add_u32 s22, s22, 0x80080
	v_lshl_add_u64 v[170:171], v[228:229], 0, s[2:3]
	s_addc_u32 s23, s23, 0
	s_add_i32 s24, s52, s26
	global_load_lds_dwordx4 v[170:171], off
	v_lshl_add_u64 v[170:171], s[22:23], 0, v[134:135]
	s_mov_b32 m0, s24
	s_nop 0
	global_load_lds_dwordx4 v[170:171], off
	v_lshl_add_u64 v[170:171], s[22:23], 0, v[130:131]
	s_add_i32 m0, s24, 0x2000
	s_nop 0
	global_load_lds_dwordx4 v[170:171], off
	v_lshl_add_u64 v[170:171], v[230:231], 0, s[2:3]
	s_mov_b32 m0, s35
	s_nop 0
	global_load_lds_dwordx4 v[170:171], off
	v_lshl_add_u64 v[170:171], v[232:233], 0, s[2:3]
	s_mov_b32 m0, s36
	s_nop 0
	global_load_lds_dwordx4 v[170:171], off
	s_waitcnt vmcnt(8)
	s_waitcnt lgkmcnt(0)
	v_mfma_f32_16x16x32_bf16 v[60:63], v[146:149], v[196:199], v[60:63]
	v_mfma_f32_16x16x32_bf16 v[52:55], v[162:165], v[196:199], v[52:55]
	s_barrier
	s_setprio 1
	s_waitcnt lgkmcnt(0)
	v_mfma_f32_16x16x32_bf16 v[44:47], v[146:149], v[204:207], v[44:47]
	v_mfma_f32_16x16x32_bf16 v[36:39], v[162:165], v[204:207], v[36:39]
	v_mfma_f32_16x16x32_bf16 v[28:31], v[146:149], v[212:215], v[28:31]
	v_mfma_f32_16x16x32_bf16 v[20:23], v[162:165], v[212:215], v[20:23]
	v_mfma_f32_16x16x32_bf16 v[12:15], v[146:149], v[220:223], v[12:15]
	v_mfma_f32_16x16x32_bf16 v[4:7], v[162:165], v[220:223], v[4:7]
	v_mfma_f32_16x16x32_bf16 v[60:63], v[150:153], v[200:203], v[60:63]
	v_mfma_f32_16x16x32_bf16 v[52:55], v[166:169], v[200:203], v[52:55]
	v_mfma_f32_16x16x32_bf16 v[44:47], v[150:153], v[208:211], v[44:47]
	v_mfma_f32_16x16x32_bf16 v[36:39], v[166:169], v[208:211], v[36:39]
	v_mfma_f32_16x16x32_bf16 v[28:31], v[150:153], v[216:219], v[28:31]
	v_mfma_f32_16x16x32_bf16 v[20:23], v[166:169], v[216:219], v[20:23]
	v_mfma_f32_16x16x32_bf16 v[12:15], v[150:153], v[224:227], v[12:15]
	v_mfma_f32_16x16x32_bf16 v[4:7], v[166:169], v[224:227], v[4:7]
	s_setprio 0
	s_setprio 1
	v_mfma_f32_16x16x32_bf16 v[56:59], v[180:183], v[196:199], v[56:59]
	v_mfma_f32_16x16x32_bf16 v[48:51], v[188:191], v[196:199], v[48:51]
	v_mfma_f32_16x16x32_bf16 v[40:43], v[180:183], v[204:207], v[40:43]
	v_mfma_f32_16x16x32_bf16 v[32:35], v[188:191], v[204:207], v[32:35]
	v_mfma_f32_16x16x32_bf16 v[24:27], v[180:183], v[212:215], v[24:27]
	v_mfma_f32_16x16x32_bf16 v[16:19], v[188:191], v[212:215], v[16:19]
	v_mfma_f32_16x16x32_bf16 v[8:11], v[180:183], v[220:223], v[8:11]
	v_mfma_f32_16x16x32_bf16 v[0:3], v[188:191], v[220:223], v[0:3]
	v_mfma_f32_16x16x32_bf16 v[56:59], v[184:187], v[200:203], v[56:59]
	v_mfma_f32_16x16x32_bf16 v[48:51], v[192:195], v[200:203], v[48:51]
	v_mfma_f32_16x16x32_bf16 v[40:43], v[184:187], v[208:211], v[40:43]
	v_mfma_f32_16x16x32_bf16 v[32:35], v[192:195], v[208:211], v[32:35]
	v_mfma_f32_16x16x32_bf16 v[24:27], v[184:187], v[216:219], v[24:27]
	v_mfma_f32_16x16x32_bf16 v[16:19], v[192:195], v[216:219], v[16:19]
	v_mfma_f32_16x16x32_bf16 v[8:11], v[184:187], v[224:227], v[8:11]
	v_mfma_f32_16x16x32_bf16 v[0:3], v[192:195], v[224:227], v[0:3]
	s_setprio 0
	s_barrier
	s_add_i32 s50, s50, 2
	s_add_u32 s20, s20, 0x100
	s_addc_u32 s21, s21, 0
	s_add_u32 s48, s48, 0x100
	s_addc_u32 s49, s49, 0
	s_cmp_gt_u32 s50, 29
	s_cbranch_scc0 .LBB0_837
	s_and_b64 vcc, exec, s[4:5]
	s_cbranch_vccz .LBB0_840
	s_barrier

; #define PG8_STAGE(bufoff, gbase, voff) do { _Pragma("unroll") for (int _i = 0; _i < 2; ++_i) \
;         __builtin_amdgcn_global_load_lds((const unsigned*)((const char*)(gbase) + (voff)[_i]), (PG8_LAS unsigned*)(lds + (bufoff) + ldsw + _i * 8192), 16, 0, 0); } while (0)
; #define PG8_LDA(dst, b, h) do { _Pragma("unroll") for (int m = 0; m < 4; ++m) _Pragma("unroll") for (int k = 0; k < 2; ++k) dst[m][k] = *(const PG8_LAS bf16x8*)(lds + PG8_SA(b, h) + aoff + m * 2048 + k * 1024); } while (0)
; #define PG8_LDB(dst, b, h) do { _Pragma("unroll") for (int n = 0; n < 2; ++n) _Pragma("unroll") for (int k = 0; k < 2; ++k) dst[n][k] = *(const PG8_LAS bf16x8*)(lds + PG8_SB(b, h) + boff + n * 2048 + k * 1024); } while (0)
; #define PG8_MMA(ai, bj, At, Bt) do { __builtin_amdgcn_s_setprio(1); _Pragma("unroll") for (int m = 0; m < 4; ++m) _Pragma("unroll") for (int n = 0; n < 2; ++n) _Pragma("unroll") for (int k = 0; k < 2; ++k) \
;         acc[ai][bj][m][n] = __builtin_amdgcn_mfma_f32_16x16x32_bf16(Bt[n][k], At[m][k], acc[ai][bj][m][n], 0, 0, 0); __builtin_amdgcn_s_setprio(0); } while (0)
; #define PG8_WAIT_V(n) asm volatile("s_waitcnt vmcnt(" #n ")" ::: "memory")
; #define PG8_WAIT_L(n) asm volatile("s_waitcnt lgkmcnt(" #n ")" ::: "memory")
; #define PG8_BAR __builtin_amdgcn_s_barrier()
; #define PG8_SCHED __builtin_amdgcn_sched_barrier(0)
; template <class Epi, class Sched, bool ALIGN_EPI = false, bool SP2 = false>
; __device__ __forceinline__ void gemm_phase(PG8_LAS unsigned char* lds, const Gemm g, const Sched& S, const Epi& E) {
;     ...
;             PG8_LDB(B0, 0, 0); PG8_LDB(B1, 0, 1); PG8_SCHED; PG8_LDA(At, 0, 0); PG8_STAGE(PG8_SA(1, 1), a1 + hstep, voffA);
;             PG8_WAIT_V(8); PG8_WAIT_L(0); PG8_BAR; PG8_MMA(0, 0, At, B0); PG8_MMA(0, 1, At, B1); PG8_BAR; PG8_SCHED;
;             PG8_LDA(At, 0, 1); PG8_STAGE(PG8_SB(0, 0), b2, voffB); PG8_STAGE(PG8_SB(0, 1), b2 + hstep, voffB); PG8_STAGE(PG8_SA(0, 0), a2, voffA);
;             PG8_WAIT_V(8); PG8_WAIT_L(0); PG8_BAR; PG8_MMA(1, 0, At, B0); PG8_MMA(1, 1, At, B1); PG8_BAR; PG8_SCHED;
.LBB0_1080:
	ds_read_b128 v[142:145], v151
	ds_read_b128 v[154:157], v151 offset:1024
	ds_read_b128 v[158:161], v151 offset:2048
	ds_read_b128 v[162:165], v151 offset:3072
	ds_read_b128 v[166:169], v152
	ds_read_b128 v[180:183], v152 offset:1024
	ds_read_b128 v[184:187], v152 offset:2048
	ds_read_b128 v[188:191], v152 offset:3072
	s_add_u32 s20, s18, 0x100
	s_addc_u32 s21, s19, 0
	s_cmpk_eq_i32 s49, 0x54
	s_cselect_b32 s25, s13, s21
	s_cselect_b32 s24, s12, s20
	s_cselect_b32 s23, s17, s48
	s_cselect_b32 s22, s16, s47
	v_lshl_add_u64 v[146:147], s[18:19], 0, v[134:135]
	s_add_i32 m0, s29, 0xc000
	ds_read_b128 v[192:195], v153
	ds_read_b128 v[196:199], v153 offset:1024
	ds_read_b128 v[200:203], v153 offset:2048
	ds_read_b128 v[204:207], v153 offset:3072
	ds_read_b128 v[208:211], v153 offset:4096
	ds_read_b128 v[212:215], v153 offset:5120
	ds_read_b128 v[216:219], v153 offset:6144
	ds_read_b128 v[220:223], v153 offset:7168
	global_load_lds_dwordx4 v[146:147], off
	v_lshl_add_u64 v[146:147], s[18:19], 0, v[136:137]
	s_add_i32 m0, s29, 0xe000
	s_nop 0
	global_load_lds_dwordx4 v[146:147], off
	s_waitcnt vmcnt(8)
	s_waitcnt lgkmcnt(0)
	v_mfma_f32_16x16x32_bf16 v[124:127], v[142:145], v[192:195], v[124:127]
	v_mfma_f32_16x16x32_bf16 v[120:123], v[158:161], v[192:195], v[120:123]
	s_barrier
	s_setprio 1
	s_waitcnt lgkmcnt(0)
	v_mfma_f32_16x16x32_bf16 v[108:111], v[142:145], v[200:203], v[108:111]
	v_mfma_f32_16x16x32_bf16 v[104:107], v[158:161], v[200:203], v[104:107]
	v_mfma_f32_16x16x32_bf16 v[92:95], v[142:145], v[208:211], v[92:95]
	v_mfma_f32_16x16x32_bf16 v[88:91], v[158:161], v[208:211], v[88:91]
	v_mfma_f32_16x16x32_bf16 v[76:79], v[142:145], v[216:219], v[76:79]
	v_mfma_f32_16x16x32_bf16 v[72:75], v[158:161], v[216:219], v[72:75]
	v_mfma_f32_16x16x32_bf16 v[124:127], v[154:157], v[196:199], v[124:127]
	v_mfma_f32_16x16x32_bf16 v[120:123], v[162:165], v[196:199], v[120:123]
	v_mfma_f32_16x16x32_bf16 v[108:111], v[154:157], v[204:207], v[108:111]
	v_mfma_f32_16x16x32_bf16 v[104:107], v[162:165], v[204:207], v[104:107]
	v_mfma_f32_16x16x32_bf16 v[92:95], v[154:157], v[212:215], v[92:95]
	v_mfma_f32_16x16x32_bf16 v[88:91], v[162:165], v[212:215], v[88:91]
	v_mfma_f32_16x16x32_bf16 v[76:79], v[154:157], v[220:223], v[76:79]
	v_mfma_f32_16x16x32_bf16 v[72:75], v[162:165], v[220:223], v[72:75]
	s_setprio 0
	s_setprio 1
	v_mfma_f32_16x16x32_bf16 v[116:119], v[166:169], v[192:195], v[116:119]
	v_mfma_f32_16x16x32_bf16 v[112:115], v[184:187], v[192:195], v[112:115]
	v_mfma_f32_16x16x32_bf16 v[100:103], v[166:169], v[200:203], v[100:103]
	v_mfma_f32_16x16x32_bf16 v[96:99], v[184:187], v[200:203], v[96:99]
	v_mfma_f32_16x16x32_bf16 v[84:87], v[166:169], v[208:211], v[84:87]
	v_mfma_f32_16x16x32_bf16 v[80:83], v[184:187], v[208:211], v[80:83]
	v_mfma_f32_16x16x32_bf16 v[68:71], v[166:169], v[216:219], v[68:71]
	v_mfma_f32_16x16x32_bf16 v[64:67], v[184:187], v[216:219], v[64:67]
	v_mfma_f32_16x16x32_bf16 v[116:119], v[180:183], v[196:199], v[116:119]
	v_mfma_f32_16x16x32_bf16 v[112:115], v[188:191], v[196:199], v[112:115]
	v_mfma_f32_16x16x32_bf16 v[100:103], v[180:183], v[204:207], v[100:103]
	v_mfma_f32_16x16x32_bf16 v[96:99], v[188:191], v[204:207], v[96:99]
	v_mfma_f32_16x16x32_bf16 v[84:87], v[180:183], v[212:215], v[84:87]
	v_mfma_f32_16x16x32_bf16 v[80:83], v[188:191], v[212:215], v[80:83]
	v_mfma_f32_16x16x32_bf16 v[68:71], v[180:183], v[220:223], v[68:71]
	v_mfma_f32_16x16x32_bf16 v[64:67], v[188:191], v[220:223], v[64:67]
	s_setprio 0
	s_barrier
	s_add_i32 s18, s37, s28
	v_lshl_add_u64 v[146:147], s[22:23], 0, v[130:131]
	s_mov_b32 m0, s18
	ds_read_b128 v[192:195], v153 offset:16384
	ds_read_b128 v[196:199], v153 offset:17408
	ds_read_b128 v[200:203], v153 offset:18432
	ds_read_b128 v[204:207], v153 offset:19456
	ds_read_b128 v[208:211], v153 offset:20480
	ds_read_b128 v[212:215], v153 offset:21504
	ds_read_b128 v[216:219], v153 offset:22528
	ds_read_b128 v[220:223], v153 offset:23552
	global_load_lds_dwordx4 v[146:147], off
	s_add_i32 m0, s18, 0x2000
	s_add_u32 s18, s22, 0x160000
	v_lshl_add_u64 v[170:171], s[22:23], 0, v[132:133]
	s_addc_u32 s19, s23, 0
	s_add_i32 s50, s40, s28
	global_load_lds_dwordx4 v[170:171], off
	v_lshl_add_u64 v[224:225], s[18:19], 0, v[130:131]
	s_mov_b32 m0, s50
	v_lshl_add_u64 v[226:227], s[24:25], 0, v[132:133]
	global_load_lds_dwordx4 v[224:225], off
	v_lshl_add_u64 v[224:225], s[18:19], 0, v[132:133]
	s_add_i32 m0, s50, 0x2000
	s_nop 0
	global_load_lds_dwordx4 v[224:225], off
	v_lshl_add_u64 v[224:225], s[24:25], 0, v[130:131]
	s_mov_b32 m0, s29
	s_nop 0
	global_load_lds_dwordx4 v[224:225], off
	s_mov_b32 m0, s30
	s_nop 0
	global_load_lds_dwordx4 v[226:227], off
	s_waitcnt vmcnt(8)
	s_waitcnt lgkmcnt(0)
	v_mfma_f32_16x16x32_bf16 v[60:63], v[142:145], v[192:195], v[60:63]
	v_mfma_f32_16x16x32_bf16 v[56:59], v[158:161], v[192:195], v[56:59]
	s_barrier
; #define PG8_STAGE(bufoff, gbase, voff) do { _Pragma("unroll") for (int _i = 0; _i < 2; ++_i) \
;         __builtin_amdgcn_global_load_lds((const unsigned*)((const char*)(gbase) + (voff)[_i]), (PG8_LAS unsigned*)(lds + (bufoff) + ldsw + _i * 8192), 16, 0, 0); } while (0)
; #define PG8_LDA(dst, b, h) do { _Pragma("unroll") for (int m = 0; m < 4; ++m) _Pragma("unroll") for (int k = 0; k < 2; ++k) dst[m][k] = *(const PG8_LAS bf16x8*)(lds + PG8_SA(b, h) + aoff + m * 2048 + k * 1024); } while (0)
; #define PG8_LDB(dst, b, h) do { _Pragma("unroll") for (int n = 0; n < 2; ++n) _Pragma("unroll") for (int k = 0; k < 2; ++k) dst[n][k] = *(const PG8_LAS bf16x8*)(lds + PG8_SB(b, h) + boff + n * 2048 + k * 1024); } while (0)
; #define PG8_MMA(ai, bj, At, Bt) do { __builtin_amdgcn_s_setprio(1); _Pragma("unroll") for (int m = 0; m < 4; ++m) _Pragma("unroll") for (int n = 0; n < 2; ++n) _Pragma("unroll") for (int k = 0; k < 2; ++k) \
;         acc[ai][bj][m][n] = __builtin_amdgcn_mfma_f32_16x16x32_bf16(Bt[n][k], At[m][k], acc[ai][bj][m][n], 0, 0, 0); __builtin_amdgcn_s_setprio(0); } while (0)
; #define PG8_WAIT_V(n) asm volatile("s_waitcnt vmcnt(" #n ")" ::: "memory")
; #define PG8_WAIT_L(n) asm volatile("s_waitcnt lgkmcnt(" #n ")" ::: "memory")
; #define PG8_BAR __builtin_amdgcn_s_barrier()
; #define PG8_SCHED __builtin_amdgcn_sched_barrier(0)
; template <class Epi, class Sched, bool ALIGN_EPI = false, bool SP2 = false>
; __device__ __forceinline__ void gemm_phase(PG8_LAS unsigned char* lds, const Gemm g, const Sched& S, const Epi& E) {
;     ...
;             PG8_WAIT_V(8); PG8_WAIT_L(0); PG8_BAR; PG8_MMA(1, 0, At, B0); PG8_MMA(1, 1, At, B1); PG8_BAR; PG8_SCHED;
;             PG8_LDB(B0, 1, 0); PG8_LDB(B1, 1, 1); PG8_SCHED; PG8_LDA(At, 1, 0); PG8_STAGE(PG8_SA(0, 1), a2 + hstep, voffA);
;             PG8_WAIT_V(8); PG8_WAIT_L(0); PG8_BAR; PG8_MMA(0, 0, At, B0); PG8_MMA(0, 1, At, B1); PG8_BAR; PG8_SCHED;
	s_setprio 1
	s_waitcnt lgkmcnt(0)
	v_mfma_f32_16x16x32_bf16 v[44:47], v[142:145], v[200:203], v[44:47]
	v_mfma_f32_16x16x32_bf16 v[40:43], v[158:161], v[200:203], v[40:43]
	v_mfma_f32_16x16x32_bf16 v[28:31], v[142:145], v[208:211], v[28:31]
	v_mfma_f32_16x16x32_bf16 v[24:27], v[158:161], v[208:211], v[24:27]
	v_mfma_f32_16x16x32_bf16 v[12:15], v[142:145], v[216:219], v[12:15]
	v_mfma_f32_16x16x32_bf16 v[8:11], v[158:161], v[216:219], v[8:11]
	v_mfma_f32_16x16x32_bf16 v[60:63], v[154:157], v[196:199], v[60:63]
	v_mfma_f32_16x16x32_bf16 v[56:59], v[162:165], v[196:199], v[56:59]
	v_mfma_f32_16x16x32_bf16 v[44:47], v[154:157], v[204:207], v[44:47]
	v_mfma_f32_16x16x32_bf16 v[40:43], v[162:165], v[204:207], v[40:43]
	v_mfma_f32_16x16x32_bf16 v[28:31], v[154:157], v[212:215], v[28:31]
	v_mfma_f32_16x16x32_bf16 v[24:27], v[162:165], v[212:215], v[24:27]
	v_mfma_f32_16x16x32_bf16 v[12:15], v[154:157], v[220:223], v[12:15]
	v_mfma_f32_16x16x32_bf16 v[8:11], v[162:165], v[220:223], v[8:11]
	s_setprio 0
	s_setprio 1
	v_mfma_f32_16x16x32_bf16 v[52:55], v[166:169], v[192:195], v[52:55]
	v_mfma_f32_16x16x32_bf16 v[48:51], v[184:187], v[192:195], v[48:51]
	v_mfma_f32_16x16x32_bf16 v[36:39], v[166:169], v[200:203], v[36:39]
	v_mfma_f32_16x16x32_bf16 v[32:35], v[184:187], v[200:203], v[32:35]
	v_mfma_f32_16x16x32_bf16 v[20:23], v[166:169], v[208:211], v[20:23]
	v_mfma_f32_16x16x32_bf16 v[16:19], v[184:187], v[208:211], v[16:19]
	v_mfma_f32_16x16x32_bf16 v[4:7], v[166:169], v[216:219], v[4:7]
	v_mfma_f32_16x16x32_bf16 v[0:3], v[184:187], v[216:219], v[0:3]
	v_mfma_f32_16x16x32_bf16 v[52:55], v[180:183], v[196:199], v[52:55]
	v_mfma_f32_16x16x32_bf16 v[48:51], v[188:191], v[196:199], v[48:51]
	v_mfma_f32_16x16x32_bf16 v[36:39], v[180:183], v[204:207], v[36:39]
	v_mfma_f32_16x16x32_bf16 v[32:35], v[188:191], v[204:207], v[32:35]
	v_mfma_f32_16x16x32_bf16 v[20:23], v[180:183], v[212:215], v[20:23]
	v_mfma_f32_16x16x32_bf16 v[16:19], v[188:191], v[212:215], v[16:19]
	v_mfma_f32_16x16x32_bf16 v[4:7], v[180:183], v[220:223], v[4:7]
	v_mfma_f32_16x16x32_bf16 v[0:3], v[188:191], v[220:223], v[0:3]
	s_setprio 0
	s_barrier
	s_add_i32 s50, 0, 0x18000
	s_add_i32 s51, 0, 0x1c000
	v_add_u32_e32 v162, s50, v149
	v_add_u32_e32 v179, s51, v149
	ds_read_b128 v[142:145], v162
	ds_read_b128 v[154:157], v162 offset:1024
	ds_read_b128 v[158:161], v162 offset:2048
	ds_read_b128 v[162:165], v162 offset:3072
	ds_read_b128 v[166:169], v179
	ds_read_b128 v[180:183], v179 offset:1024
	ds_read_b128 v[184:187], v179 offset:2048
	ds_read_b128 v[188:191], v179 offset:3072
	s_add_u32 s18, s24, 0x160000
	s_addc_u32 s19, s25, 0
	s_mov_b32 m0, s31
	v_lshl_add_u64 v[228:229], s[18:19], 0, v[130:131]
	ds_read_b128 v[192:195], v153 offset:32768
	ds_read_b128 v[196:199], v153 offset:33792
	ds_read_b128 v[200:203], v153 offset:34816
	ds_read_b128 v[204:207], v153 offset:35840
	ds_read_b128 v[208:211], v153 offset:36864
	ds_read_b128 v[212:215], v153 offset:37888
	ds_read_b128 v[216:219], v153 offset:38912
	ds_read_b128 v[220:223], v153 offset:39936
	global_load_lds_dwordx4 v[228:229], off
	v_lshl_add_u64 v[228:229], s[18:19], 0, v[132:133]
	s_mov_b32 m0, s33
	s_nop 0
	global_load_lds_dwordx4 v[228:229], off
	s_waitcnt vmcnt(8)
	s_waitcnt lgkmcnt(0)
	v_mfma_f32_16x16x32_bf16 v[124:127], v[142:145], v[192:195], v[124:127]
	v_mfma_f32_16x16x32_bf16 v[120:123], v[158:161], v[192:195], v[120:123]
	s_barrier
	s_setprio 1
	s_waitcnt lgkmcnt(0)
	v_mfma_f32_16x16x32_bf16 v[108:111], v[142:145], v[200:203], v[108:111]
	v_mfma_f32_16x16x32_bf16 v[104:107], v[158:161], v[200:203], v[104:107]
	v_mfma_f32_16x16x32_bf16 v[92:95], v[142:145], v[208:211], v[92:95]
	v_mfma_f32_16x16x32_bf16 v[88:91], v[158:161], v[208:211], v[88:91]
	v_mfma_f32_16x16x32_bf16 v[76:79], v[142:145], v[216:219], v[76:79]
	v_mfma_f32_16x16x32_bf16 v[72:75], v[158:161], v[216:219], v[72:75]
	v_mfma_f32_16x16x32_bf16 v[124:127], v[154:157], v[196:199], v[124:127]
	v_mfma_f32_16x16x32_bf16 v[120:123], v[162:165], v[196:199], v[120:123]
	v_mfma_f32_16x16x32_bf16 v[108:111], v[154:157], v[204:207], v[108:111]
	v_mfma_f32_16x16x32_bf16 v[104:107], v[162:165], v[204:207], v[104:107]
	v_mfma_f32_16x16x32_bf16 v[92:95], v[154:157], v[212:215], v[92:95]
	v_mfma_f32_16x16x32_bf16 v[88:91], v[162:165], v[212:215], v[88:91]
	v_mfma_f32_16x16x32_bf16 v[76:79], v[154:157], v[220:223], v[76:79]
	v_mfma_f32_16x16x32_bf16 v[72:75], v[162:165], v[220:223], v[72:75]
	s_setprio 0
	s_setprio 1
	v_mfma_f32_16x16x32_bf16 v[116:119], v[166:169], v[192:195], v[116:119]
	v_mfma_f32_16x16x32_bf16 v[112:115], v[184:187], v[192:195], v[112:115]
	v_mfma_f32_16x16x32_bf16 v[100:103], v[166:169], v[200:203], v[100:103]
	v_mfma_f32_16x16x32_bf16 v[96:99], v[184:187], v[200:203], v[96:99]
	v_mfma_f32_16x16x32_bf16 v[84:87], v[166:169], v[208:211], v[84:87]
	v_mfma_f32_16x16x32_bf16 v[80:83], v[184:187], v[208:211], v[80:83]
	v_mfma_f32_16x16x32_bf16 v[68:71], v[166:169], v[216:219], v[68:71]
	v_mfma_f32_16x16x32_bf16 v[64:67], v[184:187], v[216:219], v[64:67]
	v_mfma_f32_16x16x32_bf16 v[116:119], v[180:183], v[196:199], v[116:119]
	v_mfma_f32_16x16x32_bf16 v[112:115], v[188:191], v[196:199], v[112:115]
	v_mfma_f32_16x16x32_bf16 v[100:103], v[180:183], v[204:207], v[100:103]
	v_mfma_f32_16x16x32_bf16 v[96:99], v[188:191], v[204:207], v[96:99]
	v_mfma_f32_16x16x32_bf16 v[84:87], v[180:183], v[212:215], v[84:87]
	v_mfma_f32_16x16x32_bf16 v[80:83], v[188:191], v[212:215], v[80:83]
	v_mfma_f32_16x16x32_bf16 v[68:71], v[180:183], v[220:223], v[68:71]
	v_mfma_f32_16x16x32_bf16 v[64:67], v[188:191], v[220:223], v[64:67]
	s_setprio 0
	s_barrier
; #define PG8_STAGE(bufoff, gbase, voff) do { _Pragma("unroll") for (int _i = 0; _i < 2; ++_i) \
;         __builtin_amdgcn_global_load_lds((const unsigned*)((const char*)(gbase) + (voff)[_i]), (PG8_LAS unsigned*)(lds + (bufoff) + ldsw + _i * 8192), 16, 0, 0); } while (0)
; #define PG8_LDA(dst, b, h) do { _Pragma("unroll") for (int m = 0; m < 4; ++m) _Pragma("unroll") for (int k = 0; k < 2; ++k) dst[m][k] = *(const PG8_LAS bf16x8*)(lds + PG8_SA(b, h) + aoff + m * 2048 + k * 1024); } while (0)
; #define PG8_MMA(ai, bj, At, Bt) do { __builtin_amdgcn_s_setprio(1); _Pragma("unroll") for (int m = 0; m < 4; ++m) _Pragma("unroll") for (int n = 0; n < 2; ++n) _Pragma("unroll") for (int k = 0; k < 2; ++k) \
;         acc[ai][bj][m][n] = __builtin_amdgcn_mfma_f32_16x16x32_bf16(Bt[n][k], At[m][k], acc[ai][bj][m][n], 0, 0, 0); __builtin_amdgcn_s_setprio(0); } while (0)
; #define PG8_WAIT_V(n) asm volatile("s_waitcnt vmcnt(" #n ")" ::: "memory")
; #define PG8_WAIT_L(n) asm volatile("s_waitcnt lgkmcnt(" #n ")" ::: "memory")
; #define PG8_BAR __builtin_amdgcn_s_barrier()
; #define PG8_SCHED __builtin_amdgcn_sched_barrier(0)
; template <class Epi, class Sched, bool ALIGN_EPI = false, bool SP2 = false>
; __device__ __forceinline__ void gemm_phase(PG8_LAS unsigned char* lds, const Gemm g, const Sched& S, const Epi& E) {
;     ...
;             PG8_LDA(At, 1, 1); PG8_STAGE(PG8_SB(1, 0), b3, voffB); PG8_STAGE(PG8_SB(1, 1), b3 + hstep, voffB); PG8_STAGE(PG8_SA(1, 0), a3, voffA);
;             PG8_WAIT_V(8); PG8_WAIT_L(0); PG8_BAR; PG8_MMA(1, 0, At, B0); PG8_MMA(1, 1, At, B1); PG8_BAR; PG8_SCHED;
	s_add_i32 s18, s50, s28
	v_lshl_add_u64 v[146:147], v[146:147], 0, s[4:5]
	s_mov_b32 m0, s18
	ds_read_b128 v[192:195], v153 offset:49152
	ds_read_b128 v[196:199], v153 offset:50176
	ds_read_b128 v[200:203], v153 offset:51200
	ds_read_b128 v[204:207], v153 offset:52224
	ds_read_b128 v[208:211], v153 offset:53248
	ds_read_b128 v[212:215], v153 offset:54272
	ds_read_b128 v[216:219], v153 offset:55296
	ds_read_b128 v[220:223], v153 offset:56320
	global_load_lds_dwordx4 v[146:147], off
	s_add_i32 m0, s18, 0x2000
	s_add_u32 s18, s22, 0x160080
	v_lshl_add_u64 v[146:147], v[170:171], 0, s[4:5]
	s_addc_u32 s19, s23, 0
	s_add_i32 s22, s51, s28
	global_load_lds_dwordx4 v[146:147], off
	v_lshl_add_u64 v[146:147], s[18:19], 0, v[130:131]
	s_mov_b32 m0, s22
	s_nop 0
	global_load_lds_dwordx4 v[146:147], off
	v_lshl_add_u64 v[146:147], s[18:19], 0, v[132:133]
	s_add_i32 m0, s22, 0x2000
	s_nop 0
	global_load_lds_dwordx4 v[146:147], off
	v_lshl_add_u64 v[146:147], v[224:225], 0, s[4:5]
	s_mov_b32 m0, s35
	s_nop 0
	global_load_lds_dwordx4 v[146:147], off
	v_lshl_add_u64 v[146:147], v[226:227], 0, s[4:5]
	s_mov_b32 m0, s36
	s_nop 0
	global_load_lds_dwordx4 v[146:147], off
	s_waitcnt vmcnt(8)
	s_waitcnt lgkmcnt(0)
	v_mfma_f32_16x16x32_bf16 v[60:63], v[142:145], v[192:195], v[60:63]
	v_mfma_f32_16x16x32_bf16 v[56:59], v[158:161], v[192:195], v[56:59]
	s_barrier
	s_setprio 1
	s_waitcnt lgkmcnt(0)
	v_mfma_f32_16x16x32_bf16 v[44:47], v[142:145], v[200:203], v[44:47]
	v_mfma_f32_16x16x32_bf16 v[40:43], v[158:161], v[200:203], v[40:43]
	v_mfma_f32_16x16x32_bf16 v[28:31], v[142:145], v[208:211], v[28:31]
	v_mfma_f32_16x16x32_bf16 v[24:27], v[158:161], v[208:211], v[24:27]
	v_mfma_f32_16x16x32_bf16 v[12:15], v[142:145], v[216:219], v[12:15]
	v_mfma_f32_16x16x32_bf16 v[8:11], v[158:161], v[216:219], v[8:11]
	v_mfma_f32_16x16x32_bf16 v[60:63], v[154:157], v[196:199], v[60:63]
	v_mfma_f32_16x16x32_bf16 v[56:59], v[162:165], v[196:199], v[56:59]
	v_mfma_f32_16x16x32_bf16 v[44:47], v[154:157], v[204:207], v[44:47]
	v_mfma_f32_16x16x32_bf16 v[40:43], v[162:165], v[204:207], v[40:43]
	v_mfma_f32_16x16x32_bf16 v[28:31], v[154:157], v[212:215], v[28:31]
	v_mfma_f32_16x16x32_bf16 v[24:27], v[162:165], v[212:215], v[24:27]
	v_mfma_f32_16x16x32_bf16 v[12:15], v[154:157], v[220:223], v[12:15]
	v_mfma_f32_16x16x32_bf16 v[8:11], v[162:165], v[220:223], v[8:11]
	s_setprio 0
	s_setprio 1
	v_mfma_f32_16x16x32_bf16 v[52:55], v[166:169], v[192:195], v[52:55]
	v_mfma_f32_16x16x32_bf16 v[48:51], v[184:187], v[192:195], v[48:51]
	v_mfma_f32_16x16x32_bf16 v[36:39], v[166:169], v[200:203], v[36:39]
	v_mfma_f32_16x16x32_bf16 v[32:35], v[184:187], v[200:203], v[32:35]
	v_mfma_f32_16x16x32_bf16 v[20:23], v[166:169], v[208:211], v[20:23]
	v_mfma_f32_16x16x32_bf16 v[16:19], v[184:187], v[208:211], v[16:19]
	v_mfma_f32_16x16x32_bf16 v[4:7], v[166:169], v[216:219], v[4:7]
	v_mfma_f32_16x16x32_bf16 v[0:3], v[184:187], v[216:219], v[0:3]
	v_mfma_f32_16x16x32_bf16 v[52:55], v[180:183], v[196:199], v[52:55]
	v_mfma_f32_16x16x32_bf16 v[48:51], v[188:191], v[196:199], v[48:51]
	v_mfma_f32_16x16x32_bf16 v[36:39], v[180:183], v[204:207], v[36:39]
	v_mfma_f32_16x16x32_bf16 v[32:35], v[188:191], v[204:207], v[32:35]
	v_mfma_f32_16x16x32_bf16 v[20:23], v[180:183], v[212:215], v[20:23]
	v_mfma_f32_16x16x32_bf16 v[16:19], v[188:191], v[212:215], v[16:19]
	v_mfma_f32_16x16x32_bf16 v[4:7], v[180:183], v[220:223], v[4:7]
	v_mfma_f32_16x16x32_bf16 v[0:3], v[188:191], v[220:223], v[0:3]
	s_setprio 0
	s_barrier
	s_add_i32 s49, s49, 2
	s_add_u32 s47, s47, 0x100
	s_addc_u32 s48, s48, 0
	s_cmpk_gt_u32 s49, 0x55
	s_mov_b64 s[18:19], s[20:21]
	s_cbranch_scc0 .LBB0_1080
	s_and_b64 vcc, exec, s[6:7]
	s_cbranch_vccz .LBB0_1083
	s_barrier

; #define PG8_STAGE(bufoff, gbase, voff) do { _Pragma("unroll") for (int _i = 0; _i < 2; ++_i) \
;         __builtin_amdgcn_global_load_lds((const unsigned*)((const char*)(gbase) + (voff)[_i]), (PG8_LAS unsigned*)(lds + (bufoff) + ldsw + _i * 8192), 16, 0, 0); } while (0)
; #define PG8_LDA(dst, b, h) do { _Pragma("unroll") for (int m = 0; m < 4; ++m) _Pragma("unroll") for (int k = 0; k < 2; ++k) dst[m][k] = *(const PG8_LAS bf16x8*)(lds + PG8_SA(b, h) + aoff + m * 2048 + k * 1024); } while (0)
; #define PG8_LDB(dst, b, h) do { _Pragma("unroll") for (int n = 0; n < 2; ++n) _Pragma("unroll") for (int k = 0; k < 2; ++k) dst[n][k] = *(const PG8_LAS bf16x8*)(lds + PG8_SB(b, h) + boff + n * 2048 + k * 1024); } while (0)
; #define PG8_MMA(ai, bj, At, Bt) do { __builtin_amdgcn_s_setprio(1); _Pragma("unroll") for (int m = 0; m < 4; ++m) _Pragma("unroll") for (int n = 0; n < 2; ++n) _Pragma("unroll") for (int k = 0; k < 2; ++k) \
;         acc[ai][bj][m][n] = __builtin_amdgcn_mfma_f32_16x16x32_bf16(Bt[n][k], At[m][k], acc[ai][bj][m][n], 0, 0, 0); __builtin_amdgcn_s_setprio(0); } while (0)
; #define PG8_WAIT_V(n) asm volatile("s_waitcnt vmcnt(" #n ")" ::: "memory")
; #define PG8_WAIT_L(n) asm volatile("s_waitcnt lgkmcnt(" #n ")" ::: "memory")
; #define PG8_BAR __builtin_amdgcn_s_barrier()
; #define PG8_SCHED __builtin_amdgcn_sched_barrier(0)
; template <class Epi, class Sched, bool ALIGN_EPI = false, bool SP2 = false>
; __device__ __forceinline__ void gemm_phase(PG8_LAS unsigned char* lds, const Gemm g, const Sched& S, const Epi& E) {
;     ...
;             PG8_LDB(B0, 0, 0); PG8_LDB(B1, 0, 1); PG8_SCHED; PG8_LDA(At, 0, 0); PG8_STAGE(PG8_SA(1, 1), a1 + hstep, voffA);
;             PG8_WAIT_V(8); PG8_WAIT_L(0); PG8_BAR; PG8_MMA(0, 0, At, B0); PG8_MMA(0, 1, At, B1); PG8_BAR; PG8_SCHED;
;             PG8_LDA(At, 0, 1); PG8_STAGE(PG8_SB(0, 0), b2, voffB); PG8_STAGE(PG8_SB(0, 1), b2 + hstep, voffB); PG8_STAGE(PG8_SA(0, 0), a2, voffA);
;             PG8_WAIT_V(8); PG8_WAIT_L(0); PG8_BAR; PG8_MMA(1, 0, At, B0); PG8_MMA(1, 1, At, B1); PG8_BAR; PG8_SCHED;
.LBB0_1181:
	ds_read_b128 v[146:149], v154
	ds_read_b128 v[158:161], v154 offset:1024
	ds_read_b128 v[162:165], v154 offset:2048
	ds_read_b128 v[166:169], v154 offset:3072
	ds_read_b128 v[180:183], v155
	ds_read_b128 v[184:187], v155 offset:1024
	ds_read_b128 v[188:191], v155 offset:2048
	ds_read_b128 v[192:195], v155 offset:3072
	s_add_u32 s22, s20, 0xfff80080
	s_addc_u32 s23, s21, -1
	s_cmp_eq_u32 s48, 28
	s_cselect_b32 s25, s11, s23
	s_cselect_b32 s24, s44, s22
	s_cselect_b32 s23, s7, s47
	s_cselect_b32 s22, s45, s46
	v_lshl_add_u64 v[170:171], s[20:21], 0, v[138:139]
	s_add_i32 m0, s17, 0xc000
	ds_read_b128 v[196:199], v156
	ds_read_b128 v[200:203], v156 offset:1024
	ds_read_b128 v[204:207], v156 offset:2048
	ds_read_b128 v[208:211], v156 offset:3072
	ds_read_b128 v[212:215], v156 offset:4096
	ds_read_b128 v[216:219], v156 offset:5120
	ds_read_b128 v[220:223], v156 offset:6144
	ds_read_b128 v[224:227], v156 offset:7168
	global_load_lds_dwordx4 v[170:171], off
	v_lshl_add_u64 v[170:171], s[20:21], 0, v[140:141]
	s_add_i32 m0, s17, 0xe000
	s_nop 0
	global_load_lds_dwordx4 v[170:171], off
	s_waitcnt vmcnt(8)
	s_waitcnt lgkmcnt(0)
	v_mfma_f32_16x16x32_bf16 v[124:127], v[146:149], v[196:199], v[124:127]
	v_mfma_f32_16x16x32_bf16 v[120:123], v[162:165], v[196:199], v[120:123]
	s_barrier
	s_setprio 1
	s_waitcnt lgkmcnt(0)
	v_mfma_f32_16x16x32_bf16 v[112:115], v[146:149], v[204:207], v[112:115]
	v_mfma_f32_16x16x32_bf16 v[104:107], v[162:165], v[204:207], v[104:107]
	v_mfma_f32_16x16x32_bf16 v[96:99], v[146:149], v[212:215], v[96:99]
	v_mfma_f32_16x16x32_bf16 v[88:91], v[162:165], v[212:215], v[88:91]
	v_mfma_f32_16x16x32_bf16 v[80:83], v[146:149], v[220:223], v[80:83]
	v_mfma_f32_16x16x32_bf16 v[72:75], v[162:165], v[220:223], v[72:75]
	v_mfma_f32_16x16x32_bf16 v[124:127], v[158:161], v[200:203], v[124:127]
	v_mfma_f32_16x16x32_bf16 v[120:123], v[166:169], v[200:203], v[120:123]
	v_mfma_f32_16x16x32_bf16 v[112:115], v[158:161], v[208:211], v[112:115]
	v_mfma_f32_16x16x32_bf16 v[104:107], v[166:169], v[208:211], v[104:107]
	v_mfma_f32_16x16x32_bf16 v[96:99], v[158:161], v[216:219], v[96:99]
	v_mfma_f32_16x16x32_bf16 v[88:91], v[166:169], v[216:219], v[88:91]
	v_mfma_f32_16x16x32_bf16 v[80:83], v[158:161], v[224:227], v[80:83]
	v_mfma_f32_16x16x32_bf16 v[72:75], v[166:169], v[224:227], v[72:75]
	s_setprio 0
	s_setprio 1
	v_mfma_f32_16x16x32_bf16 v[116:119], v[180:183], v[196:199], v[116:119]
	v_mfma_f32_16x16x32_bf16 v[108:111], v[188:191], v[196:199], v[108:111]
	v_mfma_f32_16x16x32_bf16 v[100:103], v[180:183], v[204:207], v[100:103]
	v_mfma_f32_16x16x32_bf16 v[92:95], v[188:191], v[204:207], v[92:95]
	v_mfma_f32_16x16x32_bf16 v[84:87], v[180:183], v[212:215], v[84:87]
	v_mfma_f32_16x16x32_bf16 v[76:79], v[188:191], v[212:215], v[76:79]
	v_mfma_f32_16x16x32_bf16 v[68:71], v[180:183], v[220:223], v[68:71]
	v_mfma_f32_16x16x32_bf16 v[64:67], v[188:191], v[220:223], v[64:67]
	v_mfma_f32_16x16x32_bf16 v[116:119], v[184:187], v[200:203], v[116:119]
	v_mfma_f32_16x16x32_bf16 v[108:111], v[192:195], v[200:203], v[108:111]
	v_mfma_f32_16x16x32_bf16 v[100:103], v[184:187], v[208:211], v[100:103]
	v_mfma_f32_16x16x32_bf16 v[92:95], v[192:195], v[208:211], v[92:95]
	v_mfma_f32_16x16x32_bf16 v[84:87], v[184:187], v[216:219], v[84:87]
	v_mfma_f32_16x16x32_bf16 v[76:79], v[192:195], v[216:219], v[76:79]
	v_mfma_f32_16x16x32_bf16 v[68:71], v[184:187], v[224:227], v[68:71]
	v_mfma_f32_16x16x32_bf16 v[64:67], v[192:195], v[224:227], v[64:67]
	s_setprio 0
	s_barrier
	s_add_i32 s49, s35, s28
	v_lshl_add_u64 v[170:171], s[22:23], 0, v[132:133]
	s_mov_b32 m0, s49
	ds_read_b128 v[196:199], v156 offset:16384
	ds_read_b128 v[200:203], v156 offset:17408
	ds_read_b128 v[204:207], v156 offset:18432
	ds_read_b128 v[208:211], v156 offset:19456
	ds_read_b128 v[212:215], v156 offset:20480
	ds_read_b128 v[216:219], v156 offset:21504
	ds_read_b128 v[220:223], v156 offset:22528
	ds_read_b128 v[224:227], v156 offset:23552
	global_load_lds_dwordx4 v[170:171], off
	s_add_i32 m0, s49, 0x2000
	s_add_u32 s50, s22, 0x80000
	v_lshl_add_u64 v[228:229], s[22:23], 0, v[136:137]
	s_addc_u32 s51, s23, 0
	s_add_i32 s49, s36, s28
	global_load_lds_dwordx4 v[228:229], off
	v_lshl_add_u64 v[230:231], s[50:51], 0, v[132:133]
	s_mov_b32 m0, s49
	v_lshl_add_u64 v[232:233], s[24:25], 0, v[134:135]
	global_load_lds_dwordx4 v[230:231], off
	v_lshl_add_u64 v[230:231], s[50:51], 0, v[136:137]
	s_add_i32 m0, s49, 0x2000
	s_nop 0
	global_load_lds_dwordx4 v[230:231], off
	v_lshl_add_u64 v[230:231], s[24:25], 0, v[130:131]
	s_mov_b32 m0, s17
	s_nop 0
	global_load_lds_dwordx4 v[230:231], off
	s_mov_b32 m0, s29
	s_nop 0
	global_load_lds_dwordx4 v[232:233], off
	s_waitcnt vmcnt(8)
	s_waitcnt lgkmcnt(0)
	v_mfma_f32_16x16x32_bf16 v[60:63], v[146:149], v[196:199], v[60:63]
	v_mfma_f32_16x16x32_bf16 v[56:59], v[162:165], v[196:199], v[56:59]
	s_barrier
; #define PG8_STAGE(bufoff, gbase, voff) do { _Pragma("unroll") for (int _i = 0; _i < 2; ++_i) \
;         __builtin_amdgcn_global_load_lds((const unsigned*)((const char*)(gbase) + (voff)[_i]), (PG8_LAS unsigned*)(lds + (bufoff) + ldsw + _i * 8192), 16, 0, 0); } while (0)
; #define PG8_LDA(dst, b, h) do { _Pragma("unroll") for (int m = 0; m < 4; ++m) _Pragma("unroll") for (int k = 0; k < 2; ++k) dst[m][k] = *(const PG8_LAS bf16x8*)(lds + PG8_SA(b, h) + aoff + m * 2048 + k * 1024); } while (0)
; #define PG8_LDB(dst, b, h) do { _Pragma("unroll") for (int n = 0; n < 2; ++n) _Pragma("unroll") for (int k = 0; k < 2; ++k) dst[n][k] = *(const PG8_LAS bf16x8*)(lds + PG8_SB(b, h) + boff + n * 2048 + k * 1024); } while (0)
; #define PG8_MMA(ai, bj, At, Bt) do { __builtin_amdgcn_s_setprio(1); _Pragma("unroll") for (int m = 0; m < 4; ++m) _Pragma("unroll") for (int n = 0; n < 2; ++n) _Pragma("unroll") for (int k = 0; k < 2; ++k) \
;         acc[ai][bj][m][n] = __builtin_amdgcn_mfma_f32_16x16x32_bf16(Bt[n][k], At[m][k], acc[ai][bj][m][n], 0, 0, 0); __builtin_amdgcn_s_setprio(0); } while (0)
; #define PG8_WAIT_V(n) asm volatile("s_waitcnt vmcnt(" #n ")" ::: "memory")
; #define PG8_WAIT_L(n) asm volatile("s_waitcnt lgkmcnt(" #n ")" ::: "memory")
; #define PG8_BAR __builtin_amdgcn_s_barrier()
; #define PG8_SCHED __builtin_amdgcn_sched_barrier(0)
; template <class Epi, class Sched, bool ALIGN_EPI = false, bool SP2 = false>
; __device__ __forceinline__ void gemm_phase(PG8_LAS unsigned char* lds, const Gemm g, const Sched& S, const Epi& E) {
;     ...
;             PG8_WAIT_V(8); PG8_WAIT_L(0); PG8_BAR; PG8_MMA(1, 0, At, B0); PG8_MMA(1, 1, At, B1); PG8_BAR; PG8_SCHED;
;             PG8_LDB(B0, 1, 0); PG8_LDB(B1, 1, 1); PG8_SCHED; PG8_LDA(At, 1, 0); PG8_STAGE(PG8_SA(0, 1), a2 + hstep, voffA);
;             PG8_WAIT_V(8); PG8_WAIT_L(0); PG8_BAR; PG8_MMA(0, 0, At, B0); PG8_MMA(0, 1, At, B1); PG8_BAR; PG8_SCHED;
	s_setprio 1
	s_waitcnt lgkmcnt(0)
	v_mfma_f32_16x16x32_bf16 v[52:55], v[146:149], v[204:207], v[52:55]
	v_mfma_f32_16x16x32_bf16 v[44:47], v[162:165], v[204:207], v[44:47]
	v_mfma_f32_16x16x32_bf16 v[36:39], v[146:149], v[212:215], v[36:39]
	v_mfma_f32_16x16x32_bf16 v[28:31], v[162:165], v[212:215], v[28:31]
	v_mfma_f32_16x16x32_bf16 v[20:23], v[146:149], v[220:223], v[20:23]
	v_mfma_f32_16x16x32_bf16 v[12:15], v[162:165], v[220:223], v[12:15]
	v_mfma_f32_16x16x32_bf16 v[60:63], v[158:161], v[200:203], v[60:63]
	v_mfma_f32_16x16x32_bf16 v[56:59], v[166:169], v[200:203], v[56:59]
	v_mfma_f32_16x16x32_bf16 v[52:55], v[158:161], v[208:211], v[52:55]
	v_mfma_f32_16x16x32_bf16 v[44:47], v[166:169], v[208:211], v[44:47]
	v_mfma_f32_16x16x32_bf16 v[36:39], v[158:161], v[216:219], v[36:39]
	v_mfma_f32_16x16x32_bf16 v[28:31], v[166:169], v[216:219], v[28:31]
	v_mfma_f32_16x16x32_bf16 v[20:23], v[158:161], v[224:227], v[20:23]
	v_mfma_f32_16x16x32_bf16 v[12:15], v[166:169], v[224:227], v[12:15]
	s_setprio 0
	s_setprio 1
	v_mfma_f32_16x16x32_bf16 v[48:51], v[180:183], v[196:199], v[48:51]
	v_mfma_f32_16x16x32_bf16 v[40:43], v[188:191], v[196:199], v[40:43]
	v_mfma_f32_16x16x32_bf16 v[32:35], v[180:183], v[204:207], v[32:35]
	v_mfma_f32_16x16x32_bf16 v[24:27], v[188:191], v[204:207], v[24:27]
	v_mfma_f32_16x16x32_bf16 v[16:19], v[180:183], v[212:215], v[16:19]
	v_mfma_f32_16x16x32_bf16 v[8:11], v[188:191], v[212:215], v[8:11]
	v_mfma_f32_16x16x32_bf16 v[4:7], v[180:183], v[220:223], v[4:7]
	v_mfma_f32_16x16x32_bf16 v[0:3], v[188:191], v[220:223], v[0:3]
	v_mfma_f32_16x16x32_bf16 v[48:51], v[184:187], v[200:203], v[48:51]
	v_mfma_f32_16x16x32_bf16 v[40:43], v[192:195], v[200:203], v[40:43]
	v_mfma_f32_16x16x32_bf16 v[32:35], v[184:187], v[208:211], v[32:35]
	v_mfma_f32_16x16x32_bf16 v[24:27], v[192:195], v[208:211], v[24:27]
	v_mfma_f32_16x16x32_bf16 v[16:19], v[184:187], v[216:219], v[16:19]
	v_mfma_f32_16x16x32_bf16 v[8:11], v[192:195], v[216:219], v[8:11]
	v_mfma_f32_16x16x32_bf16 v[4:7], v[184:187], v[224:227], v[4:7]
	v_mfma_f32_16x16x32_bf16 v[0:3], v[192:195], v[224:227], v[0:3]
	s_setprio 0
	s_barrier
	s_add_i32 s49, 0, 0x18000
	v_add_u32_e32 v157, s49, v151
	s_add_i32 s50, 0, 0x1c000
	ds_read_b128 v[146:149], v157
	ds_read_b128 v[158:161], v157 offset:1024
	ds_read_b128 v[162:165], v157 offset:2048
	ds_read_b128 v[166:169], v157 offset:3072
	v_add_u32_e32 v157, s50, v151
	ds_read_b128 v[180:183], v157
	ds_read_b128 v[184:187], v157 offset:1024
	ds_read_b128 v[188:191], v157 offset:2048
	ds_read_b128 v[192:195], v157 offset:3072
	s_add_u32 s24, s24, 0x80000
	s_addc_u32 s25, s25, 0
	s_mov_b32 m0, s30
	v_lshl_add_u64 v[234:235], s[24:25], 0, v[130:131]
	ds_read_b128 v[196:199], v156 offset:32768
	ds_read_b128 v[200:203], v156 offset:33792
	ds_read_b128 v[204:207], v156 offset:34816
	ds_read_b128 v[208:211], v156 offset:35840
	ds_read_b128 v[212:215], v156 offset:36864
	ds_read_b128 v[216:219], v156 offset:37888
	ds_read_b128 v[220:223], v156 offset:38912
	ds_read_b128 v[224:227], v156 offset:39936
	global_load_lds_dwordx4 v[234:235], off
	v_lshl_add_u64 v[234:235], s[24:25], 0, v[134:135]
	s_mov_b32 m0, s31
	s_nop 0
	global_load_lds_dwordx4 v[234:235], off
	s_waitcnt vmcnt(8)
	s_waitcnt lgkmcnt(0)
	v_mfma_f32_16x16x32_bf16 v[124:127], v[146:149], v[196:199], v[124:127]
	v_mfma_f32_16x16x32_bf16 v[120:123], v[162:165], v[196:199], v[120:123]
	s_barrier
	s_setprio 1
	s_waitcnt lgkmcnt(0)
	v_mfma_f32_16x16x32_bf16 v[112:115], v[146:149], v[204:207], v[112:115]
	v_mfma_f32_16x16x32_bf16 v[104:107], v[162:165], v[204:207], v[104:107]
	v_mfma_f32_16x16x32_bf16 v[96:99], v[146:149], v[212:215], v[96:99]
	v_mfma_f32_16x16x32_bf16 v[88:91], v[162:165], v[212:215], v[88:91]
	v_mfma_f32_16x16x32_bf16 v[80:83], v[146:149], v[220:223], v[80:83]
	v_mfma_f32_16x16x32_bf16 v[72:75], v[162:165], v[220:223], v[72:75]
	v_mfma_f32_16x16x32_bf16 v[124:127], v[158:161], v[200:203], v[124:127]
	v_mfma_f32_16x16x32_bf16 v[120:123], v[166:169], v[200:203], v[120:123]
	v_mfma_f32_16x16x32_bf16 v[112:115], v[158:161], v[208:211], v[112:115]
	v_mfma_f32_16x16x32_bf16 v[104:107], v[166:169], v[208:211], v[104:107]
	v_mfma_f32_16x16x32_bf16 v[96:99], v[158:161], v[216:219], v[96:99]
	v_mfma_f32_16x16x32_bf16 v[88:91], v[166:169], v[216:219], v[88:91]
	v_mfma_f32_16x16x32_bf16 v[80:83], v[158:161], v[224:227], v[80:83]
	v_mfma_f32_16x16x32_bf16 v[72:75], v[166:169], v[224:227], v[72:75]
	s_setprio 0
	s_setprio 1
	v_mfma_f32_16x16x32_bf16 v[116:119], v[180:183], v[196:199], v[116:119]
	v_mfma_f32_16x16x32_bf16 v[108:111], v[188:191], v[196:199], v[108:111]
	v_mfma_f32_16x16x32_bf16 v[100:103], v[180:183], v[204:207], v[100:103]
	v_mfma_f32_16x16x32_bf16 v[92:95], v[188:191], v[204:207], v[92:95]
	v_mfma_f32_16x16x32_bf16 v[84:87], v[180:183], v[212:215], v[84:87]
	v_mfma_f32_16x16x32_bf16 v[76:79], v[188:191], v[212:215], v[76:79]
	v_mfma_f32_16x16x32_bf16 v[68:71], v[180:183], v[220:223], v[68:71]
	v_mfma_f32_16x16x32_bf16 v[64:67], v[188:191], v[220:223], v[64:67]
	v_mfma_f32_16x16x32_bf16 v[116:119], v[184:187], v[200:203], v[116:119]
	v_mfma_f32_16x16x32_bf16 v[108:111], v[192:195], v[200:203], v[108:111]
	v_mfma_f32_16x16x32_bf16 v[100:103], v[184:187], v[208:211], v[100:103]
	v_mfma_f32_16x16x32_bf16 v[92:95], v[192:195], v[208:211], v[92:95]
	v_mfma_f32_16x16x32_bf16 v[84:87], v[184:187], v[216:219], v[84:87]
	v_mfma_f32_16x16x32_bf16 v[76:79], v[192:195], v[216:219], v[76:79]
	v_mfma_f32_16x16x32_bf16 v[68:71], v[184:187], v[224:227], v[68:71]
	v_mfma_f32_16x16x32_bf16 v[64:67], v[192:195], v[224:227], v[64:67]
	s_setprio 0
	s_barrier
; #define PG8_STAGE(bufoff, gbase, voff) do { _Pragma("unroll") for (int _i = 0; _i < 2; ++_i) \
;         __builtin_amdgcn_global_load_lds((const unsigned*)((const char*)(gbase) + (voff)[_i]), (PG8_LAS unsigned*)(lds + (bufoff) + ldsw + _i * 8192), 16, 0, 0); } while (0)
; #define PG8_LDA(dst, b, h) do { _Pragma("unroll") for (int m = 0; m < 4; ++m) _Pragma("unroll") for (int k = 0; k < 2; ++k) dst[m][k] = *(const PG8_LAS bf16x8*)(lds + PG8_SA(b, h) + aoff + m * 2048 + k * 1024); } while (0)
; #define PG8_MMA(ai, bj, At, Bt) do { __builtin_amdgcn_s_setprio(1); _Pragma("unroll") for (int m = 0; m < 4; ++m) _Pragma("unroll") for (int n = 0; n < 2; ++n) _Pragma("unroll") for (int k = 0; k < 2; ++k) \
;         acc[ai][bj][m][n] = __builtin_amdgcn_mfma_f32_16x16x32_bf16(Bt[n][k], At[m][k], acc[ai][bj][m][n], 0, 0, 0); __builtin_amdgcn_s_setprio(0); } while (0)
; #define PG8_WAIT_V(n) asm volatile("s_waitcnt vmcnt(" #n ")" ::: "memory")
; #define PG8_WAIT_L(n) asm volatile("s_waitcnt lgkmcnt(" #n ")" ::: "memory")
; #define PG8_BAR __builtin_amdgcn_s_barrier()
; #define PG8_SCHED __builtin_amdgcn_sched_barrier(0)
; template <class Epi, class Sched, bool ALIGN_EPI = false, bool SP2 = false>
; __device__ __forceinline__ void gemm_phase(PG8_LAS unsigned char* lds, const Gemm g, const Sched& S, const Epi& E) {
;     ...
;             PG8_LDA(At, 1, 1); PG8_STAGE(PG8_SB(1, 0), b3, voffB); PG8_STAGE(PG8_SB(1, 1), b3 + hstep, voffB); PG8_STAGE(PG8_SA(1, 0), a3, voffA);
;             PG8_WAIT_V(8); PG8_WAIT_L(0); PG8_BAR; PG8_MMA(1, 0, At, B0); PG8_MMA(1, 1, At, B1); PG8_BAR; PG8_SCHED;
	s_add_i32 s24, s49, s28
	v_lshl_add_u64 v[170:171], v[170:171], 0, s[2:3]
	s_mov_b32 m0, s24
	ds_read_b128 v[196:199], v156 offset:49152
	ds_read_b128 v[200:203], v156 offset:50176
	ds_read_b128 v[204:207], v156 offset:51200
	ds_read_b128 v[208:211], v156 offset:52224
	ds_read_b128 v[212:215], v156 offset:53248
	ds_read_b128 v[216:219], v156 offset:54272
	ds_read_b128 v[220:223], v156 offset:55296
	ds_read_b128 v[224:227], v156 offset:56320
	global_load_lds_dwordx4 v[170:171], off
	s_add_i32 m0, s24, 0x2000
	s_add_u32 s22, s22, 0x80080
	v_lshl_add_u64 v[170:171], v[228:229], 0, s[2:3]
	s_addc_u32 s23, s23, 0
	s_add_i32 s24, s50, s28
	global_load_lds_dwordx4 v[170:171], off
	v_lshl_add_u64 v[170:171], s[22:23], 0, v[132:133]
	s_mov_b32 m0, s24
	s_nop 0
	global_load_lds_dwordx4 v[170:171], off
	v_lshl_add_u64 v[170:171], s[22:23], 0, v[136:137]
	s_add_i32 m0, s24, 0x2000
	s_nop 0
	global_load_lds_dwordx4 v[170:171], off
	v_lshl_add_u64 v[170:171], v[230:231], 0, s[2:3]
	s_mov_b32 m0, s33
	s_nop 0
	global_load_lds_dwordx4 v[170:171], off
	v_lshl_add_u64 v[170:171], v[232:233], 0, s[2:3]
	s_mov_b32 m0, s34
	s_nop 0
	global_load_lds_dwordx4 v[170:171], off
	s_waitcnt vmcnt(8)
	s_waitcnt lgkmcnt(0)
	v_mfma_f32_16x16x32_bf16 v[60:63], v[146:149], v[196:199], v[60:63]
	v_mfma_f32_16x16x32_bf16 v[56:59], v[162:165], v[196:199], v[56:59]
	s_barrier
	s_setprio 1
	s_waitcnt lgkmcnt(0)
	v_mfma_f32_16x16x32_bf16 v[52:55], v[146:149], v[204:207], v[52:55]
	v_mfma_f32_16x16x32_bf16 v[44:47], v[162:165], v[204:207], v[44:47]
	v_mfma_f32_16x16x32_bf16 v[36:39], v[146:149], v[212:215], v[36:39]
	v_mfma_f32_16x16x32_bf16 v[28:31], v[162:165], v[212:215], v[28:31]
	v_mfma_f32_16x16x32_bf16 v[20:23], v[146:149], v[220:223], v[20:23]
	v_mfma_f32_16x16x32_bf16 v[12:15], v[162:165], v[220:223], v[12:15]
	v_mfma_f32_16x16x32_bf16 v[60:63], v[158:161], v[200:203], v[60:63]
	v_mfma_f32_16x16x32_bf16 v[56:59], v[166:169], v[200:203], v[56:59]
	v_mfma_f32_16x16x32_bf16 v[52:55], v[158:161], v[208:211], v[52:55]
	v_mfma_f32_16x16x32_bf16 v[44:47], v[166:169], v[208:211], v[44:47]
	v_mfma_f32_16x16x32_bf16 v[36:39], v[158:161], v[216:219], v[36:39]
	v_mfma_f32_16x16x32_bf16 v[28:31], v[166:169], v[216:219], v[28:31]
	v_mfma_f32_16x16x32_bf16 v[20:23], v[158:161], v[224:227], v[20:23]
	v_mfma_f32_16x16x32_bf16 v[12:15], v[166:169], v[224:227], v[12:15]
	s_setprio 0
	s_setprio 1
	v_mfma_f32_16x16x32_bf16 v[48:51], v[180:183], v[196:199], v[48:51]
	v_mfma_f32_16x16x32_bf16 v[40:43], v[188:191], v[196:199], v[40:43]
	v_mfma_f32_16x16x32_bf16 v[32:35], v[180:183], v[204:207], v[32:35]
	v_mfma_f32_16x16x32_bf16 v[24:27], v[188:191], v[204:207], v[24:27]
	v_mfma_f32_16x16x32_bf16 v[16:19], v[180:183], v[212:215], v[16:19]
	v_mfma_f32_16x16x32_bf16 v[8:11], v[188:191], v[212:215], v[8:11]
	v_mfma_f32_16x16x32_bf16 v[4:7], v[180:183], v[220:223], v[4:7]
	v_mfma_f32_16x16x32_bf16 v[0:3], v[188:191], v[220:223], v[0:3]
	v_mfma_f32_16x16x32_bf16 v[48:51], v[184:187], v[200:203], v[48:51]
	v_mfma_f32_16x16x32_bf16 v[40:43], v[192:195], v[200:203], v[40:43]
	v_mfma_f32_16x16x32_bf16 v[32:35], v[184:187], v[208:211], v[32:35]
	v_mfma_f32_16x16x32_bf16 v[24:27], v[192:195], v[208:211], v[24:27]
	v_mfma_f32_16x16x32_bf16 v[16:19], v[184:187], v[216:219], v[16:19]
	v_mfma_f32_16x16x32_bf16 v[8:11], v[192:195], v[216:219], v[8:11]
	v_mfma_f32_16x16x32_bf16 v[4:7], v[184:187], v[224:227], v[4:7]
	v_mfma_f32_16x16x32_bf16 v[0:3], v[192:195], v[224:227], v[0:3]
	s_setprio 0
	s_barrier
	s_add_i32 s48, s48, 2
	s_add_u32 s20, s20, 0x100
	s_addc_u32 s21, s21, 0
	s_add_u32 s46, s46, 0x100
	s_addc_u32 s47, s47, 0
	s_cmp_gt_u32 s48, 29
	s_cbranch_scc0 .LBB0_1181
	s_and_b64 vcc, exec, s[4:5]
	s_cbranch_vccz .LBB0_1184
	s_barrier

; #define PG8_STAGE(bufoff, gbase, voff) do { _Pragma("unroll") for (int _i = 0; _i < 2; ++_i) \
;         __builtin_amdgcn_global_load_lds((const unsigned*)((const char*)(gbase) + (voff)[_i]), (PG8_LAS unsigned*)(lds + (bufoff) + ldsw + _i * 8192), 16, 0, 0); } while (0)
; #define PG8_LDA(dst, b, h) do { _Pragma("unroll") for (int m = 0; m < 4; ++m) _Pragma("unroll") for (int k = 0; k < 2; ++k) dst[m][k] = *(const PG8_LAS bf16x8*)(lds + PG8_SA(b, h) + aoff + m * 2048 + k * 1024); } while (0)
; #define PG8_LDB(dst, b, h) do { _Pragma("unroll") for (int n = 0; n < 2; ++n) _Pragma("unroll") for (int k = 0; k < 2; ++k) dst[n][k] = *(const PG8_LAS bf16x8*)(lds + PG8_SB(b, h) + boff + n * 2048 + k * 1024); } while (0)
; #define PG8_MMA(ai, bj, At, Bt) do { __builtin_amdgcn_s_setprio(1); _Pragma("unroll") for (int m = 0; m < 4; ++m) _Pragma("unroll") for (int n = 0; n < 2; ++n) _Pragma("unroll") for (int k = 0; k < 2; ++k) \
;         acc[ai][bj][m][n] = __builtin_amdgcn_mfma_f32_16x16x32_bf16(Bt[n][k], At[m][k], acc[ai][bj][m][n], 0, 0, 0); __builtin_amdgcn_s_setprio(0); } while (0)
; #define PG8_WAIT_V(n) asm volatile("s_waitcnt vmcnt(" #n ")" ::: "memory")
; #define PG8_WAIT_L(n) asm volatile("s_waitcnt lgkmcnt(" #n ")" ::: "memory")
; #define PG8_BAR __builtin_amdgcn_s_barrier()
; #define PG8_SCHED __builtin_amdgcn_sched_barrier(0)
; template <class Epi, class Sched, bool ALIGN_EPI = false, bool SP2 = false>
; __device__ __forceinline__ void gemm_phase(PG8_LAS unsigned char* lds, const Gemm g, const Sched& S, const Epi& E) {
;     ...
;             PG8_LDB(B0, 0, 0); PG8_LDB(B1, 0, 1); PG8_SCHED; PG8_LDA(At, 0, 0); PG8_STAGE(PG8_SA(1, 1), a1 + hstep, voffA);
;             PG8_WAIT_V(8); PG8_WAIT_L(0); PG8_BAR; PG8_MMA(0, 0, At, B0); PG8_MMA(0, 1, At, B1); PG8_BAR; PG8_SCHED;
;             PG8_LDA(At, 0, 1); PG8_STAGE(PG8_SB(0, 0), b2, voffB); PG8_STAGE(PG8_SB(0, 1), b2 + hstep, voffB); PG8_STAGE(PG8_SA(0, 0), a2, voffA);
;             PG8_WAIT_V(8); PG8_WAIT_L(0); PG8_BAR; PG8_MMA(1, 0, At, B0); PG8_MMA(1, 1, At, B1); PG8_BAR; PG8_SCHED;
.LBB0_1457:
	ds_read_b128 v[142:145], v151
	ds_read_b128 v[154:157], v151 offset:1024
	ds_read_b128 v[158:161], v151 offset:2048
	ds_read_b128 v[162:165], v151 offset:3072
	ds_read_b128 v[166:169], v152
	ds_read_b128 v[178:181], v152 offset:1024
	ds_read_b128 v[182:185], v152 offset:2048
	ds_read_b128 v[186:189], v152 offset:3072
	s_add_u32 s24, s22, 0x100
	s_addc_u32 s25, s23, 0
	s_cmp_eq_u32 s47, 28
	s_cselect_b32 s29, s15, s25
	s_cselect_b32 s28, s21, s24
	s_cselect_b32 s27, s13, s46
	s_cselect_b32 s26, s44, s45
	v_lshl_add_u64 v[146:147], s[22:23], 0, v[134:135]
	s_add_i32 m0, s34, 0xc000
	ds_read_b128 v[190:193], v153
	ds_read_b128 v[194:197], v153 offset:1024
	ds_read_b128 v[198:201], v153 offset:2048
	ds_read_b128 v[202:205], v153 offset:3072
	ds_read_b128 v[206:209], v153 offset:4096
	ds_read_b128 v[210:213], v153 offset:5120
	ds_read_b128 v[214:217], v153 offset:6144
	ds_read_b128 v[218:221], v153 offset:7168
	global_load_lds_dwordx4 v[146:147], off
	v_lshl_add_u64 v[146:147], s[22:23], 0, v[136:137]
	s_add_i32 m0, s34, 0xe000
	s_nop 0
	global_load_lds_dwordx4 v[146:147], off
	s_waitcnt vmcnt(8)
	s_waitcnt lgkmcnt(0)
	v_mfma_f32_16x16x32_bf16 v[124:127], v[142:145], v[190:193], v[124:127]
	v_mfma_f32_16x16x32_bf16 v[120:123], v[158:161], v[190:193], v[120:123]
	s_barrier
	s_setprio 1
	s_waitcnt lgkmcnt(0)
	v_mfma_f32_16x16x32_bf16 v[108:111], v[142:145], v[198:201], v[108:111]
	v_mfma_f32_16x16x32_bf16 v[104:107], v[158:161], v[198:201], v[104:107]
	v_mfma_f32_16x16x32_bf16 v[92:95], v[142:145], v[206:209], v[92:95]
	v_mfma_f32_16x16x32_bf16 v[88:91], v[158:161], v[206:209], v[88:91]
	v_mfma_f32_16x16x32_bf16 v[76:79], v[142:145], v[214:217], v[76:79]
	v_mfma_f32_16x16x32_bf16 v[72:75], v[158:161], v[214:217], v[72:75]
	v_mfma_f32_16x16x32_bf16 v[124:127], v[154:157], v[194:197], v[124:127]
	v_mfma_f32_16x16x32_bf16 v[120:123], v[162:165], v[194:197], v[120:123]
	v_mfma_f32_16x16x32_bf16 v[108:111], v[154:157], v[202:205], v[108:111]
	v_mfma_f32_16x16x32_bf16 v[104:107], v[162:165], v[202:205], v[104:107]
	v_mfma_f32_16x16x32_bf16 v[92:95], v[154:157], v[210:213], v[92:95]
	v_mfma_f32_16x16x32_bf16 v[88:91], v[162:165], v[210:213], v[88:91]
	v_mfma_f32_16x16x32_bf16 v[76:79], v[154:157], v[218:221], v[76:79]
	v_mfma_f32_16x16x32_bf16 v[72:75], v[162:165], v[218:221], v[72:75]
	s_setprio 0
	s_setprio 1
	v_mfma_f32_16x16x32_bf16 v[116:119], v[166:169], v[190:193], v[116:119]
	v_mfma_f32_16x16x32_bf16 v[112:115], v[182:185], v[190:193], v[112:115]
	v_mfma_f32_16x16x32_bf16 v[100:103], v[166:169], v[198:201], v[100:103]
	v_mfma_f32_16x16x32_bf16 v[96:99], v[182:185], v[198:201], v[96:99]
	v_mfma_f32_16x16x32_bf16 v[84:87], v[166:169], v[206:209], v[84:87]
	v_mfma_f32_16x16x32_bf16 v[80:83], v[182:185], v[206:209], v[80:83]
	v_mfma_f32_16x16x32_bf16 v[68:71], v[166:169], v[214:217], v[68:71]
	v_mfma_f32_16x16x32_bf16 v[64:67], v[182:185], v[214:217], v[64:67]
	v_mfma_f32_16x16x32_bf16 v[116:119], v[178:181], v[194:197], v[116:119]
	v_mfma_f32_16x16x32_bf16 v[112:115], v[186:189], v[194:197], v[112:115]
	v_mfma_f32_16x16x32_bf16 v[100:103], v[178:181], v[202:205], v[100:103]
	v_mfma_f32_16x16x32_bf16 v[96:99], v[186:189], v[202:205], v[96:99]
	v_mfma_f32_16x16x32_bf16 v[84:87], v[178:181], v[210:213], v[84:87]
	v_mfma_f32_16x16x32_bf16 v[80:83], v[186:189], v[210:213], v[80:83]
	v_mfma_f32_16x16x32_bf16 v[68:71], v[178:181], v[218:221], v[68:71]
	v_mfma_f32_16x16x32_bf16 v[64:67], v[186:189], v[218:221], v[64:67]
	s_setprio 0
	s_barrier
	s_add_i32 s22, s41, s33
	v_lshl_add_u64 v[146:147], s[26:27], 0, v[130:131]
	s_mov_b32 m0, s22
	ds_read_b128 v[190:193], v153 offset:16384
	ds_read_b128 v[194:197], v153 offset:17408
	ds_read_b128 v[198:201], v153 offset:18432
	ds_read_b128 v[202:205], v153 offset:19456
	ds_read_b128 v[206:209], v153 offset:20480
	ds_read_b128 v[210:213], v153 offset:21504
	ds_read_b128 v[214:217], v153 offset:22528
	ds_read_b128 v[218:221], v153 offset:23552
	global_load_lds_dwordx4 v[146:147], off
	s_add_i32 m0, s22, 0x2000
	s_add_u32 s22, s26, 0x80000
	v_lshl_add_u64 v[170:171], s[26:27], 0, v[132:133]
	s_addc_u32 s23, s27, 0
	s_add_i32 s48, s42, s33
	global_load_lds_dwordx4 v[170:171], off
	v_lshl_add_u64 v[222:223], s[22:23], 0, v[130:131]
	s_mov_b32 m0, s48
	v_lshl_add_u64 v[224:225], s[28:29], 0, v[132:133]
	global_load_lds_dwordx4 v[222:223], off
	v_lshl_add_u64 v[222:223], s[22:23], 0, v[132:133]
	s_add_i32 m0, s48, 0x2000
	s_nop 0
	global_load_lds_dwordx4 v[222:223], off
	v_lshl_add_u64 v[222:223], s[28:29], 0, v[130:131]
	s_mov_b32 m0, s34
	s_nop 0
	global_load_lds_dwordx4 v[222:223], off
	s_mov_b32 m0, s35
	s_nop 0
	global_load_lds_dwordx4 v[224:225], off
	s_waitcnt vmcnt(8)
	s_waitcnt lgkmcnt(0)
	v_mfma_f32_16x16x32_bf16 v[60:63], v[142:145], v[190:193], v[60:63]
	v_mfma_f32_16x16x32_bf16 v[56:59], v[158:161], v[190:193], v[56:59]
	s_barrier
; #define PG8_STAGE(bufoff, gbase, voff) do { _Pragma("unroll") for (int _i = 0; _i < 2; ++_i) \
;         __builtin_amdgcn_global_load_lds((const unsigned*)((const char*)(gbase) + (voff)[_i]), (PG8_LAS unsigned*)(lds + (bufoff) + ldsw + _i * 8192), 16, 0, 0); } while (0)
; #define PG8_LDA(dst, b, h) do { _Pragma("unroll") for (int m = 0; m < 4; ++m) _Pragma("unroll") for (int k = 0; k < 2; ++k) dst[m][k] = *(const PG8_LAS bf16x8*)(lds + PG8_SA(b, h) + aoff + m * 2048 + k * 1024); } while (0)
; #define PG8_LDB(dst, b, h) do { _Pragma("unroll") for (int n = 0; n < 2; ++n) _Pragma("unroll") for (int k = 0; k < 2; ++k) dst[n][k] = *(const PG8_LAS bf16x8*)(lds + PG8_SB(b, h) + boff + n * 2048 + k * 1024); } while (0)
; #define PG8_MMA(ai, bj, At, Bt) do { __builtin_amdgcn_s_setprio(1); _Pragma("unroll") for (int m = 0; m < 4; ++m) _Pragma("unroll") for (int n = 0; n < 2; ++n) _Pragma("unroll") for (int k = 0; k < 2; ++k) \
;         acc[ai][bj][m][n] = __builtin_amdgcn_mfma_f32_16x16x32_bf16(Bt[n][k], At[m][k], acc[ai][bj][m][n], 0, 0, 0); __builtin_amdgcn_s_setprio(0); } while (0)
; #define PG8_WAIT_V(n) asm volatile("s_waitcnt vmcnt(" #n ")" ::: "memory")
; #define PG8_WAIT_L(n) asm volatile("s_waitcnt lgkmcnt(" #n ")" ::: "memory")
; #define PG8_BAR __builtin_amdgcn_s_barrier()
; #define PG8_SCHED __builtin_amdgcn_sched_barrier(0)
; template <class Epi, class Sched, bool ALIGN_EPI = false, bool SP2 = false>
; __device__ __forceinline__ void gemm_phase(PG8_LAS unsigned char* lds, const Gemm g, const Sched& S, const Epi& E) {
;     ...
;             PG8_WAIT_V(8); PG8_WAIT_L(0); PG8_BAR; PG8_MMA(1, 0, At, B0); PG8_MMA(1, 1, At, B1); PG8_BAR; PG8_SCHED;
;             PG8_LDB(B0, 1, 0); PG8_LDB(B1, 1, 1); PG8_SCHED; PG8_LDA(At, 1, 0); PG8_STAGE(PG8_SA(0, 1), a2 + hstep, voffA);
;             PG8_WAIT_V(8); PG8_WAIT_L(0); PG8_BAR; PG8_MMA(0, 0, At, B0); PG8_MMA(0, 1, At, B1); PG8_BAR; PG8_SCHED;
	s_setprio 1
	s_waitcnt lgkmcnt(0)
	v_mfma_f32_16x16x32_bf16 v[44:47], v[142:145], v[198:201], v[44:47]
	v_mfma_f32_16x16x32_bf16 v[40:43], v[158:161], v[198:201], v[40:43]
	v_mfma_f32_16x16x32_bf16 v[28:31], v[142:145], v[206:209], v[28:31]
	v_mfma_f32_16x16x32_bf16 v[24:27], v[158:161], v[206:209], v[24:27]
	v_mfma_f32_16x16x32_bf16 v[12:15], v[142:145], v[214:217], v[12:15]
	v_mfma_f32_16x16x32_bf16 v[8:11], v[158:161], v[214:217], v[8:11]
	v_mfma_f32_16x16x32_bf16 v[60:63], v[154:157], v[194:197], v[60:63]
	v_mfma_f32_16x16x32_bf16 v[56:59], v[162:165], v[194:197], v[56:59]
	v_mfma_f32_16x16x32_bf16 v[44:47], v[154:157], v[202:205], v[44:47]
	v_mfma_f32_16x16x32_bf16 v[40:43], v[162:165], v[202:205], v[40:43]
	v_mfma_f32_16x16x32_bf16 v[28:31], v[154:157], v[210:213], v[28:31]
	v_mfma_f32_16x16x32_bf16 v[24:27], v[162:165], v[210:213], v[24:27]
	v_mfma_f32_16x16x32_bf16 v[12:15], v[154:157], v[218:221], v[12:15]
	v_mfma_f32_16x16x32_bf16 v[8:11], v[162:165], v[218:221], v[8:11]
	s_setprio 0
	s_setprio 1
	v_mfma_f32_16x16x32_bf16 v[52:55], v[166:169], v[190:193], v[52:55]
	v_mfma_f32_16x16x32_bf16 v[48:51], v[182:185], v[190:193], v[48:51]
	v_mfma_f32_16x16x32_bf16 v[36:39], v[166:169], v[198:201], v[36:39]
	v_mfma_f32_16x16x32_bf16 v[32:35], v[182:185], v[198:201], v[32:35]
	v_mfma_f32_16x16x32_bf16 v[20:23], v[166:169], v[206:209], v[20:23]
	v_mfma_f32_16x16x32_bf16 v[16:19], v[182:185], v[206:209], v[16:19]
	v_mfma_f32_16x16x32_bf16 v[4:7], v[166:169], v[214:217], v[4:7]
	v_mfma_f32_16x16x32_bf16 v[0:3], v[182:185], v[214:217], v[0:3]
	v_mfma_f32_16x16x32_bf16 v[52:55], v[178:181], v[194:197], v[52:55]
	v_mfma_f32_16x16x32_bf16 v[48:51], v[186:189], v[194:197], v[48:51]
	v_mfma_f32_16x16x32_bf16 v[36:39], v[178:181], v[202:205], v[36:39]
	v_mfma_f32_16x16x32_bf16 v[32:35], v[186:189], v[202:205], v[32:35]
	v_mfma_f32_16x16x32_bf16 v[20:23], v[178:181], v[210:213], v[20:23]
	v_mfma_f32_16x16x32_bf16 v[16:19], v[186:189], v[210:213], v[16:19]
	v_mfma_f32_16x16x32_bf16 v[4:7], v[178:181], v[218:221], v[4:7]
	v_mfma_f32_16x16x32_bf16 v[0:3], v[186:189], v[218:221], v[0:3]
	s_setprio 0
	s_barrier
	s_add_i32 s48, 0, 0x18000
	s_add_i32 s49, 0, 0x1c000
	v_add_u32_e32 v162, s48, v149
	v_add_u32_e32 v186, s49, v149
	ds_read_b128 v[142:145], v162
	ds_read_b128 v[154:157], v162 offset:1024
	ds_read_b128 v[158:161], v162 offset:2048
	ds_read_b128 v[162:165], v162 offset:3072
	ds_read_b128 v[166:169], v186
	ds_read_b128 v[178:181], v186 offset:1024
	ds_read_b128 v[182:185], v186 offset:2048
	ds_read_b128 v[186:189], v186 offset:3072
	s_add_u32 s22, s28, 0x80000
	s_addc_u32 s23, s29, 0
	s_mov_b32 m0, s36
	v_lshl_add_u64 v[226:227], s[22:23], 0, v[130:131]
	ds_read_b128 v[190:193], v153 offset:32768
	ds_read_b128 v[194:197], v153 offset:33792
	ds_read_b128 v[198:201], v153 offset:34816
	ds_read_b128 v[202:205], v153 offset:35840
	ds_read_b128 v[206:209], v153 offset:36864
	ds_read_b128 v[210:213], v153 offset:37888
	ds_read_b128 v[214:217], v153 offset:38912
	ds_read_b128 v[218:221], v153 offset:39936
	global_load_lds_dwordx4 v[226:227], off
	v_lshl_add_u64 v[226:227], s[22:23], 0, v[132:133]
	s_mov_b32 m0, s37
	s_nop 0
	global_load_lds_dwordx4 v[226:227], off
	s_waitcnt vmcnt(8)
	s_waitcnt lgkmcnt(0)
	v_mfma_f32_16x16x32_bf16 v[124:127], v[142:145], v[190:193], v[124:127]
	v_mfma_f32_16x16x32_bf16 v[120:123], v[158:161], v[190:193], v[120:123]
	s_barrier
	s_setprio 1
	s_waitcnt lgkmcnt(0)
	v_mfma_f32_16x16x32_bf16 v[108:111], v[142:145], v[198:201], v[108:111]
	v_mfma_f32_16x16x32_bf16 v[104:107], v[158:161], v[198:201], v[104:107]
	v_mfma_f32_16x16x32_bf16 v[92:95], v[142:145], v[206:209], v[92:95]
	v_mfma_f32_16x16x32_bf16 v[88:91], v[158:161], v[206:209], v[88:91]
	v_mfma_f32_16x16x32_bf16 v[76:79], v[142:145], v[214:217], v[76:79]
	v_mfma_f32_16x16x32_bf16 v[72:75], v[158:161], v[214:217], v[72:75]
	v_mfma_f32_16x16x32_bf16 v[124:127], v[154:157], v[194:197], v[124:127]
	v_mfma_f32_16x16x32_bf16 v[120:123], v[162:165], v[194:197], v[120:123]
	v_mfma_f32_16x16x32_bf16 v[108:111], v[154:157], v[202:205], v[108:111]
	v_mfma_f32_16x16x32_bf16 v[104:107], v[162:165], v[202:205], v[104:107]
	v_mfma_f32_16x16x32_bf16 v[92:95], v[154:157], v[210:213], v[92:95]
	v_mfma_f32_16x16x32_bf16 v[88:91], v[162:165], v[210:213], v[88:91]
	v_mfma_f32_16x16x32_bf16 v[76:79], v[154:157], v[218:221], v[76:79]
	v_mfma_f32_16x16x32_bf16 v[72:75], v[162:165], v[218:221], v[72:75]
	s_setprio 0
	s_setprio 1
	v_mfma_f32_16x16x32_bf16 v[116:119], v[166:169], v[190:193], v[116:119]
	v_mfma_f32_16x16x32_bf16 v[112:115], v[182:185], v[190:193], v[112:115]
	v_mfma_f32_16x16x32_bf16 v[100:103], v[166:169], v[198:201], v[100:103]
	v_mfma_f32_16x16x32_bf16 v[96:99], v[182:185], v[198:201], v[96:99]
	v_mfma_f32_16x16x32_bf16 v[84:87], v[166:169], v[206:209], v[84:87]
	v_mfma_f32_16x16x32_bf16 v[80:83], v[182:185], v[206:209], v[80:83]
	v_mfma_f32_16x16x32_bf16 v[68:71], v[166:169], v[214:217], v[68:71]
	v_mfma_f32_16x16x32_bf16 v[64:67], v[182:185], v[214:217], v[64:67]
	v_mfma_f32_16x16x32_bf16 v[116:119], v[178:181], v[194:197], v[116:119]
	v_mfma_f32_16x16x32_bf16 v[112:115], v[186:189], v[194:197], v[112:115]
	v_mfma_f32_16x16x32_bf16 v[100:103], v[178:181], v[202:205], v[100:103]
	v_mfma_f32_16x16x32_bf16 v[96:99], v[186:189], v[202:205], v[96:99]
	v_mfma_f32_16x16x32_bf16 v[84:87], v[178:181], v[210:213], v[84:87]
	v_mfma_f32_16x16x32_bf16 v[80:83], v[186:189], v[210:213], v[80:83]
	v_mfma_f32_16x16x32_bf16 v[68:71], v[178:181], v[218:221], v[68:71]
	v_mfma_f32_16x16x32_bf16 v[64:67], v[186:189], v[218:221], v[64:67]
	s_setprio 0
	s_barrier
; #define PG8_STAGE(bufoff, gbase, voff) do { _Pragma("unroll") for (int _i = 0; _i < 2; ++_i) \
;         __builtin_amdgcn_global_load_lds((const unsigned*)((const char*)(gbase) + (voff)[_i]), (PG8_LAS unsigned*)(lds + (bufoff) + ldsw + _i * 8192), 16, 0, 0); } while (0)
; #define PG8_LDA(dst, b, h) do { _Pragma("unroll") for (int m = 0; m < 4; ++m) _Pragma("unroll") for (int k = 0; k < 2; ++k) dst[m][k] = *(const PG8_LAS bf16x8*)(lds + PG8_SA(b, h) + aoff + m * 2048 + k * 1024); } while (0)
; #define PG8_MMA(ai, bj, At, Bt) do { __builtin_amdgcn_s_setprio(1); _Pragma("unroll") for (int m = 0; m < 4; ++m) _Pragma("unroll") for (int n = 0; n < 2; ++n) _Pragma("unroll") for (int k = 0; k < 2; ++k) \
;         acc[ai][bj][m][n] = __builtin_amdgcn_mfma_f32_16x16x32_bf16(Bt[n][k], At[m][k], acc[ai][bj][m][n], 0, 0, 0); __builtin_amdgcn_s_setprio(0); } while (0)
; #define PG8_WAIT_V(n) asm volatile("s_waitcnt vmcnt(" #n ")" ::: "memory")
; #define PG8_WAIT_L(n) asm volatile("s_waitcnt lgkmcnt(" #n ")" ::: "memory")
; #define PG8_BAR __builtin_amdgcn_s_barrier()
; #define PG8_SCHED __builtin_amdgcn_sched_barrier(0)
; template <class Epi, class Sched, bool ALIGN_EPI = false, bool SP2 = false>
; __device__ __forceinline__ void gemm_phase(PG8_LAS unsigned char* lds, const Gemm g, const Sched& S, const Epi& E) {
;     ...
;             PG8_LDA(At, 1, 1); PG8_STAGE(PG8_SB(1, 0), b3, voffB); PG8_STAGE(PG8_SB(1, 1), b3 + hstep, voffB); PG8_STAGE(PG8_SA(1, 0), a3, voffA);
;             PG8_WAIT_V(8); PG8_WAIT_L(0); PG8_BAR; PG8_MMA(1, 0, At, B0); PG8_MMA(1, 1, At, B1); PG8_BAR; PG8_SCHED;
	s_add_i32 s22, s48, s33
	v_lshl_add_u64 v[146:147], v[146:147], 0, s[4:5]
	s_mov_b32 m0, s22
	ds_read_b128 v[190:193], v153 offset:49152
	ds_read_b128 v[194:197], v153 offset:50176
	ds_read_b128 v[198:201], v153 offset:51200
	ds_read_b128 v[202:205], v153 offset:52224
	ds_read_b128 v[206:209], v153 offset:53248
	ds_read_b128 v[210:213], v153 offset:54272
	ds_read_b128 v[214:217], v153 offset:55296
	ds_read_b128 v[218:221], v153 offset:56320
	global_load_lds_dwordx4 v[146:147], off
	s_add_i32 m0, s22, 0x2000
	s_add_u32 s22, s26, 0x80080
	v_lshl_add_u64 v[146:147], v[170:171], 0, s[4:5]
	s_addc_u32 s23, s27, 0
	s_add_i32 s26, s49, s33
	global_load_lds_dwordx4 v[146:147], off
	v_lshl_add_u64 v[146:147], s[22:23], 0, v[130:131]
	s_mov_b32 m0, s26
	s_nop 0
	global_load_lds_dwordx4 v[146:147], off
	v_lshl_add_u64 v[146:147], s[22:23], 0, v[132:133]
	s_add_i32 m0, s26, 0x2000
	s_nop 0
	global_load_lds_dwordx4 v[146:147], off
	v_lshl_add_u64 v[146:147], v[222:223], 0, s[4:5]
	s_mov_b32 m0, s39
	s_nop 0
	global_load_lds_dwordx4 v[146:147], off
	v_lshl_add_u64 v[146:147], v[224:225], 0, s[4:5]
	s_mov_b32 m0, s40
	s_nop 0
	global_load_lds_dwordx4 v[146:147], off
	s_waitcnt vmcnt(8)
	s_waitcnt lgkmcnt(0)
	v_mfma_f32_16x16x32_bf16 v[60:63], v[142:145], v[190:193], v[60:63]
	v_mfma_f32_16x16x32_bf16 v[56:59], v[158:161], v[190:193], v[56:59]
	s_barrier
	s_setprio 1
	s_waitcnt lgkmcnt(0)
	v_mfma_f32_16x16x32_bf16 v[44:47], v[142:145], v[198:201], v[44:47]
	v_mfma_f32_16x16x32_bf16 v[40:43], v[158:161], v[198:201], v[40:43]
	v_mfma_f32_16x16x32_bf16 v[28:31], v[142:145], v[206:209], v[28:31]
	v_mfma_f32_16x16x32_bf16 v[24:27], v[158:161], v[206:209], v[24:27]
	v_mfma_f32_16x16x32_bf16 v[12:15], v[142:145], v[214:217], v[12:15]
	v_mfma_f32_16x16x32_bf16 v[8:11], v[158:161], v[214:217], v[8:11]
	v_mfma_f32_16x16x32_bf16 v[60:63], v[154:157], v[194:197], v[60:63]
	v_mfma_f32_16x16x32_bf16 v[56:59], v[162:165], v[194:197], v[56:59]
	v_mfma_f32_16x16x32_bf16 v[44:47], v[154:157], v[202:205], v[44:47]
	v_mfma_f32_16x16x32_bf16 v[40:43], v[162:165], v[202:205], v[40:43]
	v_mfma_f32_16x16x32_bf16 v[28:31], v[154:157], v[210:213], v[28:31]
	v_mfma_f32_16x16x32_bf16 v[24:27], v[162:165], v[210:213], v[24:27]
	v_mfma_f32_16x16x32_bf16 v[12:15], v[154:157], v[218:221], v[12:15]
	v_mfma_f32_16x16x32_bf16 v[8:11], v[162:165], v[218:221], v[8:11]
	s_setprio 0
	s_setprio 1
	v_mfma_f32_16x16x32_bf16 v[52:55], v[166:169], v[190:193], v[52:55]
	v_mfma_f32_16x16x32_bf16 v[48:51], v[182:185], v[190:193], v[48:51]
	v_mfma_f32_16x16x32_bf16 v[36:39], v[166:169], v[198:201], v[36:39]
	v_mfma_f32_16x16x32_bf16 v[32:35], v[182:185], v[198:201], v[32:35]
	v_mfma_f32_16x16x32_bf16 v[20:23], v[166:169], v[206:209], v[20:23]
	v_mfma_f32_16x16x32_bf16 v[16:19], v[182:185], v[206:209], v[16:19]
	v_mfma_f32_16x16x32_bf16 v[4:7], v[166:169], v[214:217], v[4:7]
	v_mfma_f32_16x16x32_bf16 v[0:3], v[182:185], v[214:217], v[0:3]
	v_mfma_f32_16x16x32_bf16 v[52:55], v[178:181], v[194:197], v[52:55]
	v_mfma_f32_16x16x32_bf16 v[48:51], v[186:189], v[194:197], v[48:51]
	v_mfma_f32_16x16x32_bf16 v[36:39], v[178:181], v[202:205], v[36:39]
	v_mfma_f32_16x16x32_bf16 v[32:35], v[186:189], v[202:205], v[32:35]
	v_mfma_f32_16x16x32_bf16 v[20:23], v[178:181], v[210:213], v[20:23]
	v_mfma_f32_16x16x32_bf16 v[16:19], v[186:189], v[210:213], v[16:19]
	v_mfma_f32_16x16x32_bf16 v[4:7], v[178:181], v[218:221], v[4:7]
	v_mfma_f32_16x16x32_bf16 v[0:3], v[186:189], v[218:221], v[0:3]
	s_setprio 0
	s_barrier
	s_add_i32 s47, s47, 2
	s_add_u32 s45, s45, 0x100
	s_addc_u32 s46, s46, 0
	s_cmp_gt_u32 s47, 29
	s_mov_b64 s[22:23], s[24:25]
	s_cbranch_scc0 .LBB0_1457
	s_and_b64 vcc, exec, s[6:7]
	s_cbranch_vccz .LBB0_1460
	s_barrier

; #define PG8_STAGE(bufoff, gbase, voff) do { _Pragma("unroll") for (int _i = 0; _i < 2; ++_i) \
;         __builtin_amdgcn_global_load_lds((const unsigned*)((const char*)(gbase) + (voff)[_i]), (PG8_LAS unsigned*)(lds + (bufoff) + ldsw + _i * 8192), 16, 0, 0); } while (0)
; #define PG8_LDA(dst, b, h) do { _Pragma("unroll") for (int m = 0; m < 4; ++m) _Pragma("unroll") for (int k = 0; k < 2; ++k) dst[m][k] = *(const PG8_LAS bf16x8*)(lds + PG8_SA(b, h) + aoff + m * 2048 + k * 1024); } while (0)
; #define PG8_LDB(dst, b, h) do { _Pragma("unroll") for (int n = 0; n < 2; ++n) _Pragma("unroll") for (int k = 0; k < 2; ++k) dst[n][k] = *(const PG8_LAS bf16x8*)(lds + PG8_SB(b, h) + boff + n * 2048 + k * 1024); } while (0)
; #define PG8_MMA(ai, bj, At, Bt) do { __builtin_amdgcn_s_setprio(1); _Pragma("unroll") for (int m = 0; m < 4; ++m) _Pragma("unroll") for (int n = 0; n < 2; ++n) _Pragma("unroll") for (int k = 0; k < 2; ++k) \
;         acc[ai][bj][m][n] = __builtin_amdgcn_mfma_f32_16x16x32_bf16(Bt[n][k], At[m][k], acc[ai][bj][m][n], 0, 0, 0); __builtin_amdgcn_s_setprio(0); } while (0)
; #define PG8_WAIT_V(n) asm volatile("s_waitcnt vmcnt(" #n ")" ::: "memory")
; #define PG8_WAIT_L(n) asm volatile("s_waitcnt lgkmcnt(" #n ")" ::: "memory")
; #define PG8_BAR __builtin_amdgcn_s_barrier()
; #define PG8_SCHED __builtin_amdgcn_sched_barrier(0)
; template <class Epi, class Sched, bool ALIGN_EPI = false, bool SP2 = false>
; __device__ __forceinline__ void gemm_phase(PG8_LAS unsigned char* lds, const Gemm g, const Sched& S, const Epi& E) {
;     ...
;             PG8_LDB(B0, 0, 0); PG8_LDB(B1, 0, 1); PG8_SCHED; PG8_LDA(At, 0, 0); PG8_STAGE(PG8_SA(1, 1), a1 + hstep, voffA);
;             PG8_WAIT_V(8); PG8_WAIT_L(0); PG8_BAR; PG8_MMA(0, 0, At, B0); PG8_MMA(0, 1, At, B1); PG8_BAR; PG8_SCHED;
;             PG8_LDA(At, 0, 1); PG8_STAGE(PG8_SB(0, 0), b2, voffB); PG8_STAGE(PG8_SB(0, 1), b2 + hstep, voffB); PG8_STAGE(PG8_SA(0, 0), a2, voffA);
;             PG8_WAIT_V(8); PG8_WAIT_L(0); PG8_BAR; PG8_MMA(1, 0, At, B0); PG8_MMA(1, 1, At, B1); PG8_BAR; PG8_SCHED;
.LBB0_1712:
	ds_read_b128 v[144:147], v156
	ds_read_b128 v[148:151], v156 offset:1024
	ds_read_b128 v[160:163], v156 offset:2048
	ds_read_b128 v[164:167], v156 offset:3072
	ds_read_b128 v[168:171], v157
	ds_read_b128 v[174:177], v157 offset:1024
	ds_read_b128 v[178:181], v157 offset:2048
	ds_read_b128 v[182:185], v157 offset:3072
	s_add_u32 s20, s18, 0xfff80080
	s_addc_u32 s21, s19, -1
	s_cmp_eq_u32 s44, 28
	s_cselect_b32 s23, s11, s21
	s_cselect_b32 s22, s40, s20
	s_cselect_b32 s21, s9, s43
	s_cselect_b32 s20, s41, s42
	v_lshl_add_u64 v[218:219], s[18:19], 0, v[136:137]
	s_add_i32 m0, s17, 0xc000
	ds_read_b128 v[186:189], v158
	ds_read_b128 v[190:193], v158 offset:1024
	ds_read_b128 v[194:197], v158 offset:2048
	ds_read_b128 v[198:201], v158 offset:3072
	ds_read_b128 v[202:205], v158 offset:4096
	ds_read_b128 v[206:209], v158 offset:5120
	ds_read_b128 v[210:213], v158 offset:6144
	ds_read_b128 v[214:217], v158 offset:7168
	global_load_lds_dwordx4 v[218:219], off
	v_lshl_add_u64 v[218:219], s[18:19], 0, v[138:139]
	s_add_i32 m0, s17, 0xe000
	s_nop 0
	global_load_lds_dwordx4 v[218:219], off
	s_waitcnt vmcnt(8)
	s_waitcnt lgkmcnt(0)
	v_mfma_f32_16x16x32_bf16 v[124:127], v[144:147], v[186:189], v[124:127]
	v_mfma_f32_16x16x32_bf16 v[120:123], v[160:163], v[186:189], v[120:123]
	s_barrier
	s_setprio 1
	s_waitcnt lgkmcnt(0)
	v_mfma_f32_16x16x32_bf16 v[108:111], v[144:147], v[194:197], v[108:111]
	v_mfma_f32_16x16x32_bf16 v[104:107], v[160:163], v[194:197], v[104:107]
	v_mfma_f32_16x16x32_bf16 v[92:95], v[144:147], v[202:205], v[92:95]
	v_mfma_f32_16x16x32_bf16 v[88:91], v[160:163], v[202:205], v[88:91]
	v_mfma_f32_16x16x32_bf16 v[76:79], v[144:147], v[210:213], v[76:79]
	v_mfma_f32_16x16x32_bf16 v[72:75], v[160:163], v[210:213], v[72:75]
	v_mfma_f32_16x16x32_bf16 v[124:127], v[148:151], v[190:193], v[124:127]
	v_mfma_f32_16x16x32_bf16 v[120:123], v[164:167], v[190:193], v[120:123]
	v_mfma_f32_16x16x32_bf16 v[108:111], v[148:151], v[198:201], v[108:111]
	v_mfma_f32_16x16x32_bf16 v[104:107], v[164:167], v[198:201], v[104:107]
	v_mfma_f32_16x16x32_bf16 v[92:95], v[148:151], v[206:209], v[92:95]
	v_mfma_f32_16x16x32_bf16 v[88:91], v[164:167], v[206:209], v[88:91]
	v_mfma_f32_16x16x32_bf16 v[76:79], v[148:151], v[214:217], v[76:79]
	v_mfma_f32_16x16x32_bf16 v[72:75], v[164:167], v[214:217], v[72:75]
	s_setprio 0
	s_setprio 1
	v_mfma_f32_16x16x32_bf16 v[116:119], v[168:171], v[186:189], v[116:119]
	v_mfma_f32_16x16x32_bf16 v[112:115], v[178:181], v[186:189], v[112:115]
	v_mfma_f32_16x16x32_bf16 v[100:103], v[168:171], v[194:197], v[100:103]
	v_mfma_f32_16x16x32_bf16 v[96:99], v[178:181], v[194:197], v[96:99]
	v_mfma_f32_16x16x32_bf16 v[84:87], v[168:171], v[202:205], v[84:87]
	v_mfma_f32_16x16x32_bf16 v[80:83], v[178:181], v[202:205], v[80:83]
	v_mfma_f32_16x16x32_bf16 v[68:71], v[168:171], v[210:213], v[68:71]
	v_mfma_f32_16x16x32_bf16 v[64:67], v[178:181], v[210:213], v[64:67]
	v_mfma_f32_16x16x32_bf16 v[116:119], v[174:177], v[190:193], v[116:119]
	v_mfma_f32_16x16x32_bf16 v[112:115], v[182:185], v[190:193], v[112:115]
	v_mfma_f32_16x16x32_bf16 v[100:103], v[174:177], v[198:201], v[100:103]
	v_mfma_f32_16x16x32_bf16 v[96:99], v[182:185], v[198:201], v[96:99]
	v_mfma_f32_16x16x32_bf16 v[84:87], v[174:177], v[206:209], v[84:87]
	v_mfma_f32_16x16x32_bf16 v[80:83], v[182:185], v[206:209], v[80:83]
	v_mfma_f32_16x16x32_bf16 v[68:71], v[174:177], v[214:217], v[68:71]
	v_mfma_f32_16x16x32_bf16 v[64:67], v[182:185], v[214:217], v[64:67]
	s_setprio 0
	s_barrier
	s_add_i32 s45, s34, s26
	v_lshl_add_u64 v[218:219], s[20:21], 0, v[132:133]
	s_mov_b32 m0, s45
	ds_read_b128 v[186:189], v158 offset:16384
	ds_read_b128 v[190:193], v158 offset:17408
	ds_read_b128 v[194:197], v158 offset:18432
	ds_read_b128 v[198:201], v158 offset:19456
	ds_read_b128 v[202:205], v158 offset:20480
	ds_read_b128 v[206:209], v158 offset:21504
	ds_read_b128 v[210:213], v158 offset:22528
	ds_read_b128 v[214:217], v158 offset:23552
	global_load_lds_dwordx4 v[218:219], off
	s_add_i32 m0, s45, 0x2000
	s_add_u32 s46, s20, 0x80000
	v_lshl_add_u64 v[220:221], s[20:21], 0, v[128:129]
	s_addc_u32 s47, s21, 0
	s_add_i32 s45, s35, s26
	global_load_lds_dwordx4 v[220:221], off
	v_lshl_add_u64 v[222:223], s[46:47], 0, v[132:133]
	s_mov_b32 m0, s45
	v_lshl_add_u64 v[224:225], s[22:23], 0, v[130:131]
	global_load_lds_dwordx4 v[222:223], off
	v_lshl_add_u64 v[222:223], s[46:47], 0, v[128:129]
	s_add_i32 m0, s45, 0x2000
	s_nop 0
	global_load_lds_dwordx4 v[222:223], off
	v_lshl_add_u64 v[222:223], s[22:23], 0, v[134:135]
	s_mov_b32 m0, s17
	s_nop 0
	global_load_lds_dwordx4 v[222:223], off
	s_mov_b32 m0, s28
	s_nop 0
	global_load_lds_dwordx4 v[224:225], off
	s_waitcnt vmcnt(8)
	s_waitcnt lgkmcnt(0)
	v_mfma_f32_16x16x32_bf16 v[60:63], v[144:147], v[186:189], v[60:63]
	v_mfma_f32_16x16x32_bf16 v[56:59], v[160:163], v[186:189], v[56:59]
	s_barrier
; #define PG8_STAGE(bufoff, gbase, voff) do { _Pragma("unroll") for (int _i = 0; _i < 2; ++_i) \
;         __builtin_amdgcn_global_load_lds((const unsigned*)((const char*)(gbase) + (voff)[_i]), (PG8_LAS unsigned*)(lds + (bufoff) + ldsw + _i * 8192), 16, 0, 0); } while (0)
; #define PG8_LDA(dst, b, h) do { _Pragma("unroll") for (int m = 0; m < 4; ++m) _Pragma("unroll") for (int k = 0; k < 2; ++k) dst[m][k] = *(const PG8_LAS bf16x8*)(lds + PG8_SA(b, h) + aoff + m * 2048 + k * 1024); } while (0)
; #define PG8_LDB(dst, b, h) do { _Pragma("unroll") for (int n = 0; n < 2; ++n) _Pragma("unroll") for (int k = 0; k < 2; ++k) dst[n][k] = *(const PG8_LAS bf16x8*)(lds + PG8_SB(b, h) + boff + n * 2048 + k * 1024); } while (0)
; #define PG8_MMA(ai, bj, At, Bt) do { __builtin_amdgcn_s_setprio(1); _Pragma("unroll") for (int m = 0; m < 4; ++m) _Pragma("unroll") for (int n = 0; n < 2; ++n) _Pragma("unroll") for (int k = 0; k < 2; ++k) \
;         acc[ai][bj][m][n] = __builtin_amdgcn_mfma_f32_16x16x32_bf16(Bt[n][k], At[m][k], acc[ai][bj][m][n], 0, 0, 0); __builtin_amdgcn_s_setprio(0); } while (0)
; #define PG8_WAIT_V(n) asm volatile("s_waitcnt vmcnt(" #n ")" ::: "memory")
; #define PG8_WAIT_L(n) asm volatile("s_waitcnt lgkmcnt(" #n ")" ::: "memory")
; #define PG8_BAR __builtin_amdgcn_s_barrier()
; #define PG8_SCHED __builtin_amdgcn_sched_barrier(0)
; template <class Epi, class Sched, bool ALIGN_EPI = false, bool SP2 = false>
; __device__ __forceinline__ void gemm_phase(PG8_LAS unsigned char* lds, const Gemm g, const Sched& S, const Epi& E) {
;     ...
;             PG8_WAIT_V(8); PG8_WAIT_L(0); PG8_BAR; PG8_MMA(1, 0, At, B0); PG8_MMA(1, 1, At, B1); PG8_BAR; PG8_SCHED;
;             PG8_LDB(B0, 1, 0); PG8_LDB(B1, 1, 1); PG8_SCHED; PG8_LDA(At, 1, 0); PG8_STAGE(PG8_SA(0, 1), a2 + hstep, voffA);
;             PG8_WAIT_V(8); PG8_WAIT_L(0); PG8_BAR; PG8_MMA(0, 0, At, B0); PG8_MMA(0, 1, At, B1); PG8_BAR; PG8_SCHED;
	s_setprio 1
	s_waitcnt lgkmcnt(0)
	v_mfma_f32_16x16x32_bf16 v[44:47], v[144:147], v[194:197], v[44:47]
	v_mfma_f32_16x16x32_bf16 v[40:43], v[160:163], v[194:197], v[40:43]
	v_mfma_f32_16x16x32_bf16 v[28:31], v[144:147], v[202:205], v[28:31]
	v_mfma_f32_16x16x32_bf16 v[24:27], v[160:163], v[202:205], v[24:27]
	v_mfma_f32_16x16x32_bf16 v[12:15], v[144:147], v[210:213], v[12:15]
	v_mfma_f32_16x16x32_bf16 v[8:11], v[160:163], v[210:213], v[8:11]
	v_mfma_f32_16x16x32_bf16 v[60:63], v[148:151], v[190:193], v[60:63]
	v_mfma_f32_16x16x32_bf16 v[56:59], v[164:167], v[190:193], v[56:59]
	v_mfma_f32_16x16x32_bf16 v[44:47], v[148:151], v[198:201], v[44:47]
	v_mfma_f32_16x16x32_bf16 v[40:43], v[164:167], v[198:201], v[40:43]
	v_mfma_f32_16x16x32_bf16 v[28:31], v[148:151], v[206:209], v[28:31]
	v_mfma_f32_16x16x32_bf16 v[24:27], v[164:167], v[206:209], v[24:27]
	v_mfma_f32_16x16x32_bf16 v[12:15], v[148:151], v[214:217], v[12:15]
	v_mfma_f32_16x16x32_bf16 v[8:11], v[164:167], v[214:217], v[8:11]
	s_setprio 0
	s_setprio 1
	v_mfma_f32_16x16x32_bf16 v[52:55], v[168:171], v[186:189], v[52:55]
	v_mfma_f32_16x16x32_bf16 v[48:51], v[178:181], v[186:189], v[48:51]
	v_mfma_f32_16x16x32_bf16 v[36:39], v[168:171], v[194:197], v[36:39]
	v_mfma_f32_16x16x32_bf16 v[32:35], v[178:181], v[194:197], v[32:35]
	v_mfma_f32_16x16x32_bf16 v[20:23], v[168:171], v[202:205], v[20:23]
	v_mfma_f32_16x16x32_bf16 v[16:19], v[178:181], v[202:205], v[16:19]
	v_mfma_f32_16x16x32_bf16 v[4:7], v[168:171], v[210:213], v[4:7]
	v_mfma_f32_16x16x32_bf16 v[0:3], v[178:181], v[210:213], v[0:3]
	v_mfma_f32_16x16x32_bf16 v[52:55], v[174:177], v[190:193], v[52:55]
	v_mfma_f32_16x16x32_bf16 v[48:51], v[182:185], v[190:193], v[48:51]
	v_mfma_f32_16x16x32_bf16 v[36:39], v[174:177], v[198:201], v[36:39]
	v_mfma_f32_16x16x32_bf16 v[32:35], v[182:185], v[198:201], v[32:35]
	v_mfma_f32_16x16x32_bf16 v[20:23], v[174:177], v[206:209], v[20:23]
	v_mfma_f32_16x16x32_bf16 v[16:19], v[182:185], v[206:209], v[16:19]
	v_mfma_f32_16x16x32_bf16 v[4:7], v[174:177], v[214:217], v[4:7]
	v_mfma_f32_16x16x32_bf16 v[0:3], v[182:185], v[214:217], v[0:3]
	s_setprio 0
	s_barrier
	s_add_i32 s45, 0, 0x18000
	v_add_u32_e32 v159, s45, v153
	s_add_i32 s46, 0, 0x1c000
	ds_read_b128 v[144:147], v159
	ds_read_b128 v[148:151], v159 offset:1024
	ds_read_b128 v[160:163], v159 offset:2048
	ds_read_b128 v[164:167], v159 offset:3072
	v_add_u32_e32 v159, s46, v153
	ds_read_b128 v[168:171], v159
	ds_read_b128 v[174:177], v159 offset:1024
	ds_read_b128 v[178:181], v159 offset:2048
	ds_read_b128 v[182:185], v159 offset:3072
	s_add_u32 s22, s22, 0x80000
	s_addc_u32 s23, s23, 0
	s_mov_b32 m0, s29
	v_lshl_add_u64 v[226:227], s[22:23], 0, v[134:135]
	ds_read_b128 v[186:189], v158 offset:32768
	ds_read_b128 v[190:193], v158 offset:33792
	ds_read_b128 v[194:197], v158 offset:34816
	ds_read_b128 v[198:201], v158 offset:35840
	ds_read_b128 v[202:205], v158 offset:36864
	ds_read_b128 v[206:209], v158 offset:37888
	ds_read_b128 v[210:213], v158 offset:38912
	ds_read_b128 v[214:217], v158 offset:39936
	global_load_lds_dwordx4 v[226:227], off
	v_lshl_add_u64 v[226:227], s[22:23], 0, v[130:131]
	s_mov_b32 m0, s30
	s_nop 0
	global_load_lds_dwordx4 v[226:227], off
	s_waitcnt vmcnt(8)
	s_waitcnt lgkmcnt(0)
	v_mfma_f32_16x16x32_bf16 v[124:127], v[144:147], v[186:189], v[124:127]
	v_mfma_f32_16x16x32_bf16 v[120:123], v[160:163], v[186:189], v[120:123]
	s_barrier
	s_setprio 1
	s_waitcnt lgkmcnt(0)
	v_mfma_f32_16x16x32_bf16 v[108:111], v[144:147], v[194:197], v[108:111]
	v_mfma_f32_16x16x32_bf16 v[104:107], v[160:163], v[194:197], v[104:107]
	v_mfma_f32_16x16x32_bf16 v[92:95], v[144:147], v[202:205], v[92:95]
	v_mfma_f32_16x16x32_bf16 v[88:91], v[160:163], v[202:205], v[88:91]
	v_mfma_f32_16x16x32_bf16 v[76:79], v[144:147], v[210:213], v[76:79]
	v_mfma_f32_16x16x32_bf16 v[72:75], v[160:163], v[210:213], v[72:75]
	v_mfma_f32_16x16x32_bf16 v[124:127], v[148:151], v[190:193], v[124:127]
	v_mfma_f32_16x16x32_bf16 v[120:123], v[164:167], v[190:193], v[120:123]
	v_mfma_f32_16x16x32_bf16 v[108:111], v[148:151], v[198:201], v[108:111]
	v_mfma_f32_16x16x32_bf16 v[104:107], v[164:167], v[198:201], v[104:107]
	v_mfma_f32_16x16x32_bf16 v[92:95], v[148:151], v[206:209], v[92:95]
	v_mfma_f32_16x16x32_bf16 v[88:91], v[164:167], v[206:209], v[88:91]
	v_mfma_f32_16x16x32_bf16 v[76:79], v[148:151], v[214:217], v[76:79]
	v_mfma_f32_16x16x32_bf16 v[72:75], v[164:167], v[214:217], v[72:75]
	s_setprio 0
	s_setprio 1
	v_mfma_f32_16x16x32_bf16 v[116:119], v[168:171], v[186:189], v[116:119]
	v_mfma_f32_16x16x32_bf16 v[112:115], v[178:181], v[186:189], v[112:115]
	v_mfma_f32_16x16x32_bf16 v[100:103], v[168:171], v[194:197], v[100:103]
	v_mfma_f32_16x16x32_bf16 v[96:99], v[178:181], v[194:197], v[96:99]
	v_mfma_f32_16x16x32_bf16 v[84:87], v[168:171], v[202:205], v[84:87]
	v_mfma_f32_16x16x32_bf16 v[80:83], v[178:181], v[202:205], v[80:83]
	v_mfma_f32_16x16x32_bf16 v[68:71], v[168:171], v[210:213], v[68:71]
	v_mfma_f32_16x16x32_bf16 v[64:67], v[178:181], v[210:213], v[64:67]
	v_mfma_f32_16x16x32_bf16 v[116:119], v[174:177], v[190:193], v[116:119]
	v_mfma_f32_16x16x32_bf16 v[112:115], v[182:185], v[190:193], v[112:115]
	v_mfma_f32_16x16x32_bf16 v[100:103], v[174:177], v[198:201], v[100:103]
	v_mfma_f32_16x16x32_bf16 v[96:99], v[182:185], v[198:201], v[96:99]
	v_mfma_f32_16x16x32_bf16 v[84:87], v[174:177], v[206:209], v[84:87]
	v_mfma_f32_16x16x32_bf16 v[80:83], v[182:185], v[206:209], v[80:83]
	v_mfma_f32_16x16x32_bf16 v[68:71], v[174:177], v[214:217], v[68:71]
	v_mfma_f32_16x16x32_bf16 v[64:67], v[182:185], v[214:217], v[64:67]
	s_setprio 0
	s_barrier
; #define PG8_STAGE(bufoff, gbase, voff) do { _Pragma("unroll") for (int _i = 0; _i < 2; ++_i) \
;         __builtin_amdgcn_global_load_lds((const unsigned*)((const char*)(gbase) + (voff)[_i]), (PG8_LAS unsigned*)(lds + (bufoff) + ldsw + _i * 8192), 16, 0, 0); } while (0)
; #define PG8_LDA(dst, b, h) do { _Pragma("unroll") for (int m = 0; m < 4; ++m) _Pragma("unroll") for (int k = 0; k < 2; ++k) dst[m][k] = *(const PG8_LAS bf16x8*)(lds + PG8_SA(b, h) + aoff + m * 2048 + k * 1024); } while (0)
; #define PG8_MMA(ai, bj, At, Bt) do { __builtin_amdgcn_s_setprio(1); _Pragma("unroll") for (int m = 0; m < 4; ++m) _Pragma("unroll") for (int n = 0; n < 2; ++n) _Pragma("unroll") for (int k = 0; k < 2; ++k) \
;         acc[ai][bj][m][n] = __builtin_amdgcn_mfma_f32_16x16x32_bf16(Bt[n][k], At[m][k], acc[ai][bj][m][n], 0, 0, 0); __builtin_amdgcn_s_setprio(0); } while (0)
; #define PG8_WAIT_V(n) asm volatile("s_waitcnt vmcnt(" #n ")" ::: "memory")
; #define PG8_WAIT_L(n) asm volatile("s_waitcnt lgkmcnt(" #n ")" ::: "memory")
; #define PG8_BAR __builtin_amdgcn_s_barrier()
; #define PG8_SCHED __builtin_amdgcn_sched_barrier(0)
; template <class Epi, class Sched, bool ALIGN_EPI = false, bool SP2 = false>
; __device__ __forceinline__ void gemm_phase(PG8_LAS unsigned char* lds, const Gemm g, const Sched& S, const Epi& E) {
;     ...
;             PG8_LDA(At, 1, 1); PG8_STAGE(PG8_SB(1, 0), b3, voffB); PG8_STAGE(PG8_SB(1, 1), b3 + hstep, voffB); PG8_STAGE(PG8_SA(1, 0), a3, voffA);
;             PG8_WAIT_V(8); PG8_WAIT_L(0); PG8_BAR; PG8_MMA(1, 0, At, B0); PG8_MMA(1, 1, At, B1); PG8_BAR; PG8_SCHED;
	s_add_i32 s22, s45, s26
	v_lshl_add_u64 v[218:219], v[218:219], 0, s[2:3]
	s_mov_b32 m0, s22
	ds_read_b128 v[186:189], v158 offset:49152
	ds_read_b128 v[190:193], v158 offset:50176
	ds_read_b128 v[194:197], v158 offset:51200
	ds_read_b128 v[198:201], v158 offset:52224
	ds_read_b128 v[202:205], v158 offset:53248
	ds_read_b128 v[206:209], v158 offset:54272
	ds_read_b128 v[210:213], v158 offset:55296
	ds_read_b128 v[214:217], v158 offset:56320
	global_load_lds_dwordx4 v[218:219], off
	s_add_i32 m0, s22, 0x2000
	s_add_u32 s20, s20, 0x80080
	v_lshl_add_u64 v[218:219], v[220:221], 0, s[2:3]
	s_addc_u32 s21, s21, 0
	s_add_i32 s22, s46, s26
	global_load_lds_dwordx4 v[218:219], off
	v_lshl_add_u64 v[218:219], s[20:21], 0, v[132:133]
	s_mov_b32 m0, s22
	s_nop 0
	global_load_lds_dwordx4 v[218:219], off
	v_lshl_add_u64 v[218:219], s[20:21], 0, v[128:129]
	s_add_i32 m0, s22, 0x2000
	s_nop 0
	global_load_lds_dwordx4 v[218:219], off
	v_lshl_add_u64 v[218:219], v[222:223], 0, s[2:3]
	s_mov_b32 m0, s31
	s_nop 0
	global_load_lds_dwordx4 v[218:219], off
	v_lshl_add_u64 v[218:219], v[224:225], 0, s[2:3]
	s_mov_b32 m0, s33
	s_nop 0
	global_load_lds_dwordx4 v[218:219], off
	s_waitcnt vmcnt(8)
	s_waitcnt lgkmcnt(0)
	v_mfma_f32_16x16x32_bf16 v[60:63], v[144:147], v[186:189], v[60:63]
	v_mfma_f32_16x16x32_bf16 v[56:59], v[160:163], v[186:189], v[56:59]
	s_barrier
	s_setprio 1
	s_waitcnt lgkmcnt(0)
	v_mfma_f32_16x16x32_bf16 v[44:47], v[144:147], v[194:197], v[44:47]
	v_mfma_f32_16x16x32_bf16 v[40:43], v[160:163], v[194:197], v[40:43]
	v_mfma_f32_16x16x32_bf16 v[28:31], v[144:147], v[202:205], v[28:31]
	v_mfma_f32_16x16x32_bf16 v[24:27], v[160:163], v[202:205], v[24:27]
	v_mfma_f32_16x16x32_bf16 v[12:15], v[144:147], v[210:213], v[12:15]
	v_mfma_f32_16x16x32_bf16 v[8:11], v[160:163], v[210:213], v[8:11]
	v_mfma_f32_16x16x32_bf16 v[60:63], v[148:151], v[190:193], v[60:63]
	v_mfma_f32_16x16x32_bf16 v[56:59], v[164:167], v[190:193], v[56:59]
	v_mfma_f32_16x16x32_bf16 v[44:47], v[148:151], v[198:201], v[44:47]
	v_mfma_f32_16x16x32_bf16 v[40:43], v[164:167], v[198:201], v[40:43]
	v_mfma_f32_16x16x32_bf16 v[28:31], v[148:151], v[206:209], v[28:31]
	v_mfma_f32_16x16x32_bf16 v[24:27], v[164:167], v[206:209], v[24:27]
	v_mfma_f32_16x16x32_bf16 v[12:15], v[148:151], v[214:217], v[12:15]
	v_mfma_f32_16x16x32_bf16 v[8:11], v[164:167], v[214:217], v[8:11]
	s_setprio 0
	s_setprio 1
	v_mfma_f32_16x16x32_bf16 v[52:55], v[168:171], v[186:189], v[52:55]
	v_mfma_f32_16x16x32_bf16 v[48:51], v[178:181], v[186:189], v[48:51]
	v_mfma_f32_16x16x32_bf16 v[36:39], v[168:171], v[194:197], v[36:39]
	v_mfma_f32_16x16x32_bf16 v[32:35], v[178:181], v[194:197], v[32:35]
	v_mfma_f32_16x16x32_bf16 v[20:23], v[168:171], v[202:205], v[20:23]
	v_mfma_f32_16x16x32_bf16 v[16:19], v[178:181], v[202:205], v[16:19]
	v_mfma_f32_16x16x32_bf16 v[4:7], v[168:171], v[210:213], v[4:7]
	v_mfma_f32_16x16x32_bf16 v[0:3], v[178:181], v[210:213], v[0:3]
	v_mfma_f32_16x16x32_bf16 v[52:55], v[174:177], v[190:193], v[52:55]
	v_mfma_f32_16x16x32_bf16 v[48:51], v[182:185], v[190:193], v[48:51]
	v_mfma_f32_16x16x32_bf16 v[36:39], v[174:177], v[198:201], v[36:39]
	v_mfma_f32_16x16x32_bf16 v[32:35], v[182:185], v[198:201], v[32:35]
	v_mfma_f32_16x16x32_bf16 v[20:23], v[174:177], v[206:209], v[20:23]
	v_mfma_f32_16x16x32_bf16 v[16:19], v[182:185], v[206:209], v[16:19]
	v_mfma_f32_16x16x32_bf16 v[4:7], v[174:177], v[214:217], v[4:7]
	v_mfma_f32_16x16x32_bf16 v[0:3], v[182:185], v[214:217], v[0:3]
	s_setprio 0
	s_barrier
	s_add_i32 s44, s44, 2
	s_add_u32 s18, s18, 0x100
	s_addc_u32 s19, s19, 0
	s_add_u32 s42, s42, 0x100
	s_addc_u32 s43, s43, 0
	s_cmp_gt_u32 s44, 29
	s_cbranch_scc0 .LBB0_1712
	s_and_b64 vcc, exec, s[6:7]
	s_cbranch_vccz .LBB0_1715
	s_barrier

; #define PG8_STAGE(bufoff, gbase, voff) do { _Pragma("unroll") for (int _i = 0; _i < 2; ++_i) \
;         __builtin_amdgcn_global_load_lds((const unsigned*)((const char*)(gbase) + (voff)[_i]), (PG8_LAS unsigned*)(lds + (bufoff) + ldsw + _i * 8192), 16, 0, 0); } while (0)
; #define PG8_LDA(dst, b, h) do { _Pragma("unroll") for (int m = 0; m < 4; ++m) _Pragma("unroll") for (int k = 0; k < 2; ++k) dst[m][k] = *(const PG8_LAS bf16x8*)(lds + PG8_SA(b, h) + aoff + m * 2048 + k * 1024); } while (0)
; #define PG8_LDB(dst, b, h) do { _Pragma("unroll") for (int n = 0; n < 2; ++n) _Pragma("unroll") for (int k = 0; k < 2; ++k) dst[n][k] = *(const PG8_LAS bf16x8*)(lds + PG8_SB(b, h) + boff + n * 2048 + k * 1024); } while (0)
; #define PG8_MMA(ai, bj, At, Bt) do { __builtin_amdgcn_s_setprio(1); _Pragma("unroll") for (int m = 0; m < 4; ++m) _Pragma("unroll") for (int n = 0; n < 2; ++n) _Pragma("unroll") for (int k = 0; k < 2; ++k) \
;         acc[ai][bj][m][n] = __builtin_amdgcn_mfma_f32_16x16x32_bf16(Bt[n][k], At[m][k], acc[ai][bj][m][n], 0, 0, 0); __builtin_amdgcn_s_setprio(0); } while (0)
; #define PG8_WAIT_V(n) asm volatile("s_waitcnt vmcnt(" #n ")" ::: "memory")
; #define PG8_WAIT_L(n) asm volatile("s_waitcnt lgkmcnt(" #n ")" ::: "memory")
; #define PG8_BAR __builtin_amdgcn_s_barrier()
; #define PG8_SCHED __builtin_amdgcn_sched_barrier(0)
; template <class Epi, class Sched, bool ALIGN_EPI = false, bool SP2 = false>
; __device__ __forceinline__ void gemm_phase(PG8_LAS unsigned char* lds, const Gemm g, const Sched& S, const Epi& E) {
;     ...
;             PG8_LDB(B0, 0, 0); PG8_LDB(B1, 0, 1); PG8_SCHED; PG8_LDA(At, 0, 0); PG8_STAGE(PG8_SA(1, 1), a1 + hstep, voffA);
;             PG8_WAIT_V(8); PG8_WAIT_L(0); PG8_BAR; PG8_MMA(0, 0, At, B0); PG8_MMA(0, 1, At, B1); PG8_BAR; PG8_SCHED;
;             PG8_LDA(At, 0, 1); PG8_STAGE(PG8_SB(0, 0), b2, voffB); PG8_STAGE(PG8_SB(0, 1), b2 + hstep, voffB); PG8_STAGE(PG8_SA(0, 0), a2, voffA);
;             PG8_WAIT_V(8); PG8_WAIT_L(0); PG8_BAR; PG8_MMA(1, 0, At, B0); PG8_MMA(1, 1, At, B1); PG8_BAR; PG8_SCHED;
.LBB0_1956:
	ds_read_b128 v[140:143], v149
	ds_read_b128 v[152:155], v149 offset:1024
	ds_read_b128 v[156:159], v149 offset:2048
	ds_read_b128 v[160:163], v149 offset:3072
	ds_read_b128 v[164:167], v150
	ds_read_b128 v[168:171], v150 offset:1024
	ds_read_b128 v[172:175], v150 offset:2048
	ds_read_b128 v[176:179], v150 offset:3072
	s_add_u32 s22, s20, 0x100
	s_addc_u32 s23, s21, 0
	s_cmpk_eq_i32 s47, 0x54
	s_cselect_b32 s27, s5, s23
	s_cselect_b32 s26, s4, s22
	s_cselect_b32 s25, s19, s46
	s_cselect_b32 s24, s18, s45
	v_lshl_add_u64 v[144:145], s[20:21], 0, v[132:133]
	s_add_i32 m0, s31, 0xc000
	ds_read_b128 v[180:183], v151
	ds_read_b128 v[184:187], v151 offset:1024
	ds_read_b128 v[188:191], v151 offset:2048
	ds_read_b128 v[192:195], v151 offset:3072
	ds_read_b128 v[196:199], v151 offset:4096
	ds_read_b128 v[200:203], v151 offset:5120
	ds_read_b128 v[204:207], v151 offset:6144
	ds_read_b128 v[208:211], v151 offset:7168
	global_load_lds_dwordx4 v[144:145], off
	v_lshl_add_u64 v[144:145], s[20:21], 0, v[134:135]
	s_add_i32 m0, s31, 0xe000
	s_nop 0
	global_load_lds_dwordx4 v[144:145], off
	s_waitcnt vmcnt(8)
	s_waitcnt lgkmcnt(0)
	v_mfma_f32_16x16x32_bf16 v[124:127], v[140:143], v[180:183], v[124:127]
	v_mfma_f32_16x16x32_bf16 v[120:123], v[156:159], v[180:183], v[120:123]
	s_barrier
	s_setprio 1
	s_waitcnt lgkmcnt(0)
	v_mfma_f32_16x16x32_bf16 v[108:111], v[140:143], v[188:191], v[108:111]
	v_mfma_f32_16x16x32_bf16 v[104:107], v[156:159], v[188:191], v[104:107]
	v_mfma_f32_16x16x32_bf16 v[92:95], v[140:143], v[196:199], v[92:95]
	v_mfma_f32_16x16x32_bf16 v[88:91], v[156:159], v[196:199], v[88:91]
	v_mfma_f32_16x16x32_bf16 v[76:79], v[140:143], v[204:207], v[76:79]
	v_mfma_f32_16x16x32_bf16 v[72:75], v[156:159], v[204:207], v[72:75]
	v_mfma_f32_16x16x32_bf16 v[124:127], v[152:155], v[184:187], v[124:127]
	v_mfma_f32_16x16x32_bf16 v[120:123], v[160:163], v[184:187], v[120:123]
	v_mfma_f32_16x16x32_bf16 v[108:111], v[152:155], v[192:195], v[108:111]
	v_mfma_f32_16x16x32_bf16 v[104:107], v[160:163], v[192:195], v[104:107]
	v_mfma_f32_16x16x32_bf16 v[92:95], v[152:155], v[200:203], v[92:95]
	v_mfma_f32_16x16x32_bf16 v[88:91], v[160:163], v[200:203], v[88:91]
	v_mfma_f32_16x16x32_bf16 v[76:79], v[152:155], v[208:211], v[76:79]
	v_mfma_f32_16x16x32_bf16 v[72:75], v[160:163], v[208:211], v[72:75]
	s_setprio 0
	s_setprio 1
	v_mfma_f32_16x16x32_bf16 v[116:119], v[164:167], v[180:183], v[116:119]
	v_mfma_f32_16x16x32_bf16 v[112:115], v[172:175], v[180:183], v[112:115]
	v_mfma_f32_16x16x32_bf16 v[100:103], v[164:167], v[188:191], v[100:103]
	v_mfma_f32_16x16x32_bf16 v[96:99], v[172:175], v[188:191], v[96:99]
	v_mfma_f32_16x16x32_bf16 v[84:87], v[164:167], v[196:199], v[84:87]
	v_mfma_f32_16x16x32_bf16 v[80:83], v[172:175], v[196:199], v[80:83]
	v_mfma_f32_16x16x32_bf16 v[68:71], v[164:167], v[204:207], v[68:71]
	v_mfma_f32_16x16x32_bf16 v[64:67], v[172:175], v[204:207], v[64:67]
	v_mfma_f32_16x16x32_bf16 v[116:119], v[168:171], v[184:187], v[116:119]
	v_mfma_f32_16x16x32_bf16 v[112:115], v[176:179], v[184:187], v[112:115]
	v_mfma_f32_16x16x32_bf16 v[100:103], v[168:171], v[192:195], v[100:103]
	v_mfma_f32_16x16x32_bf16 v[96:99], v[176:179], v[192:195], v[96:99]
	v_mfma_f32_16x16x32_bf16 v[84:87], v[168:171], v[200:203], v[84:87]
	v_mfma_f32_16x16x32_bf16 v[80:83], v[176:179], v[200:203], v[80:83]
	v_mfma_f32_16x16x32_bf16 v[68:71], v[168:171], v[208:211], v[68:71]
	v_mfma_f32_16x16x32_bf16 v[64:67], v[176:179], v[208:211], v[64:67]
	s_setprio 0
	s_barrier
	s_add_i32 s20, s39, s30
	v_lshl_add_u64 v[144:145], s[24:25], 0, v[128:129]
	s_mov_b32 m0, s20
	ds_read_b128 v[180:183], v151 offset:16384
	ds_read_b128 v[184:187], v151 offset:17408
	ds_read_b128 v[188:191], v151 offset:18432
	ds_read_b128 v[192:195], v151 offset:19456
	ds_read_b128 v[196:199], v151 offset:20480
	ds_read_b128 v[200:203], v151 offset:21504
	ds_read_b128 v[204:207], v151 offset:22528
	ds_read_b128 v[208:211], v151 offset:23552
	global_load_lds_dwordx4 v[144:145], off
	s_add_i32 m0, s20, 0x2000
	s_add_u32 s20, s24, 0x160000
	v_lshl_add_u64 v[212:213], s[24:25], 0, v[130:131]
	s_addc_u32 s21, s25, 0
	s_add_i32 s48, s40, s30
	global_load_lds_dwordx4 v[212:213], off
	v_lshl_add_u64 v[214:215], s[20:21], 0, v[128:129]
	s_mov_b32 m0, s48
	v_lshl_add_u64 v[216:217], s[26:27], 0, v[130:131]
	global_load_lds_dwordx4 v[214:215], off
	v_lshl_add_u64 v[214:215], s[20:21], 0, v[130:131]
	s_add_i32 m0, s48, 0x2000
	s_nop 0
	global_load_lds_dwordx4 v[214:215], off
	v_lshl_add_u64 v[214:215], s[26:27], 0, v[128:129]
	s_mov_b32 m0, s31
	s_nop 0
	global_load_lds_dwordx4 v[214:215], off
	s_mov_b32 m0, s33
	s_nop 0
	global_load_lds_dwordx4 v[216:217], off
	s_waitcnt vmcnt(8)
	s_waitcnt lgkmcnt(0)
	v_mfma_f32_16x16x32_bf16 v[60:63], v[140:143], v[180:183], v[60:63]
	v_mfma_f32_16x16x32_bf16 v[56:59], v[156:159], v[180:183], v[56:59]
	s_barrier
; #define PG8_STAGE(bufoff, gbase, voff) do { _Pragma("unroll") for (int _i = 0; _i < 2; ++_i) \
;         __builtin_amdgcn_global_load_lds((const unsigned*)((const char*)(gbase) + (voff)[_i]), (PG8_LAS unsigned*)(lds + (bufoff) + ldsw + _i * 8192), 16, 0, 0); } while (0)
; #define PG8_LDA(dst, b, h) do { _Pragma("unroll") for (int m = 0; m < 4; ++m) _Pragma("unroll") for (int k = 0; k < 2; ++k) dst[m][k] = *(const PG8_LAS bf16x8*)(lds + PG8_SA(b, h) + aoff + m * 2048 + k * 1024); } while (0)
; #define PG8_LDB(dst, b, h) do { _Pragma("unroll") for (int n = 0; n < 2; ++n) _Pragma("unroll") for (int k = 0; k < 2; ++k) dst[n][k] = *(const PG8_LAS bf16x8*)(lds + PG8_SB(b, h) + boff + n * 2048 + k * 1024); } while (0)
; #define PG8_MMA(ai, bj, At, Bt) do { __builtin_amdgcn_s_setprio(1); _Pragma("unroll") for (int m = 0; m < 4; ++m) _Pragma("unroll") for (int n = 0; n < 2; ++n) _Pragma("unroll") for (int k = 0; k < 2; ++k) \
;         acc[ai][bj][m][n] = __builtin_amdgcn_mfma_f32_16x16x32_bf16(Bt[n][k], At[m][k], acc[ai][bj][m][n], 0, 0, 0); __builtin_amdgcn_s_setprio(0); } while (0)
; #define PG8_WAIT_V(n) asm volatile("s_waitcnt vmcnt(" #n ")" ::: "memory")
; #define PG8_WAIT_L(n) asm volatile("s_waitcnt lgkmcnt(" #n ")" ::: "memory")
; #define PG8_BAR __builtin_amdgcn_s_barrier()
; #define PG8_SCHED __builtin_amdgcn_sched_barrier(0)
; template <class Epi, class Sched, bool ALIGN_EPI = false, bool SP2 = false>
; __device__ __forceinline__ void gemm_phase(PG8_LAS unsigned char* lds, const Gemm g, const Sched& S, const Epi& E) {
;     ...
;             PG8_WAIT_V(8); PG8_WAIT_L(0); PG8_BAR; PG8_MMA(1, 0, At, B0); PG8_MMA(1, 1, At, B1); PG8_BAR; PG8_SCHED;
;             PG8_LDB(B0, 1, 0); PG8_LDB(B1, 1, 1); PG8_SCHED; PG8_LDA(At, 1, 0); PG8_STAGE(PG8_SA(0, 1), a2 + hstep, voffA);
;             PG8_WAIT_V(8); PG8_WAIT_L(0); PG8_BAR; PG8_MMA(0, 0, At, B0); PG8_MMA(0, 1, At, B1); PG8_BAR; PG8_SCHED;
	s_setprio 1
	s_waitcnt lgkmcnt(0)
	v_mfma_f32_16x16x32_bf16 v[44:47], v[140:143], v[188:191], v[44:47]
	v_mfma_f32_16x16x32_bf16 v[40:43], v[156:159], v[188:191], v[40:43]
	v_mfma_f32_16x16x32_bf16 v[28:31], v[140:143], v[196:199], v[28:31]
	v_mfma_f32_16x16x32_bf16 v[24:27], v[156:159], v[196:199], v[24:27]
	v_mfma_f32_16x16x32_bf16 v[12:15], v[140:143], v[204:207], v[12:15]
	v_mfma_f32_16x16x32_bf16 v[8:11], v[156:159], v[204:207], v[8:11]
	v_mfma_f32_16x16x32_bf16 v[60:63], v[152:155], v[184:187], v[60:63]
	v_mfma_f32_16x16x32_bf16 v[56:59], v[160:163], v[184:187], v[56:59]
	v_mfma_f32_16x16x32_bf16 v[44:47], v[152:155], v[192:195], v[44:47]
	v_mfma_f32_16x16x32_bf16 v[40:43], v[160:163], v[192:195], v[40:43]
	v_mfma_f32_16x16x32_bf16 v[28:31], v[152:155], v[200:203], v[28:31]
	v_mfma_f32_16x16x32_bf16 v[24:27], v[160:163], v[200:203], v[24:27]
	v_mfma_f32_16x16x32_bf16 v[12:15], v[152:155], v[208:211], v[12:15]
	v_mfma_f32_16x16x32_bf16 v[8:11], v[160:163], v[208:211], v[8:11]
	s_setprio 0
	s_setprio 1
	v_mfma_f32_16x16x32_bf16 v[52:55], v[164:167], v[180:183], v[52:55]
	v_mfma_f32_16x16x32_bf16 v[48:51], v[172:175], v[180:183], v[48:51]
	v_mfma_f32_16x16x32_bf16 v[36:39], v[164:167], v[188:191], v[36:39]
	v_mfma_f32_16x16x32_bf16 v[32:35], v[172:175], v[188:191], v[32:35]
	v_mfma_f32_16x16x32_bf16 v[20:23], v[164:167], v[196:199], v[20:23]
	v_mfma_f32_16x16x32_bf16 v[16:19], v[172:175], v[196:199], v[16:19]
	v_mfma_f32_16x16x32_bf16 v[4:7], v[164:167], v[204:207], v[4:7]
	v_mfma_f32_16x16x32_bf16 v[0:3], v[172:175], v[204:207], v[0:3]
	v_mfma_f32_16x16x32_bf16 v[52:55], v[168:171], v[184:187], v[52:55]
	v_mfma_f32_16x16x32_bf16 v[48:51], v[176:179], v[184:187], v[48:51]
	v_mfma_f32_16x16x32_bf16 v[36:39], v[168:171], v[192:195], v[36:39]
	v_mfma_f32_16x16x32_bf16 v[32:35], v[176:179], v[192:195], v[32:35]
	v_mfma_f32_16x16x32_bf16 v[20:23], v[168:171], v[200:203], v[20:23]
	v_mfma_f32_16x16x32_bf16 v[16:19], v[176:179], v[200:203], v[16:19]
	v_mfma_f32_16x16x32_bf16 v[4:7], v[168:171], v[208:211], v[4:7]
	v_mfma_f32_16x16x32_bf16 v[0:3], v[176:179], v[208:211], v[0:3]
	s_setprio 0
	s_barrier
	s_add_i32 s48, 0, 0x18000
	s_add_i32 s49, 0, 0x1c000
	v_add_u32_e32 v160, s48, v147
	v_add_u32_e32 v176, s49, v147
	ds_read_b128 v[140:143], v160
	ds_read_b128 v[152:155], v160 offset:1024
	ds_read_b128 v[156:159], v160 offset:2048
	ds_read_b128 v[160:163], v160 offset:3072
	ds_read_b128 v[164:167], v176
	ds_read_b128 v[168:171], v176 offset:1024
	ds_read_b128 v[172:175], v176 offset:2048
	ds_read_b128 v[176:179], v176 offset:3072
	s_add_u32 s20, s26, 0x160000
	s_addc_u32 s21, s27, 0
	s_mov_b32 m0, s34
	v_lshl_add_u64 v[218:219], s[20:21], 0, v[128:129]
	ds_read_b128 v[180:183], v151 offset:32768
	ds_read_b128 v[184:187], v151 offset:33792
	ds_read_b128 v[188:191], v151 offset:34816
	ds_read_b128 v[192:195], v151 offset:35840
	ds_read_b128 v[196:199], v151 offset:36864
	ds_read_b128 v[200:203], v151 offset:37888
	ds_read_b128 v[204:207], v151 offset:38912
	ds_read_b128 v[208:211], v151 offset:39936
	global_load_lds_dwordx4 v[218:219], off
	v_lshl_add_u64 v[218:219], s[20:21], 0, v[130:131]
	s_mov_b32 m0, s35
	s_nop 0
	global_load_lds_dwordx4 v[218:219], off
	s_waitcnt vmcnt(8)
	s_waitcnt lgkmcnt(0)
	v_mfma_f32_16x16x32_bf16 v[124:127], v[140:143], v[180:183], v[124:127]
	v_mfma_f32_16x16x32_bf16 v[120:123], v[156:159], v[180:183], v[120:123]
	s_barrier
	s_setprio 1
	s_waitcnt lgkmcnt(0)
	v_mfma_f32_16x16x32_bf16 v[108:111], v[140:143], v[188:191], v[108:111]
	v_mfma_f32_16x16x32_bf16 v[104:107], v[156:159], v[188:191], v[104:107]
	v_mfma_f32_16x16x32_bf16 v[92:95], v[140:143], v[196:199], v[92:95]
	v_mfma_f32_16x16x32_bf16 v[88:91], v[156:159], v[196:199], v[88:91]
	v_mfma_f32_16x16x32_bf16 v[76:79], v[140:143], v[204:207], v[76:79]
	v_mfma_f32_16x16x32_bf16 v[72:75], v[156:159], v[204:207], v[72:75]
	v_mfma_f32_16x16x32_bf16 v[124:127], v[152:155], v[184:187], v[124:127]
	v_mfma_f32_16x16x32_bf16 v[120:123], v[160:163], v[184:187], v[120:123]
	v_mfma_f32_16x16x32_bf16 v[108:111], v[152:155], v[192:195], v[108:111]
	v_mfma_f32_16x16x32_bf16 v[104:107], v[160:163], v[192:195], v[104:107]
	v_mfma_f32_16x16x32_bf16 v[92:95], v[152:155], v[200:203], v[92:95]
	v_mfma_f32_16x16x32_bf16 v[88:91], v[160:163], v[200:203], v[88:91]
	v_mfma_f32_16x16x32_bf16 v[76:79], v[152:155], v[208:211], v[76:79]
	v_mfma_f32_16x16x32_bf16 v[72:75], v[160:163], v[208:211], v[72:75]
	s_setprio 0
	s_setprio 1
	v_mfma_f32_16x16x32_bf16 v[116:119], v[164:167], v[180:183], v[116:119]
	v_mfma_f32_16x16x32_bf16 v[112:115], v[172:175], v[180:183], v[112:115]
	v_mfma_f32_16x16x32_bf16 v[100:103], v[164:167], v[188:191], v[100:103]
	v_mfma_f32_16x16x32_bf16 v[96:99], v[172:175], v[188:191], v[96:99]
	v_mfma_f32_16x16x32_bf16 v[84:87], v[164:167], v[196:199], v[84:87]
	v_mfma_f32_16x16x32_bf16 v[80:83], v[172:175], v[196:199], v[80:83]
	v_mfma_f32_16x16x32_bf16 v[68:71], v[164:167], v[204:207], v[68:71]
	v_mfma_f32_16x16x32_bf16 v[64:67], v[172:175], v[204:207], v[64:67]
	v_mfma_f32_16x16x32_bf16 v[116:119], v[168:171], v[184:187], v[116:119]
	v_mfma_f32_16x16x32_bf16 v[112:115], v[176:179], v[184:187], v[112:115]
	v_mfma_f32_16x16x32_bf16 v[100:103], v[168:171], v[192:195], v[100:103]
	v_mfma_f32_16x16x32_bf16 v[96:99], v[176:179], v[192:195], v[96:99]
	v_mfma_f32_16x16x32_bf16 v[84:87], v[168:171], v[200:203], v[84:87]
	v_mfma_f32_16x16x32_bf16 v[80:83], v[176:179], v[200:203], v[80:83]
	v_mfma_f32_16x16x32_bf16 v[68:71], v[168:171], v[208:211], v[68:71]
	v_mfma_f32_16x16x32_bf16 v[64:67], v[176:179], v[208:211], v[64:67]
	s_setprio 0
	s_barrier
; #define PG8_STAGE(bufoff, gbase, voff) do { _Pragma("unroll") for (int _i = 0; _i < 2; ++_i) \
;         __builtin_amdgcn_global_load_lds((const unsigned*)((const char*)(gbase) + (voff)[_i]), (PG8_LAS unsigned*)(lds + (bufoff) + ldsw + _i * 8192), 16, 0, 0); } while (0)
; #define PG8_LDA(dst, b, h) do { _Pragma("unroll") for (int m = 0; m < 4; ++m) _Pragma("unroll") for (int k = 0; k < 2; ++k) dst[m][k] = *(const PG8_LAS bf16x8*)(lds + PG8_SA(b, h) + aoff + m * 2048 + k * 1024); } while (0)
; #define PG8_MMA(ai, bj, At, Bt) do { __builtin_amdgcn_s_setprio(1); _Pragma("unroll") for (int m = 0; m < 4; ++m) _Pragma("unroll") for (int n = 0; n < 2; ++n) _Pragma("unroll") for (int k = 0; k < 2; ++k) \
;         acc[ai][bj][m][n] = __builtin_amdgcn_mfma_f32_16x16x32_bf16(Bt[n][k], At[m][k], acc[ai][bj][m][n], 0, 0, 0); __builtin_amdgcn_s_setprio(0); } while (0)
;     __device__ __forceinline__ void operator()(const f32x4 (&acc)[2][2][4][2], const Unit& u, int wr, int wc, int fr, int fq, int) const {
;     ...
;             for (int m = 0; m < 4; ++m) { const int row = row0 + ai * HALF + m * 16; const size_t off = (size_t)row * 2048 + col0; float s = 0.f;
; #pragma unroll
;                 for (int bj = 0; bj < 2; ++bj)
; #pragma unroll
;                     for (int n = 0; n < 2; ++n) { const size_t o2 = off + bj * HALF + n * 16; f32x4 bs;
;                         if (MODE == 0) bs = __builtin_nontemporal_load((const f32x4*)(base + o2));
;                         else { const u32x2 b2 = *(const u32x2*)(xb + o2); bs[0] = __builtin_bit_cast(float, b2.x << 16); bs[1] = __builtin_bit_cast(float, b2.x & 0xffff0000u); bs[2] = __builtin_bit_cast(float, b2.y << 16); bs[3] = __builtin_bit_cast(float, b2.y & 0xffff0000u); }
;                         const f32x4 o = bs + acc[ai][bj][m][n];
;                         if (MODE == 2) __builtin_nontemporal_store(o, (f32x4*)(out + o2));
; template <class Epi, class Sched, bool ALIGN_EPI = false, bool SP2 = false>
; __device__ __forceinline__ void gemm_phase(PG8_LAS unsigned char* lds, const Gemm g, const Sched& S, const Epi& E) {
;     ...
;             PG8_LDA(At, 1, 1); PG8_STAGE(PG8_SB(1, 0), b3, voffB); PG8_STAGE(PG8_SB(1, 1), b3 + hstep, voffB); PG8_STAGE(PG8_SA(1, 0), a3, voffA);
;             PG8_WAIT_V(8); PG8_WAIT_L(0); PG8_BAR; PG8_MMA(1, 0, At, B0); PG8_MMA(1, 1, At, B1); PG8_BAR; PG8_SCHED;
	s_add_i32 s20, s48, s30
	v_lshl_add_u64 v[144:145], v[144:145], 0, s[6:7]
	s_mov_b32 m0, s20
	ds_read_b128 v[180:183], v151 offset:49152
	ds_read_b128 v[184:187], v151 offset:50176
	ds_read_b128 v[188:191], v151 offset:51200
	ds_read_b128 v[192:195], v151 offset:52224
	ds_read_b128 v[196:199], v151 offset:53248
	ds_read_b128 v[200:203], v151 offset:54272
	ds_read_b128 v[204:207], v151 offset:55296
	ds_read_b128 v[208:211], v151 offset:56320
	global_load_lds_dwordx4 v[144:145], off
	s_add_i32 m0, s20, 0x2000
	s_add_u32 s20, s24, 0x160080
	v_lshl_add_u64 v[144:145], v[212:213], 0, s[6:7]
	s_addc_u32 s21, s25, 0
	s_add_i32 s24, s49, s30
	global_load_lds_dwordx4 v[144:145], off
	v_lshl_add_u64 v[144:145], s[20:21], 0, v[128:129]
	s_mov_b32 m0, s24
	s_nop 0
	global_load_lds_dwordx4 v[144:145], off
	v_lshl_add_u64 v[144:145], s[20:21], 0, v[130:131]
	s_add_i32 m0, s24, 0x2000
	s_nop 0
	global_load_lds_dwordx4 v[144:145], off
	v_lshl_add_u64 v[144:145], v[214:215], 0, s[6:7]
	s_mov_b32 m0, s37
	s_nop 0
	global_load_lds_dwordx4 v[144:145], off
	v_lshl_add_u64 v[144:145], v[216:217], 0, s[6:7]
	s_mov_b32 m0, s38
	s_nop 0
	global_load_lds_dwordx4 v[144:145], off
	s_waitcnt vmcnt(8)
	s_waitcnt lgkmcnt(0)
	v_mfma_f32_16x16x32_bf16 v[60:63], v[140:143], v[180:183], v[60:63]
	v_mfma_f32_16x16x32_bf16 v[56:59], v[156:159], v[180:183], v[56:59]
	s_barrier
	s_setprio 1
	s_waitcnt lgkmcnt(0)
	v_mfma_f32_16x16x32_bf16 v[44:47], v[140:143], v[188:191], v[44:47]
	v_mfma_f32_16x16x32_bf16 v[40:43], v[156:159], v[188:191], v[40:43]
	v_mfma_f32_16x16x32_bf16 v[28:31], v[140:143], v[196:199], v[28:31]
	v_mfma_f32_16x16x32_bf16 v[24:27], v[156:159], v[196:199], v[24:27]
	v_mfma_f32_16x16x32_bf16 v[12:15], v[140:143], v[204:207], v[12:15]
	v_mfma_f32_16x16x32_bf16 v[8:11], v[156:159], v[204:207], v[8:11]
	v_mfma_f32_16x16x32_bf16 v[60:63], v[152:155], v[184:187], v[60:63]
	v_mfma_f32_16x16x32_bf16 v[56:59], v[160:163], v[184:187], v[56:59]
	v_mfma_f32_16x16x32_bf16 v[44:47], v[152:155], v[192:195], v[44:47]
	v_mfma_f32_16x16x32_bf16 v[40:43], v[160:163], v[192:195], v[40:43]
	v_mfma_f32_16x16x32_bf16 v[28:31], v[152:155], v[200:203], v[28:31]
	v_mfma_f32_16x16x32_bf16 v[24:27], v[160:163], v[200:203], v[24:27]
	v_mfma_f32_16x16x32_bf16 v[12:15], v[152:155], v[208:211], v[12:15]
	v_mfma_f32_16x16x32_bf16 v[8:11], v[160:163], v[208:211], v[8:11]
	s_setprio 0
	s_setprio 1
	v_mfma_f32_16x16x32_bf16 v[52:55], v[164:167], v[180:183], v[52:55]
	v_mfma_f32_16x16x32_bf16 v[48:51], v[172:175], v[180:183], v[48:51]
	v_mfma_f32_16x16x32_bf16 v[36:39], v[164:167], v[188:191], v[36:39]
	v_mfma_f32_16x16x32_bf16 v[32:35], v[172:175], v[188:191], v[32:35]
	v_mfma_f32_16x16x32_bf16 v[20:23], v[164:167], v[196:199], v[20:23]
	v_mfma_f32_16x16x32_bf16 v[16:19], v[172:175], v[196:199], v[16:19]
	v_mfma_f32_16x16x32_bf16 v[4:7], v[164:167], v[204:207], v[4:7]
	v_mfma_f32_16x16x32_bf16 v[0:3], v[172:175], v[204:207], v[0:3]
	v_mfma_f32_16x16x32_bf16 v[52:55], v[168:171], v[184:187], v[52:55]
	v_mfma_f32_16x16x32_bf16 v[48:51], v[176:179], v[184:187], v[48:51]
	v_mfma_f32_16x16x32_bf16 v[36:39], v[168:171], v[192:195], v[36:39]
	v_mfma_f32_16x16x32_bf16 v[32:35], v[176:179], v[192:195], v[32:35]
	v_mfma_f32_16x16x32_bf16 v[20:23], v[168:171], v[200:203], v[20:23]
	v_mfma_f32_16x16x32_bf16 v[16:19], v[176:179], v[200:203], v[16:19]
	v_mfma_f32_16x16x32_bf16 v[4:7], v[168:171], v[208:211], v[4:7]
	v_mfma_f32_16x16x32_bf16 v[0:3], v[176:179], v[208:211], v[0:3]
	s_setprio 0
	s_barrier
	s_add_i32 s47, s47, 2
	s_add_u32 s45, s45, 0x100
	s_addc_u32 s46, s46, 0
	s_cmpk_gt_u32 s47, 0x55
	s_mov_b64 s[20:21], s[22:23]
	s_cbranch_scc0 .LBB0_1956
	s_and_b64 vcc, exec, s[8:9]
	s_cbranch_vccz .LBB0_1959
	s_barrier
.LBB0_1959:
	v_lshl_add_u32 v144, s43, 8, v146
	v_lshl_or_b32 v142, s44, 8, v148
	v_ashrrev_i32_e32 v145, 31, v144
	v_ashrrev_i32_e32 v143, 31, v142
	v_lshlrev_b64 v[140:141], 11, v[144:145]
	v_lshl_add_u64 v[140:141], v[140:141], 0, v[142:143]
	v_lshlrev_b64 v[152:153], 1, v[140:141]
	v_lshl_add_u64 v[154:155], s[80:81], 0, v[152:153]
	global_load_dwordx2 v[154:155], v[154:155], off
	v_lshl_add_u64 v[156:157], v[140:141], 2, s[88:89]
	v_or_b32_e32 v158, 32, v152
	v_mov_b32_e32 v159, v153
	v_lshl_add_u64 v[158:159], s[80:81], 0, v[158:159]
	s_and_b64 vcc, exec, s[0:1]
	s_mov_b64 s[0:1], -1
	s_waitcnt vmcnt(0)
	v_lshlrev_b32_e32 v160, 16, v154
	v_and_b32_e32 v161, 0xffff0000, v154
	v_lshlrev_b32_e32 v154, 16, v155
	v_and_b32_e32 v155, 0xffff0000, v155
	v_pk_add_f32 v[126:127], v[126:127], v[154:155]
	v_pk_add_f32 v[124:125], v[124:125], v[160:161]
	global_store_dwordx4 v[156:157], v[124:127], off nt
	global_load_dwordx2 v[124:125], v[158:159], off
	s_waitcnt vmcnt(0)
	v_lshlrev_b32_e32 v154, 16, v124
	v_and_b32_e32 v155, 0xffff0000, v124
	v_lshlrev_b32_e32 v124, 16, v125
	v_and_b32_e32 v125, 0xffff0000, v125
	v_or_b32_e32 v126, 0x100, v152
	v_mov_b32_e32 v127, v153
	v_pk_add_f32 v[122:123], v[122:123], v[124:125]
	v_pk_add_f32 v[120:121], v[120:121], v[154:155]
	v_lshl_add_u64 v[126:127], s[80:81], 0, v[126:127]
	global_store_dwordx4 v[156:157], v[120:123], off offset:64 nt
	global_load_dwordx2 v[120:121], v[126:127], off
	v_or_b32_e32 v152, 0x120, v152
	v_lshl_add_u64 v[122:123], s[80:81], 0, v[152:153]
	s_waitcnt vmcnt(0)
	v_lshlrev_b32_e32 v124, 16, v120
	v_and_b32_e32 v125, 0xffff0000, v120
	v_lshlrev_b32_e32 v120, 16, v121
	v_and_b32_e32 v121, 0xffff0000, v121
	v_pk_add_f32 v[118:119], v[118:119], v[120:121]
	v_pk_add_f32 v[116:117], v[116:117], v[124:125]
	global_store_dwordx4 v[156:157], v[116:119], off offset:512 nt
	global_load_dwordx2 v[116:117], v[122:123], off
	s_waitcnt vmcnt(0)
;     __device__ __forceinline__ void operator()(const f32x4 (&acc)[2][2][4][2], const Unit& u, int wr, int wc, int fr, int fq, int) const {
;     ...
;                     for (int n = 0; n < 2; ++n) { const size_t o2 = off + bj * HALF + n * 16; f32x4 bs;
;                         if (MODE == 0) bs = __builtin_nontemporal_load((const f32x4*)(base + o2));
;                         else { const u32x2 b2 = *(const u32x2*)(xb + o2); bs[0] = __builtin_bit_cast(float, b2.x << 16); bs[1] = __builtin_bit_cast(float, b2.x & 0xffff0000u); bs[2] = __builtin_bit_cast(float, b2.y << 16); bs[3] = __builtin_bit_cast(float, b2.y & 0xffff0000u); }
;                         const f32x4 o = bs + acc[ai][bj][m][n];
;                         if (MODE == 2) __builtin_nontemporal_store(o, (f32x4*)(out + o2));
	v_lshlrev_b32_e32 v124, 16, v116
	v_or_b32_e32 v118, 16, v144
	v_ashrrev_i32_e32 v119, 31, v118
	v_lshlrev_b64 v[118:119], 11, v[118:119]
	v_lshl_add_u64 v[118:119], v[118:119], 0, v[142:143]
	v_and_b32_e32 v125, 0xffff0000, v116
	v_lshlrev_b32_e32 v116, 16, v117
	v_and_b32_e32 v117, 0xffff0000, v117
	v_lshlrev_b64 v[120:121], 1, v[118:119]
	v_pk_add_f32 v[114:115], v[114:115], v[116:117]
	v_pk_add_f32 v[112:113], v[112:113], v[124:125]
	v_lshl_add_u64 v[122:123], s[80:81], 0, v[120:121]
	global_store_dwordx4 v[156:157], v[112:115], off offset:576 nt
	global_load_dwordx2 v[112:113], v[122:123], off
	v_or_b32_e32 v116, 32, v120
	v_lshl_add_u64 v[114:115], v[118:119], 2, s[88:89]
	v_mov_b32_e32 v117, v121
	v_lshl_add_u64 v[116:117], s[80:81], 0, v[116:117]
	s_waitcnt vmcnt(0)
	v_lshlrev_b32_e32 v118, 16, v112
	v_and_b32_e32 v119, 0xffff0000, v112
	v_lshlrev_b32_e32 v112, 16, v113
	v_and_b32_e32 v113, 0xffff0000, v113
	v_pk_add_f32 v[110:111], v[110:111], v[112:113]
	v_pk_add_f32 v[108:109], v[108:109], v[118:119]
	global_store_dwordx4 v[114:115], v[108:111], off nt
	global_load_dwordx2 v[108:109], v[116:117], off
	s_waitcnt vmcnt(0)
	v_lshlrev_b32_e32 v112, 16, v108
	v_and_b32_e32 v113, 0xffff0000, v108
	v_lshlrev_b32_e32 v108, 16, v109
	v_and_b32_e32 v109, 0xffff0000, v109
	v_or_b32_e32 v110, 0x100, v120
	v_mov_b32_e32 v111, v121
	v_pk_add_f32 v[106:107], v[106:107], v[108:109]
	v_pk_add_f32 v[104:105], v[104:105], v[112:113]
	v_lshl_add_u64 v[110:111], s[80:81], 0, v[110:111]
	global_store_dwordx4 v[114:115], v[104:107], off offset:64 nt
	global_load_dwordx2 v[104:105], v[110:111], off
	v_or_b32_e32 v120, 0x120, v120
	v_lshl_add_u64 v[106:107], s[80:81], 0, v[120:121]
	s_waitcnt vmcnt(0)
	v_lshlrev_b32_e32 v108, 16, v104
	v_and_b32_e32 v109, 0xffff0000, v104
	v_lshlrev_b32_e32 v104, 16, v105
	v_and_b32_e32 v105, 0xffff0000, v105
	v_pk_add_f32 v[102:103], v[102:103], v[104:105]
	v_pk_add_f32 v[100:101], v[100:101], v[108:109]
	global_store_dwordx4 v[114:115], v[100:103], off offset:512 nt
	global_load_dwordx2 v[100:101], v[106:107], off
	s_waitcnt vmcnt(0)
	v_lshlrev_b32_e32 v108, 16, v100
	v_or_b32_e32 v102, 32, v144
	v_ashrrev_i32_e32 v103, 31, v102
	v_lshlrev_b64 v[102:103], 11, v[102:103]
	v_lshl_add_u64 v[102:103], v[102:103], 0, v[142:143]
	v_and_b32_e32 v109, 0xffff0000, v100
	v_lshlrev_b32_e32 v100, 16, v101
	v_and_b32_e32 v101, 0xffff0000, v101
	v_lshlrev_b64 v[104:105], 1, v[102:103]
	v_pk_add_f32 v[98:99], v[98:99], v[100:101]
	v_pk_add_f32 v[96:97], v[96:97], v[108:109]
	v_lshl_add_u64 v[106:107], s[80:81], 0, v[104:105]
	global_store_dwordx4 v[114:115], v[96:99], off offset:576 nt
	global_load_dwordx2 v[96:97], v[106:107], off
	v_or_b32_e32 v100, 32, v104
	v_lshl_add_u64 v[98:99], v[102:103], 2, s[88:89]
	v_mov_b32_e32 v101, v105
	v_lshl_add_u64 v[100:101], s[80:81], 0, v[100:101]
	s_waitcnt vmcnt(0)
	v_lshlrev_b32_e32 v102, 16, v96
	v_and_b32_e32 v103, 0xffff0000, v96
	v_lshlrev_b32_e32 v96, 16, v97
	v_and_b32_e32 v97, 0xffff0000, v97
	v_pk_add_f32 v[94:95], v[94:95], v[96:97]
	v_pk_add_f32 v[92:93], v[92:93], v[102:103]
	global_store_dwordx4 v[98:99], v[92:95], off nt
	global_load_dwordx2 v[92:93], v[100:101], off
	s_waitcnt vmcnt(0)
	v_lshlrev_b32_e32 v96, 16, v92
	v_and_b32_e32 v97, 0xffff0000, v92
	v_lshlrev_b32_e32 v92, 16, v93
	v_and_b32_e32 v93, 0xffff0000, v93
	v_or_b32_e32 v94, 0x100, v104
	v_mov_b32_e32 v95, v105
	v_pk_add_f32 v[90:91], v[90:91], v[92:93]
	v_pk_add_f32 v[88:89], v[88:89], v[96:97]
	v_lshl_add_u64 v[94:95], s[80:81], 0, v[94:95]
	global_store_dwordx4 v[98:99], v[88:91], off offset:64 nt
	global_load_dwordx2 v[88:89], v[94:95], off
	v_or_b32_e32 v104, 0x120, v104
	v_lshl_add_u64 v[90:91], s[80:81], 0, v[104:105]
	s_waitcnt vmcnt(0)
	v_lshlrev_b32_e32 v92, 16, v88
	v_and_b32_e32 v93, 0xffff0000, v88
	v_lshlrev_b32_e32 v88, 16, v89
	v_and_b32_e32 v89, 0xffff0000, v89
	v_pk_add_f32 v[86:87], v[86:87], v[88:89]
	v_pk_add_f32 v[84:85], v[84:85], v[92:93]
	global_store_dwordx4 v[98:99], v[84:87], off offset:512 nt
	global_load_dwordx2 v[84:85], v[90:91], off
	s_waitcnt vmcnt(0)
	v_lshlrev_b32_e32 v92, 16, v84
	v_or_b32_e32 v86, 48, v144
	v_ashrrev_i32_e32 v87, 31, v86
	v_lshlrev_b64 v[86:87], 11, v[86:87]
	v_lshl_add_u64 v[86:87], v[86:87], 0, v[142:143]
	v_and_b32_e32 v93, 0xffff0000, v84
	v_lshlrev_b32_e32 v84, 16, v85
	v_and_b32_e32 v85, 0xffff0000, v85
	v_lshlrev_b64 v[88:89], 1, v[86:87]
	v_pk_add_f32 v[82:83], v[82:83], v[84:85]
	v_pk_add_f32 v[80:81], v[80:81], v[92:93]
	v_lshl_add_u64 v[90:91], s[80:81], 0, v[88:89]
	global_store_dwordx4 v[98:99], v[80:83], off offset:576 nt
	global_load_dwordx2 v[80:81], v[90:91], off
	v_or_b32_e32 v84, 32, v88
	v_lshl_add_u64 v[82:83], v[86:87], 2, s[88:89]
	v_mov_b32_e32 v85, v89
	v_lshl_add_u64 v[84:85], s[80:81], 0, v[84:85]
	s_waitcnt vmcnt(0)
	v_lshlrev_b32_e32 v86, 16, v80
	v_and_b32_e32 v87, 0xffff0000, v80
	v_lshlrev_b32_e32 v80, 16, v81
	v_and_b32_e32 v81, 0xffff0000, v81
	v_pk_add_f32 v[78:79], v[78:79], v[80:81]
	v_pk_add_f32 v[76:77], v[76:77], v[86:87]
	global_store_dwordx4 v[82:83], v[76:79], off nt
	global_load_dwordx2 v[76:77], v[84:85], off
	s_waitcnt vmcnt(0)
	v_lshlrev_b32_e32 v80, 16, v76
	v_and_b32_e32 v81, 0xffff0000, v76
	v_lshlrev_b32_e32 v76, 16, v77
	v_and_b32_e32 v77, 0xffff0000, v77
	v_or_b32_e32 v78, 0x100, v88
	v_mov_b32_e32 v79, v89
	v_pk_add_f32 v[74:75], v[74:75], v[76:77]
	v_pk_add_f32 v[72:73], v[72:73], v[80:81]
	v_lshl_add_u64 v[78:79], s[80:81], 0, v[78:79]
	global_store_dwordx4 v[82:83], v[72:75], off offset:64 nt
	global_load_dwordx2 v[72:73], v[78:79], off
	v_or_b32_e32 v88, 0x120, v88
	v_lshl_add_u64 v[74:75], s[80:81], 0, v[88:89]
	s_waitcnt vmcnt(0)
;     __device__ __forceinline__ void operator()(const f32x4 (&acc)[2][2][4][2], const Unit& u, int wr, int wc, int fr, int fq, int) const {
;     ...
;                     for (int n = 0; n < 2; ++n) { const size_t o2 = off + bj * HALF + n * 16; f32x4 bs;
;                         if (MODE == 0) bs = __builtin_nontemporal_load((const f32x4*)(base + o2));
;                         else { const u32x2 b2 = *(const u32x2*)(xb + o2); bs[0] = __builtin_bit_cast(float, b2.x << 16); bs[1] = __builtin_bit_cast(float, b2.x & 0xffff0000u); bs[2] = __builtin_bit_cast(float, b2.y << 16); bs[3] = __builtin_bit_cast(float, b2.y & 0xffff0000u); }
;                         const f32x4 o = bs + acc[ai][bj][m][n];
;                         if (MODE == 2) __builtin_nontemporal_store(o, (f32x4*)(out + o2));
	v_lshlrev_b32_e32 v76, 16, v72
	v_and_b32_e32 v77, 0xffff0000, v72
	v_lshlrev_b32_e32 v72, 16, v73
	v_and_b32_e32 v73, 0xffff0000, v73
	v_pk_add_f32 v[70:71], v[70:71], v[72:73]
	v_pk_add_f32 v[68:69], v[68:69], v[76:77]
	global_store_dwordx4 v[82:83], v[68:71], off offset:512 nt
	global_load_dwordx2 v[68:69], v[74:75], off
	s_waitcnt vmcnt(0)
	v_lshlrev_b32_e32 v76, 16, v68
	v_lshl_add_u64 v[70:71], v[140:141], 0, s[10:11]
	v_and_b32_e32 v77, 0xffff0000, v68
	v_lshlrev_b32_e32 v68, 16, v69
	v_and_b32_e32 v69, 0xffff0000, v69
	v_lshlrev_b64 v[72:73], 1, v[70:71]
	v_pk_add_f32 v[66:67], v[66:67], v[68:69]
	v_pk_add_f32 v[64:65], v[64:65], v[76:77]
	v_lshl_add_u64 v[74:75], s[80:81], 0, v[72:73]
	global_store_dwordx4 v[82:83], v[64:67], off offset:576 nt
	global_load_dwordx2 v[64:65], v[74:75], off
	v_or_b32_e32 v68, 32, v72
	v_lshl_add_u64 v[66:67], v[70:71], 2, s[88:89]
	v_mov_b32_e32 v69, v73
	v_lshl_add_u64 v[68:69], s[80:81], 0, v[68:69]
	s_waitcnt vmcnt(0)
	v_lshlrev_b32_e32 v70, 16, v64
	v_and_b32_e32 v71, 0xffff0000, v64
	v_lshlrev_b32_e32 v64, 16, v65
	v_and_b32_e32 v65, 0xffff0000, v65
	v_pk_add_f32 v[62:63], v[62:63], v[64:65]
	v_pk_add_f32 v[60:61], v[60:61], v[70:71]
	global_store_dwordx4 v[66:67], v[60:63], off nt
	global_load_dwordx2 v[60:61], v[68:69], off
	s_waitcnt vmcnt(0)
	v_lshlrev_b32_e32 v64, 16, v60
	v_and_b32_e32 v65, 0xffff0000, v60
	v_lshlrev_b32_e32 v60, 16, v61
	v_and_b32_e32 v61, 0xffff0000, v61
	v_or_b32_e32 v62, 0x100, v72
	v_mov_b32_e32 v63, v73
	v_pk_add_f32 v[58:59], v[58:59], v[60:61]
	v_pk_add_f32 v[56:57], v[56:57], v[64:65]
	v_lshl_add_u64 v[62:63], s[80:81], 0, v[62:63]
	global_store_dwordx4 v[66:67], v[56:59], off offset:64 nt
	global_load_dwordx2 v[56:57], v[62:63], off
	v_or_b32_e32 v72, 0x120, v72
	v_lshl_add_u64 v[58:59], s[80:81], 0, v[72:73]
	s_waitcnt vmcnt(0)
	v_lshlrev_b32_e32 v60, 16, v56
	v_and_b32_e32 v61, 0xffff0000, v56
	v_lshlrev_b32_e32 v56, 16, v57
	v_and_b32_e32 v57, 0xffff0000, v57
	v_pk_add_f32 v[54:55], v[54:55], v[56:57]
	v_pk_add_f32 v[52:53], v[52:53], v[60:61]
	global_store_dwordx4 v[66:67], v[52:55], off offset:512 nt
	global_load_dwordx2 v[52:53], v[58:59], off
	s_waitcnt vmcnt(0)
	v_lshlrev_b32_e32 v60, 16, v52
	v_lshl_add_u64 v[54:55], v[140:141], 0, s[12:13]
	v_and_b32_e32 v61, 0xffff0000, v52
	v_lshlrev_b32_e32 v52, 16, v53
	v_and_b32_e32 v53, 0xffff0000, v53
	v_lshlrev_b64 v[56:57], 1, v[54:55]
	v_pk_add_f32 v[50:51], v[50:51], v[52:53]
	v_pk_add_f32 v[48:49], v[48:49], v[60:61]
	v_lshl_add_u64 v[58:59], s[80:81], 0, v[56:57]
	global_store_dwordx4 v[66:67], v[48:51], off offset:576 nt
	global_load_dwordx2 v[48:49], v[58:59], off
	v_or_b32_e32 v52, 32, v56
	v_lshl_add_u64 v[50:51], v[54:55], 2, s[88:89]
	v_mov_b32_e32 v53, v57
	v_lshl_add_u64 v[52:53], s[80:81], 0, v[52:53]
	s_waitcnt vmcnt(0)
	v_lshlrev_b32_e32 v54, 16, v48
	v_and_b32_e32 v55, 0xffff0000, v48
	v_lshlrev_b32_e32 v48, 16, v49
	v_and_b32_e32 v49, 0xffff0000, v49
	v_pk_add_f32 v[46:47], v[46:47], v[48:49]
	v_pk_add_f32 v[44:45], v[44:45], v[54:55]
	global_store_dwordx4 v[50:51], v[44:47], off nt
	global_load_dwordx2 v[44:45], v[52:53], off
	s_waitcnt vmcnt(0)
	v_lshlrev_b32_e32 v48, 16, v44
	v_and_b32_e32 v49, 0xffff0000, v44
	v_lshlrev_b32_e32 v44, 16, v45
	v_and_b32_e32 v45, 0xffff0000, v45
	v_or_b32_e32 v46, 0x100, v56
	v_mov_b32_e32 v47, v57
	v_pk_add_f32 v[42:43], v[42:43], v[44:45]
	v_pk_add_f32 v[40:41], v[40:41], v[48:49]
	v_lshl_add_u64 v[46:47], s[80:81], 0, v[46:47]
	global_store_dwordx4 v[50:51], v[40:43], off offset:64 nt
	global_load_dwordx2 v[40:41], v[46:47], off
	v_or_b32_e32 v56, 0x120, v56
	v_lshl_add_u64 v[42:43], s[80:81], 0, v[56:57]
	s_waitcnt vmcnt(0)
	v_lshlrev_b32_e32 v44, 16, v40
	v_and_b32_e32 v45, 0xffff0000, v40
	v_lshlrev_b32_e32 v40, 16, v41
	v_and_b32_e32 v41, 0xffff0000, v41
	v_pk_add_f32 v[38:39], v[38:39], v[40:41]
	v_pk_add_f32 v[36:37], v[36:37], v[44:45]
	global_store_dwordx4 v[50:51], v[36:39], off offset:512 nt
	global_load_dwordx2 v[36:37], v[42:43], off
	s_waitcnt vmcnt(0)
;     __device__ __forceinline__ void operator()(const f32x4 (&acc)[2][2][4][2], const Unit& u, int wr, int wc, int fr, int fq, int) const {
;     ...
;                     for (int n = 0; n < 2; ++n) { const size_t o2 = off + bj * HALF + n * 16; f32x4 bs;
;                         if (MODE == 0) bs = __builtin_nontemporal_load((const f32x4*)(base + o2));
;                         else { const u32x2 b2 = *(const u32x2*)(xb + o2); bs[0] = __builtin_bit_cast(float, b2.x << 16); bs[1] = __builtin_bit_cast(float, b2.x & 0xffff0000u); bs[2] = __builtin_bit_cast(float, b2.y << 16); bs[3] = __builtin_bit_cast(float, b2.y & 0xffff0000u); }
;                         const f32x4 o = bs + acc[ai][bj][m][n];
;                         if (MODE == 2) __builtin_nontemporal_store(o, (f32x4*)(out + o2));
	v_lshlrev_b32_e32 v44, 16, v36
	v_lshl_add_u64 v[38:39], v[140:141], 0, s[14:15]
	v_and_b32_e32 v45, 0xffff0000, v36
	v_lshlrev_b32_e32 v36, 16, v37
	v_and_b32_e32 v37, 0xffff0000, v37
	v_lshlrev_b64 v[40:41], 1, v[38:39]
	v_pk_add_f32 v[34:35], v[34:35], v[36:37]
	v_pk_add_f32 v[32:33], v[32:33], v[44:45]
	v_lshl_add_u64 v[42:43], s[80:81], 0, v[40:41]
	global_store_dwordx4 v[50:51], v[32:35], off offset:576 nt
	global_load_dwordx2 v[32:33], v[42:43], off
	v_or_b32_e32 v36, 32, v40
	v_lshl_add_u64 v[34:35], v[38:39], 2, s[88:89]
	v_mov_b32_e32 v37, v41
	v_lshl_add_u64 v[36:37], s[80:81], 0, v[36:37]
	s_waitcnt vmcnt(0)
	v_lshlrev_b32_e32 v38, 16, v32
	v_and_b32_e32 v39, 0xffff0000, v32
	v_lshlrev_b32_e32 v32, 16, v33
	v_and_b32_e32 v33, 0xffff0000, v33
	v_pk_add_f32 v[30:31], v[30:31], v[32:33]
	v_pk_add_f32 v[28:29], v[28:29], v[38:39]
	global_store_dwordx4 v[34:35], v[28:31], off nt
	global_load_dwordx2 v[28:29], v[36:37], off
	s_waitcnt vmcnt(0)
	v_lshlrev_b32_e32 v32, 16, v28
	v_and_b32_e32 v33, 0xffff0000, v28
	v_lshlrev_b32_e32 v28, 16, v29
	v_and_b32_e32 v29, 0xffff0000, v29
	v_or_b32_e32 v30, 0x100, v40
	v_mov_b32_e32 v31, v41
	v_pk_add_f32 v[26:27], v[26:27], v[28:29]
	v_pk_add_f32 v[24:25], v[24:25], v[32:33]
	v_lshl_add_u64 v[30:31], s[80:81], 0, v[30:31]
	global_store_dwordx4 v[34:35], v[24:27], off offset:64 nt
	global_load_dwordx2 v[24:25], v[30:31], off
	v_or_b32_e32 v40, 0x120, v40
	v_lshl_add_u64 v[26:27], s[80:81], 0, v[40:41]
	s_waitcnt vmcnt(0)
	v_lshlrev_b32_e32 v28, 16, v24
	v_and_b32_e32 v29, 0xffff0000, v24
	v_lshlrev_b32_e32 v24, 16, v25
	v_and_b32_e32 v25, 0xffff0000, v25
	v_pk_add_f32 v[22:23], v[22:23], v[24:25]
	v_pk_add_f32 v[20:21], v[20:21], v[28:29]
	global_store_dwordx4 v[34:35], v[20:23], off offset:512 nt
	global_load_dwordx2 v[20:21], v[26:27], off
	s_waitcnt vmcnt(0)
	v_lshlrev_b32_e32 v28, 16, v20
	v_lshl_add_u64 v[22:23], v[140:141], 0, s[16:17]
	v_and_b32_e32 v29, 0xffff0000, v20
	v_lshlrev_b32_e32 v20, 16, v21
	v_and_b32_e32 v21, 0xffff0000, v21
	v_lshlrev_b64 v[24:25], 1, v[22:23]
	v_pk_add_f32 v[18:19], v[18:19], v[20:21]
	v_pk_add_f32 v[16:17], v[16:17], v[28:29]
	v_lshl_add_u64 v[26:27], s[80:81], 0, v[24:25]
	global_store_dwordx4 v[34:35], v[16:19], off offset:576 nt
	global_load_dwordx2 v[16:17], v[26:27], off
	v_or_b32_e32 v20, 32, v24
	v_lshl_add_u64 v[18:19], v[22:23], 2, s[88:89]
	v_mov_b32_e32 v21, v25
	v_lshl_add_u64 v[20:21], s[80:81], 0, v[20:21]
	s_waitcnt vmcnt(0)
	v_lshlrev_b32_e32 v22, 16, v16
	v_and_b32_e32 v23, 0xffff0000, v16
	v_lshlrev_b32_e32 v16, 16, v17
	v_and_b32_e32 v17, 0xffff0000, v17
	v_pk_add_f32 v[14:15], v[14:15], v[16:17]
	v_pk_add_f32 v[12:13], v[12:13], v[22:23]
	global_store_dwordx4 v[18:19], v[12:15], off nt
	global_load_dwordx2 v[12:13], v[20:21], off
	s_waitcnt vmcnt(0)
	v_lshlrev_b32_e32 v16, 16, v12
	v_and_b32_e32 v17, 0xffff0000, v12
	v_lshlrev_b32_e32 v12, 16, v13
	v_and_b32_e32 v13, 0xffff0000, v13
	v_or_b32_e32 v14, 0x100, v24
	v_mov_b32_e32 v15, v25
	v_pk_add_f32 v[10:11], v[10:11], v[12:13]
	v_pk_add_f32 v[8:9], v[8:9], v[16:17]
	v_lshl_add_u64 v[14:15], s[80:81], 0, v[14:15]
	global_store_dwordx4 v[18:19], v[8:11], off offset:64 nt
	global_load_dwordx2 v[8:9], v[14:15], off
	v_or_b32_e32 v24, 0x120, v24
	v_lshl_add_u64 v[10:11], s[80:81], 0, v[24:25]
	s_waitcnt vmcnt(0)
	v_lshlrev_b32_e32 v12, 16, v8
	v_and_b32_e32 v13, 0xffff0000, v8
	v_lshlrev_b32_e32 v8, 16, v9
	v_and_b32_e32 v9, 0xffff0000, v9
	v_pk_add_f32 v[6:7], v[6:7], v[8:9]
	v_pk_add_f32 v[4:5], v[4:5], v[12:13]
	global_store_dwordx4 v[18:19], v[4:7], off offset:512 nt
	global_load_dwordx2 v[4:5], v[10:11], off
	s_waitcnt vmcnt(0)
	v_lshlrev_b32_e32 v6, 16, v4
	v_and_b32_e32 v7, 0xffff0000, v4
	v_lshlrev_b32_e32 v4, 16, v5
	v_and_b32_e32 v5, 0xffff0000, v5
	v_pk_add_f32 v[2:3], v[2:3], v[4:5]
	v_pk_add_f32 v[0:1], v[0:1], v[6:7]
	global_store_dwordx4 v[18:19], v[0:3], off offset:576 nt
	s_cbranch_vccnz .LBB0_1944
	s_andn2_b64 vcc, exec, s[2:3]
	s_cbranch_vccnz .LBB0_1943
	s_barrier
	s_branch .LBB0_1943
